# GEMM phases: first K iteration of each tile peeled with SrcC=0 on first-touch MFMAs; the 128 per-tile accumulator clears removed
# speedup vs baseline: 1.0181x; 1.0103x over previous
; #define PG8_STAGE(bufoff, gbase, voff) do { _Pragma("unroll") for (int _i = 0; _i < 2; ++_i) \
;         __builtin_amdgcn_global_load_lds((const unsigned*)((const char*)(gbase) + (voff)[_i]), (PG8_LAS unsigned*)(lds + (bufoff) + ldsw + _i * 8192), 16, 0, 0); } while (0)
; #define PG8_LDA(dst, b, h) do { _Pragma("unroll") for (int m = 0; m < 4; ++m) _Pragma("unroll") for (int k = 0; k < 2; ++k) dst[m][k] = *(const PG8_LAS bf16x8*)(lds + PG8_SA(b, h) + aoff + m * 2048 + k * 1024); } while (0)
; #define PG8_LDB(dst, b, h) do { _Pragma("unroll") for (int n = 0; n < 2; ++n) _Pragma("unroll") for (int k = 0; k < 2; ++k) dst[n][k] = *(const PG8_LAS bf16x8*)(lds + PG8_SB(b, h) + boff + n * 2048 + k * 1024); } while (0)
; #define PG8_WAIT_V(n) asm volatile("s_waitcnt vmcnt(" #n ")" ::: "memory")
; #define PG8_WAIT_L(n) asm volatile("s_waitcnt lgkmcnt(" #n ")" ::: "memory")
; #define PG8_BAR __builtin_amdgcn_s_barrier()
; #define PG8_SCHED __builtin_amdgcn_sched_barrier(0)
; template <class Epi, class Sched, bool ALIGN_EPI = false, bool SP2 = false>
; __device__ __forceinline__ void gemm_phase(PG8_LAS unsigned char* lds, const Gemm g, const Sched& S, const Epi& E) {
;     ...
;         const bool has_next = S.next(ui + 1, nxt);
;         const char* nA = has_next ? (const char*)g.A + (size_t)nxt.pm * tstep : cA; const char* nB = has_next ? (const char*)g.Bt + (size_t)nxt.pn * tstep : cB;
;         for (int t = 0; t < nt; t += 2) {
;             const bool last = (t == nt - 2);
;             const char* a1 = cA + (size_t)(t + 1) * kstep;
;             const char* a2 = last ? nA : cA + (size_t)(t + 2) * kstep; const char* b2 = last ? nB : cB + (size_t)(t + 2) * kstep;
;             const char* a3 = a2 + kstep; const char* b3 = b2 + kstep;
;             if (last && has_next) S.a_ready(nxt);
;             if constexpr (SP2) {
;             PG8_LDB(B0, 0, 0); PG8_LDB(B1, 0, 1); PG8_SCHED; PG8_LDA(At, 0, 0); PG8_STAGE(PG8_SA(1, 1), a1 + hstep, voffA);
;             PG8_WAIT_V(8); PG8_WAIT_L(0); PG8_BAR; PG8_MMA(0, 0, At, B0); PG8_MMA(0, 1, At, B1); PG8_BAR; PG8_SCHED;
;             PG8_LDA(At, 0, 1); PG8_STAGE(PG8_SB(0, 0), b2, voffB); PG8_STAGE(PG8_SB(0, 1), b2 + hstep, voffB); PG8_STAGE(PG8_SA(0, 0), a2, voffA);
;             PG8_WAIT_V(8); PG8_WAIT_L(0); PG8_BAR; PG8_MMA(1, 0, At, B0); PG8_MMA(1, 1, At, B1); PG8_BAR; PG8_SCHED;
.LBB0_380:
	s_ashr_i32 s23, s22, 31
	s_lshl_b64 s[24:25], s[22:23], 19
	s_add_u32 s24, s16, s24
	s_addc_u32 s25, s17, s25
	s_and_b64 s[38:39], s[0:1], exec
	s_cselect_b32 s23, s25, s43
	s_cselect_b32 s80, s24, s42
	s_ashr_i32 s21, s20, 31
	s_lshl_b64 s[38:39], s[20:21], 19
	s_add_u32 s38, s52, s38
	s_addc_u32 s39, s53, s39
	s_and_b64 s[46:47], s[0:1], exec
	s_cselect_b32 s21, s39, s45
	s_cselect_b32 s81, s38, s44
	s_add_u32 s42, s42, 0x40080
	s_addc_u32 s43, s43, 0
	s_add_u32 s82, s44, 0x100
	s_addc_u32 s83, s45, 0
	s_mov_b32 s86, -2
	ds_read_b128 v[144:147], v151
	ds_read_b128 v[156:159], v151 offset:1024
	ds_read_b128 v[160:163], v151 offset:2048
	ds_read_b128 v[164:167], v151 offset:3072
	ds_read_b128 v[168:171], v153
	ds_read_b128 v[172:175], v153 offset:1024
	ds_read_b128 v[176:179], v153 offset:2048
	ds_read_b128 v[180:183], v153 offset:3072
	s_add_u32 s33, s42, 0xfffc0080
	s_addc_u32 s34, s43, -1
	s_cmp_eq_u32 s86, 12
	s_cselect_b32 s47, s23, s34
	s_cselect_b32 s46, s80, s33
	s_cselect_b32 s45, s21, s83
	s_cselect_b32 s44, s81, s82
	s_add_i32 m0, s41, 0xc000
	ds_read_b128 v[184:187], v154
	ds_read_b128 v[188:191], v154 offset:1024
	ds_read_b128 v[192:195], v154 offset:2048
	ds_read_b128 v[196:199], v154 offset:3072
	ds_read_b128 v[200:203], v154 offset:4096
	ds_read_b128 v[204:207], v154 offset:5120
	ds_read_b128 v[208:211], v154 offset:6144
	ds_read_b128 v[212:215], v154 offset:7168
	global_load_lds_dwordx4 v136, s[42:43]
	s_add_i32 m0, s41, 0xe000
	s_nop 0
	global_load_lds_dwordx4 v138, s[42:43]
	s_waitcnt vmcnt(8)
	s_waitcnt lgkmcnt(0)
	s_barrier
	s_setprio 1
	s_waitcnt lgkmcnt(0)
	v_mfma_f32_16x16x32_bf16 v[124:127], v[144:147], v[184:187], 0
	v_mfma_f32_16x16x32_bf16 v[120:123], v[160:163], v[184:187], 0
	v_mfma_f32_16x16x32_bf16 v[116:119], v[144:147], v[192:195], 0
	v_mfma_f32_16x16x32_bf16 v[108:111], v[160:163], v[192:195], 0
	v_mfma_f32_16x16x32_bf16 v[100:103], v[144:147], v[200:203], 0
	v_mfma_f32_16x16x32_bf16 v[92:95], v[160:163], v[200:203], 0
	v_mfma_f32_16x16x32_bf16 v[84:87], v[144:147], v[208:211], 0
	v_mfma_f32_16x16x32_bf16 v[76:79], v[160:163], v[208:211], 0
	v_mfma_f32_16x16x32_bf16 v[124:127], v[156:159], v[188:191], v[124:127]
	v_mfma_f32_16x16x32_bf16 v[120:123], v[164:167], v[188:191], v[120:123]
	v_mfma_f32_16x16x32_bf16 v[116:119], v[156:159], v[196:199], v[116:119]
	v_mfma_f32_16x16x32_bf16 v[108:111], v[164:167], v[196:199], v[108:111]
	v_mfma_f32_16x16x32_bf16 v[100:103], v[156:159], v[204:207], v[100:103]
	v_mfma_f32_16x16x32_bf16 v[92:95], v[164:167], v[204:207], v[92:95]
	v_mfma_f32_16x16x32_bf16 v[84:87], v[156:159], v[212:215], v[84:87]
	v_mfma_f32_16x16x32_bf16 v[76:79], v[164:167], v[212:215], v[76:79]
	s_setprio 0
	s_setprio 1
	v_mfma_f32_16x16x32_bf16 v[112:115], v[168:171], v[184:187], 0
	v_mfma_f32_16x16x32_bf16 v[104:107], v[176:179], v[184:187], 0
	v_mfma_f32_16x16x32_bf16 v[96:99], v[168:171], v[192:195], 0
	v_mfma_f32_16x16x32_bf16 v[88:91], v[176:179], v[192:195], 0
	v_mfma_f32_16x16x32_bf16 v[80:83], v[168:171], v[200:203], 0
	v_mfma_f32_16x16x32_bf16 v[72:75], v[176:179], v[200:203], 0
	v_mfma_f32_16x16x32_bf16 v[68:71], v[168:171], v[208:211], 0
	v_mfma_f32_16x16x32_bf16 v[64:67], v[176:179], v[208:211], 0
	v_mfma_f32_16x16x32_bf16 v[112:115], v[172:175], v[188:191], v[112:115]
	v_mfma_f32_16x16x32_bf16 v[104:107], v[180:183], v[188:191], v[104:107]
	v_mfma_f32_16x16x32_bf16 v[96:99], v[172:175], v[196:199], v[96:99]
	v_mfma_f32_16x16x32_bf16 v[88:91], v[180:183], v[196:199], v[88:91]
	v_mfma_f32_16x16x32_bf16 v[80:83], v[172:175], v[204:207], v[80:83]
	v_mfma_f32_16x16x32_bf16 v[72:75], v[180:183], v[204:207], v[72:75]
	v_mfma_f32_16x16x32_bf16 v[68:71], v[172:175], v[212:215], v[68:71]
	v_mfma_f32_16x16x32_bf16 v[64:67], v[180:183], v[212:215], v[64:67]
	s_setprio 0
	s_barrier
	s_add_i32 s33, s76, s54
	s_add_u32 s56, s44, s10
	s_addc_u32 s57, s45, s11
	s_mov_b32 m0, s33
	ds_read_b128 v[184:187], v154 offset:16384
	ds_read_b128 v[188:191], v154 offset:17408
	ds_read_b128 v[192:195], v154 offset:18432
	ds_read_b128 v[196:199], v154 offset:19456
	ds_read_b128 v[200:203], v154 offset:20480
	ds_read_b128 v[204:207], v154 offset:21504
	ds_read_b128 v[208:211], v154 offset:22528
	ds_read_b128 v[212:215], v154 offset:23552
	global_load_lds_dwordx4 v130, s[44:45]
	s_add_i32 m0, s33, 0x2000
	s_add_u32 s90, s44, 0x40000
	s_addc_u32 s91, s45, 0
	s_add_i32 s33, s77, s54
	global_load_lds_dwordx4 v134, s[44:45]
	s_mov_b32 m0, s33
	s_add_u32 s58, s46, s10
	s_addc_u32 s59, s47, s11
	global_load_lds_dwordx4 v130, s[90:91]
	s_add_i32 m0, s33, 0x2000
	s_nop 0
	global_load_lds_dwordx4 v134, s[90:91]
	s_mov_b32 m0, s41
	s_nop 0
	global_load_lds_dwordx4 v128, s[46:47]
	s_mov_b32 m0, s63
	s_nop 0
	global_load_lds_dwordx4 v132, s[46:47]
	s_waitcnt vmcnt(8)
	s_waitcnt lgkmcnt(0)
	s_barrier
; #define PG8_STAGE(bufoff, gbase, voff) do { _Pragma("unroll") for (int _i = 0; _i < 2; ++_i) \
;         __builtin_amdgcn_global_load_lds((const unsigned*)((const char*)(gbase) + (voff)[_i]), (PG8_LAS unsigned*)(lds + (bufoff) + ldsw + _i * 8192), 16, 0, 0); } while (0)
; #define PG8_LDA(dst, b, h) do { _Pragma("unroll") for (int m = 0; m < 4; ++m) _Pragma("unroll") for (int k = 0; k < 2; ++k) dst[m][k] = *(const PG8_LAS bf16x8*)(lds + PG8_SA(b, h) + aoff + m * 2048 + k * 1024); } while (0)
; #define PG8_LDB(dst, b, h) do { _Pragma("unroll") for (int n = 0; n < 2; ++n) _Pragma("unroll") for (int k = 0; k < 2; ++k) dst[n][k] = *(const PG8_LAS bf16x8*)(lds + PG8_SB(b, h) + boff + n * 2048 + k * 1024); } while (0)
; #define PG8_MMA(ai, bj, At, Bt) do { __builtin_amdgcn_s_setprio(1); _Pragma("unroll") for (int m = 0; m < 4; ++m) _Pragma("unroll") for (int n = 0; n < 2; ++n) _Pragma("unroll") for (int k = 0; k < 2; ++k) \
;         acc[ai][bj][m][n] = __builtin_amdgcn_mfma_f32_16x16x32_bf16(Bt[n][k], At[m][k], acc[ai][bj][m][n], 0, 0, 0); __builtin_amdgcn_s_setprio(0); } while (0)
; #define PG8_WAIT_V(n) asm volatile("s_waitcnt vmcnt(" #n ")" ::: "memory")
; #define PG8_WAIT_L(n) asm volatile("s_waitcnt lgkmcnt(" #n ")" ::: "memory")
; #define PG8_BAR __builtin_amdgcn_s_barrier()
; #define PG8_SCHED __builtin_amdgcn_sched_barrier(0)
; template <class Epi, class Sched, bool ALIGN_EPI = false, bool SP2 = false>
; __device__ __forceinline__ void gemm_phase(PG8_LAS unsigned char* lds, const Gemm g, const Sched& S, const Epi& E) {
;     ...
;             PG8_WAIT_V(8); PG8_WAIT_L(0); PG8_BAR; PG8_MMA(1, 0, At, B0); PG8_MMA(1, 1, At, B1); PG8_BAR; PG8_SCHED;
;             PG8_LDB(B0, 1, 0); PG8_LDB(B1, 1, 1); PG8_SCHED; PG8_LDA(At, 1, 0); PG8_STAGE(PG8_SA(0, 1), a2 + hstep, voffA);
;             PG8_WAIT_V(8); PG8_WAIT_L(0); PG8_BAR; PG8_MMA(0, 0, At, B0); PG8_MMA(0, 1, At, B1); PG8_BAR; PG8_SCHED;
	s_setprio 1
	s_waitcnt lgkmcnt(0)
	v_mfma_f32_16x16x32_bf16 v[60:63], v[144:147], v[184:187], 0
	v_mfma_f32_16x16x32_bf16 v[56:59], v[160:163], v[184:187], 0
	v_mfma_f32_16x16x32_bf16 v[52:55], v[144:147], v[192:195], 0
	v_mfma_f32_16x16x32_bf16 v[44:47], v[160:163], v[192:195], 0
	v_mfma_f32_16x16x32_bf16 v[36:39], v[144:147], v[200:203], 0
	v_mfma_f32_16x16x32_bf16 v[28:31], v[160:163], v[200:203], 0
	v_mfma_f32_16x16x32_bf16 v[20:23], v[144:147], v[208:211], 0
	v_mfma_f32_16x16x32_bf16 v[12:15], v[160:163], v[208:211], 0
	v_mfma_f32_16x16x32_bf16 v[60:63], v[156:159], v[188:191], v[60:63]
	v_mfma_f32_16x16x32_bf16 v[56:59], v[164:167], v[188:191], v[56:59]
	v_mfma_f32_16x16x32_bf16 v[52:55], v[156:159], v[196:199], v[52:55]
	v_mfma_f32_16x16x32_bf16 v[44:47], v[164:167], v[196:199], v[44:47]
	v_mfma_f32_16x16x32_bf16 v[36:39], v[156:159], v[204:207], v[36:39]
	v_mfma_f32_16x16x32_bf16 v[28:31], v[164:167], v[204:207], v[28:31]
	v_mfma_f32_16x16x32_bf16 v[20:23], v[156:159], v[212:215], v[20:23]
	v_mfma_f32_16x16x32_bf16 v[12:15], v[164:167], v[212:215], v[12:15]
	s_setprio 0
	s_setprio 1
	v_mfma_f32_16x16x32_bf16 v[48:51], v[168:171], v[184:187], 0
	v_mfma_f32_16x16x32_bf16 v[40:43], v[176:179], v[184:187], 0
	v_mfma_f32_16x16x32_bf16 v[32:35], v[168:171], v[192:195], 0
	v_mfma_f32_16x16x32_bf16 v[24:27], v[176:179], v[192:195], 0
	v_mfma_f32_16x16x32_bf16 v[16:19], v[168:171], v[200:203], 0
	v_mfma_f32_16x16x32_bf16 v[8:11], v[176:179], v[200:203], 0
	v_mfma_f32_16x16x32_bf16 v[4:7], v[168:171], v[208:211], 0
	v_mfma_f32_16x16x32_bf16 v[0:3], v[176:179], v[208:211], 0
	v_mfma_f32_16x16x32_bf16 v[48:51], v[172:175], v[188:191], v[48:51]
	v_mfma_f32_16x16x32_bf16 v[40:43], v[180:183], v[188:191], v[40:43]
	v_mfma_f32_16x16x32_bf16 v[32:35], v[172:175], v[196:199], v[32:35]
	v_mfma_f32_16x16x32_bf16 v[24:27], v[180:183], v[196:199], v[24:27]
	v_mfma_f32_16x16x32_bf16 v[16:19], v[172:175], v[204:207], v[16:19]
	v_mfma_f32_16x16x32_bf16 v[8:11], v[180:183], v[204:207], v[8:11]
	v_mfma_f32_16x16x32_bf16 v[4:7], v[172:175], v[212:215], v[4:7]
	v_mfma_f32_16x16x32_bf16 v[0:3], v[180:183], v[212:215], v[0:3]
	s_setprio 0
	s_barrier
	s_add_i32 s33, 0, 0x18000
	v_add_u32_e32 v155, s33, v149
	s_add_i32 s34, 0, 0x1c000
	ds_read_b128 v[144:147], v155
	ds_read_b128 v[156:159], v155 offset:1024
	ds_read_b128 v[160:163], v155 offset:2048
	ds_read_b128 v[164:167], v155 offset:3072
	v_add_u32_e32 v155, s34, v149
	ds_read_b128 v[168:171], v155
	ds_read_b128 v[172:175], v155 offset:1024
	ds_read_b128 v[176:179], v155 offset:2048
	ds_read_b128 v[180:183], v155 offset:3072
	s_add_u32 s46, s46, 0x40000
	s_addc_u32 s47, s47, 0
	s_mov_b32 m0, s70
	ds_read_b128 v[184:187], v154 offset:32768
	ds_read_b128 v[188:191], v154 offset:33792
	ds_read_b128 v[192:195], v154 offset:34816
	ds_read_b128 v[196:199], v154 offset:35840
	ds_read_b128 v[200:203], v154 offset:36864
	ds_read_b128 v[204:207], v154 offset:37888
	ds_read_b128 v[208:211], v154 offset:38912
	ds_read_b128 v[212:215], v154 offset:39936
	global_load_lds_dwordx4 v128, s[46:47]
	s_mov_b32 m0, s71
	s_nop 0
	global_load_lds_dwordx4 v132, s[46:47]
	s_waitcnt vmcnt(8)
	s_waitcnt lgkmcnt(0)
	s_barrier
	s_setprio 1
	s_waitcnt lgkmcnt(0)
	v_mfma_f32_16x16x32_bf16 v[124:127], v[144:147], v[184:187], v[124:127]
	v_mfma_f32_16x16x32_bf16 v[120:123], v[160:163], v[184:187], v[120:123]
	v_mfma_f32_16x16x32_bf16 v[116:119], v[144:147], v[192:195], v[116:119]
	v_mfma_f32_16x16x32_bf16 v[108:111], v[160:163], v[192:195], v[108:111]
	v_mfma_f32_16x16x32_bf16 v[100:103], v[144:147], v[200:203], v[100:103]
	v_mfma_f32_16x16x32_bf16 v[92:95], v[160:163], v[200:203], v[92:95]
	v_mfma_f32_16x16x32_bf16 v[84:87], v[144:147], v[208:211], v[84:87]
	v_mfma_f32_16x16x32_bf16 v[76:79], v[160:163], v[208:211], v[76:79]
	v_mfma_f32_16x16x32_bf16 v[124:127], v[156:159], v[188:191], v[124:127]
	v_mfma_f32_16x16x32_bf16 v[120:123], v[164:167], v[188:191], v[120:123]
	v_mfma_f32_16x16x32_bf16 v[116:119], v[156:159], v[196:199], v[116:119]
	v_mfma_f32_16x16x32_bf16 v[108:111], v[164:167], v[196:199], v[108:111]
	v_mfma_f32_16x16x32_bf16 v[100:103], v[156:159], v[204:207], v[100:103]
	v_mfma_f32_16x16x32_bf16 v[92:95], v[164:167], v[204:207], v[92:95]
	v_mfma_f32_16x16x32_bf16 v[84:87], v[156:159], v[212:215], v[84:87]
	v_mfma_f32_16x16x32_bf16 v[76:79], v[164:167], v[212:215], v[76:79]
	s_setprio 0
	s_setprio 1
	v_mfma_f32_16x16x32_bf16 v[112:115], v[168:171], v[184:187], v[112:115]
	v_mfma_f32_16x16x32_bf16 v[104:107], v[176:179], v[184:187], v[104:107]
	v_mfma_f32_16x16x32_bf16 v[96:99], v[168:171], v[192:195], v[96:99]
	v_mfma_f32_16x16x32_bf16 v[88:91], v[176:179], v[192:195], v[88:91]
	v_mfma_f32_16x16x32_bf16 v[80:83], v[168:171], v[200:203], v[80:83]
	v_mfma_f32_16x16x32_bf16 v[72:75], v[176:179], v[200:203], v[72:75]
	v_mfma_f32_16x16x32_bf16 v[68:71], v[168:171], v[208:211], v[68:71]
	v_mfma_f32_16x16x32_bf16 v[64:67], v[176:179], v[208:211], v[64:67]
	v_mfma_f32_16x16x32_bf16 v[112:115], v[172:175], v[188:191], v[112:115]
	v_mfma_f32_16x16x32_bf16 v[104:107], v[180:183], v[188:191], v[104:107]
	v_mfma_f32_16x16x32_bf16 v[96:99], v[172:175], v[196:199], v[96:99]
	v_mfma_f32_16x16x32_bf16 v[88:91], v[180:183], v[196:199], v[88:91]
	v_mfma_f32_16x16x32_bf16 v[80:83], v[172:175], v[204:207], v[80:83]
	v_mfma_f32_16x16x32_bf16 v[72:75], v[180:183], v[204:207], v[72:75]
	v_mfma_f32_16x16x32_bf16 v[68:71], v[172:175], v[212:215], v[68:71]
	v_mfma_f32_16x16x32_bf16 v[64:67], v[180:183], v[212:215], v[64:67]
	s_setprio 0
	s_barrier
; #define PG8_STAGE(bufoff, gbase, voff) do { _Pragma("unroll") for (int _i = 0; _i < 2; ++_i) \
;         __builtin_amdgcn_global_load_lds((const unsigned*)((const char*)(gbase) + (voff)[_i]), (PG8_LAS unsigned*)(lds + (bufoff) + ldsw + _i * 8192), 16, 0, 0); } while (0)
; #define PG8_LDA(dst, b, h) do { _Pragma("unroll") for (int m = 0; m < 4; ++m) _Pragma("unroll") for (int k = 0; k < 2; ++k) dst[m][k] = *(const PG8_LAS bf16x8*)(lds + PG8_SA(b, h) + aoff + m * 2048 + k * 1024); } while (0)
; #define PG8_MMA(ai, bj, At, Bt) do { __builtin_amdgcn_s_setprio(1); _Pragma("unroll") for (int m = 0; m < 4; ++m) _Pragma("unroll") for (int n = 0; n < 2; ++n) _Pragma("unroll") for (int k = 0; k < 2; ++k) \
;         acc[ai][bj][m][n] = __builtin_amdgcn_mfma_f32_16x16x32_bf16(Bt[n][k], At[m][k], acc[ai][bj][m][n], 0, 0, 0); __builtin_amdgcn_s_setprio(0); } while (0)
; #define PG8_WAIT_V(n) asm volatile("s_waitcnt vmcnt(" #n ")" ::: "memory")
; #define PG8_WAIT_L(n) asm volatile("s_waitcnt lgkmcnt(" #n ")" ::: "memory")
; #define PG8_BAR __builtin_amdgcn_s_barrier()
; #define PG8_SCHED __builtin_amdgcn_sched_barrier(0)
; template <class Epi, class Sched, bool ALIGN_EPI = false, bool SP2 = false>
; __device__ __forceinline__ void gemm_phase(PG8_LAS unsigned char* lds, const Gemm g, const Sched& S, const Epi& E) {
;     ...
;             PG8_LDA(At, 1, 1); PG8_STAGE(PG8_SB(1, 0), b3, voffB); PG8_STAGE(PG8_SB(1, 1), b3 + hstep, voffB); PG8_STAGE(PG8_SA(1, 0), a3, voffA);
;             PG8_WAIT_V(8); PG8_WAIT_L(0); PG8_BAR; PG8_MMA(1, 0, At, B0); PG8_MMA(1, 1, At, B1); PG8_BAR; PG8_SCHED;
	s_add_i32 s33, s33, s54
	s_mov_b32 m0, s33
	ds_read_b128 v[184:187], v154 offset:49152
	ds_read_b128 v[188:191], v154 offset:50176
	ds_read_b128 v[192:195], v154 offset:51200
	ds_read_b128 v[196:199], v154 offset:52224
	ds_read_b128 v[200:203], v154 offset:53248
	ds_read_b128 v[204:207], v154 offset:54272
	ds_read_b128 v[208:211], v154 offset:55296
	ds_read_b128 v[212:215], v154 offset:56320
	global_load_lds_dwordx4 v130, s[56:57]
	s_add_i32 m0, s33, 0x2000
	s_add_u32 s44, s44, 0x40080
	s_addc_u32 s45, s45, 0
	s_add_i32 s33, s34, s54
	global_load_lds_dwordx4 v134, s[56:57]
	s_mov_b32 m0, s33
	s_nop 0
	global_load_lds_dwordx4 v130, s[44:45]
	s_add_i32 m0, s33, 0x2000
	s_nop 0
	global_load_lds_dwordx4 v134, s[44:45]
	s_mov_b32 m0, s74
	s_nop 0
	global_load_lds_dwordx4 v128, s[58:59]
	s_mov_b32 m0, s75
	s_nop 0
	global_load_lds_dwordx4 v132, s[58:59]
	s_waitcnt vmcnt(8)
	s_waitcnt lgkmcnt(0)
	s_barrier
	s_setprio 1
	s_waitcnt lgkmcnt(0)
	v_mfma_f32_16x16x32_bf16 v[60:63], v[144:147], v[184:187], v[60:63]
	v_mfma_f32_16x16x32_bf16 v[56:59], v[160:163], v[184:187], v[56:59]
	v_mfma_f32_16x16x32_bf16 v[52:55], v[144:147], v[192:195], v[52:55]
	v_mfma_f32_16x16x32_bf16 v[44:47], v[160:163], v[192:195], v[44:47]
	v_mfma_f32_16x16x32_bf16 v[36:39], v[144:147], v[200:203], v[36:39]
	v_mfma_f32_16x16x32_bf16 v[28:31], v[160:163], v[200:203], v[28:31]
	v_mfma_f32_16x16x32_bf16 v[20:23], v[144:147], v[208:211], v[20:23]
	v_mfma_f32_16x16x32_bf16 v[12:15], v[160:163], v[208:211], v[12:15]
	v_mfma_f32_16x16x32_bf16 v[60:63], v[156:159], v[188:191], v[60:63]
	v_mfma_f32_16x16x32_bf16 v[56:59], v[164:167], v[188:191], v[56:59]
	v_mfma_f32_16x16x32_bf16 v[52:55], v[156:159], v[196:199], v[52:55]
	v_mfma_f32_16x16x32_bf16 v[44:47], v[164:167], v[196:199], v[44:47]
	v_mfma_f32_16x16x32_bf16 v[36:39], v[156:159], v[204:207], v[36:39]
	v_mfma_f32_16x16x32_bf16 v[28:31], v[164:167], v[204:207], v[28:31]
	v_mfma_f32_16x16x32_bf16 v[20:23], v[156:159], v[212:215], v[20:23]
	v_mfma_f32_16x16x32_bf16 v[12:15], v[164:167], v[212:215], v[12:15]
	s_setprio 0
	s_setprio 1
	v_mfma_f32_16x16x32_bf16 v[48:51], v[168:171], v[184:187], v[48:51]
	v_mfma_f32_16x16x32_bf16 v[40:43], v[176:179], v[184:187], v[40:43]
	v_mfma_f32_16x16x32_bf16 v[32:35], v[168:171], v[192:195], v[32:35]
	v_mfma_f32_16x16x32_bf16 v[24:27], v[176:179], v[192:195], v[24:27]
	v_mfma_f32_16x16x32_bf16 v[16:19], v[168:171], v[200:203], v[16:19]
	v_mfma_f32_16x16x32_bf16 v[8:11], v[176:179], v[200:203], v[8:11]
	v_mfma_f32_16x16x32_bf16 v[4:7], v[168:171], v[208:211], v[4:7]
	v_mfma_f32_16x16x32_bf16 v[0:3], v[176:179], v[208:211], v[0:3]
	v_mfma_f32_16x16x32_bf16 v[48:51], v[172:175], v[188:191], v[48:51]
	v_mfma_f32_16x16x32_bf16 v[40:43], v[180:183], v[188:191], v[40:43]
	v_mfma_f32_16x16x32_bf16 v[32:35], v[172:175], v[196:199], v[32:35]
	v_mfma_f32_16x16x32_bf16 v[24:27], v[180:183], v[196:199], v[24:27]
	v_mfma_f32_16x16x32_bf16 v[16:19], v[172:175], v[204:207], v[16:19]
	v_mfma_f32_16x16x32_bf16 v[8:11], v[180:183], v[204:207], v[8:11]
	v_mfma_f32_16x16x32_bf16 v[4:7], v[172:175], v[212:215], v[4:7]
	v_mfma_f32_16x16x32_bf16 v[0:3], v[180:183], v[212:215], v[0:3]
	s_setprio 0
	s_barrier
	s_add_i32 s86, s86, 2
	s_add_u32 s42, s42, 0x100
	s_addc_u32 s43, s43, 0
	s_add_u32 s82, s82, 0x100
	s_addc_u32 s83, s83, 0
	s_cmp_gt_u32 s86, 13

; #define PG8_STAGE(bufoff, gbase, voff) do { _Pragma("unroll") for (int _i = 0; _i < 2; ++_i) \
;         __builtin_amdgcn_global_load_lds((const unsigned*)((const char*)(gbase) + (voff)[_i]), (PG8_LAS unsigned*)(lds + (bufoff) + ldsw + _i * 8192), 16, 0, 0); } while (0)
; #define PG8_LDA(dst, b, h) do { _Pragma("unroll") for (int m = 0; m < 4; ++m) _Pragma("unroll") for (int k = 0; k < 2; ++k) dst[m][k] = *(const PG8_LAS bf16x8*)(lds + PG8_SA(b, h) + aoff + m * 2048 + k * 1024); } while (0)
; #define PG8_LDB(dst, b, h) do { _Pragma("unroll") for (int n = 0; n < 2; ++n) _Pragma("unroll") for (int k = 0; k < 2; ++k) dst[n][k] = *(const PG8_LAS bf16x8*)(lds + PG8_SB(b, h) + boff + n * 2048 + k * 1024); } while (0)
; #define PG8_WAIT_V(n) asm volatile("s_waitcnt vmcnt(" #n ")" ::: "memory")
; #define PG8_WAIT_L(n) asm volatile("s_waitcnt lgkmcnt(" #n ")" ::: "memory")
; #define PG8_BAR __builtin_amdgcn_s_barrier()
; #define PG8_SCHED __builtin_amdgcn_sched_barrier(0)
; template <class Epi, class Sched, bool ALIGN_EPI = false, bool SP2 = false>
; __device__ __forceinline__ void gemm_phase(PG8_LAS unsigned char* lds, const Gemm g, const Sched& S, const Epi& E) {
;     ...
;         const bool has_next = S.next(ui + 1, nxt);
;         const char* nA = has_next ? (const char*)g.A + (size_t)nxt.pm * tstep : cA; const char* nB = has_next ? (const char*)g.Bt + (size_t)nxt.pn * tstep : cB;
;         for (int t = 0; t < nt; t += 2) {
;             const bool last = (t == nt - 2);
;             const char* a1 = cA + (size_t)(t + 1) * kstep;
;             const char* a2 = last ? nA : cA + (size_t)(t + 2) * kstep; const char* b2 = last ? nB : cB + (size_t)(t + 2) * kstep;
;             const char* a3 = a2 + kstep; const char* b3 = b2 + kstep;
;             if (last && has_next) S.a_ready(nxt);
;             if constexpr (SP2) {
;             PG8_LDB(B0, 0, 0); PG8_LDB(B1, 0, 1); PG8_SCHED; PG8_LDA(At, 0, 0); PG8_STAGE(PG8_SA(1, 1), a1 + hstep, voffA);
;             PG8_WAIT_V(8); PG8_WAIT_L(0); PG8_BAR; PG8_MMA(0, 0, At, B0); PG8_MMA(0, 1, At, B1); PG8_BAR; PG8_SCHED;
;             PG8_LDA(At, 0, 1); PG8_STAGE(PG8_SB(0, 0), b2, voffB); PG8_STAGE(PG8_SB(0, 1), b2 + hstep, voffB); PG8_STAGE(PG8_SA(0, 0), a2, voffA);
;             PG8_WAIT_V(8); PG8_WAIT_L(0); PG8_BAR; PG8_MMA(1, 0, At, B0); PG8_MMA(1, 1, At, B1); PG8_BAR; PG8_SCHED;
.LBB0_589:
	s_ashr_i32 s43, s42, 31
	s_lshl_b64 s[44:45], s[42:43], 19
	s_add_u32 s44, s60, s44
	s_addc_u32 s45, s61, s45
	s_and_b64 s[46:47], s[0:1], exec
	s_cselect_b32 s43, s45, s55
	s_cselect_b32 s86, s44, s54
	s_ashr_i32 s41, s40, 31
	s_lshl_b64 s[46:47], s[40:41], 19
	s_add_u32 s46, s62, s46
	s_addc_u32 s47, s63, s47
	s_and_b64 s[58:59], s[0:1], exec
	s_cselect_b32 s41, s47, s57
	s_cselect_b32 s87, s46, s56
	s_add_u32 s54, s54, 0x40080
	s_addc_u32 s55, s55, 0
	s_add_u32 s90, s56, 0x100
	s_addc_u32 s91, s57, 0
	s_mov_b32 s92, -2
	s_waitcnt lgkmcnt(0)
	ds_read_b128 v[128:131], v165
	ds_read_b128 v[132:135], v165 offset:1024
	ds_read_b128 v[154:157], v165 offset:2048
	ds_read_b128 v[158:161], v165 offset:3072
	ds_read_b128 v[168:171], v166
	ds_read_b128 v[172:175], v166 offset:1024
	ds_read_b128 v[176:179], v166 offset:2048
	ds_read_b128 v[180:183], v166 offset:3072
	s_add_u32 s33, s54, 0xfffc0080
	s_addc_u32 s34, s55, -1
	s_cmp_eq_u32 s92, 12
	s_cselect_b32 s59, s43, s34
	s_cselect_b32 s58, s86, s33
	s_cselect_b32 s57, s41, s91
	s_cselect_b32 s56, s87, s90
	s_add_i32 m0, s53, 0xc000
	ds_read_b128 v[184:187], v167
	ds_read_b128 v[188:191], v167 offset:1024
	ds_read_b128 v[192:195], v167 offset:2048
	ds_read_b128 v[196:199], v167 offset:3072
	ds_read_b128 v[200:203], v167 offset:4096
	ds_read_b128 v[204:207], v167 offset:5120
	ds_read_b128 v[208:211], v167 offset:6144
	ds_read_b128 v[212:215], v167 offset:7168
	global_load_lds_dwordx4 v144, s[54:55]
	s_add_i32 m0, s53, 0xe000
	s_nop 0
	global_load_lds_dwordx4 v146, s[54:55]
	s_waitcnt vmcnt(8)
	s_waitcnt lgkmcnt(0)
	s_barrier
	s_setprio 1
	s_waitcnt lgkmcnt(0)
	v_mfma_f32_16x16x32_bf16 v[124:127], v[128:131], v[184:187], 0
	v_mfma_f32_16x16x32_bf16 v[120:123], v[154:157], v[184:187], 0
	v_mfma_f32_16x16x32_bf16 v[116:119], v[128:131], v[192:195], 0
	v_mfma_f32_16x16x32_bf16 v[112:115], v[154:157], v[192:195], 0
	v_mfma_f32_16x16x32_bf16 v[108:111], v[128:131], v[200:203], 0
	v_mfma_f32_16x16x32_bf16 v[104:107], v[154:157], v[200:203], 0
	v_mfma_f32_16x16x32_bf16 v[100:103], v[128:131], v[208:211], 0
	v_mfma_f32_16x16x32_bf16 v[96:99], v[154:157], v[208:211], 0
	v_mfma_f32_16x16x32_bf16 v[124:127], v[132:135], v[188:191], v[124:127]
	v_mfma_f32_16x16x32_bf16 v[120:123], v[158:161], v[188:191], v[120:123]
	v_mfma_f32_16x16x32_bf16 v[116:119], v[132:135], v[196:199], v[116:119]
	v_mfma_f32_16x16x32_bf16 v[112:115], v[158:161], v[196:199], v[112:115]
	v_mfma_f32_16x16x32_bf16 v[108:111], v[132:135], v[204:207], v[108:111]
	v_mfma_f32_16x16x32_bf16 v[104:107], v[158:161], v[204:207], v[104:107]
	v_mfma_f32_16x16x32_bf16 v[100:103], v[132:135], v[212:215], v[100:103]
	v_mfma_f32_16x16x32_bf16 v[96:99], v[158:161], v[212:215], v[96:99]
	s_setprio 0
	s_setprio 1
	v_mfma_f32_16x16x32_bf16 v[68:71], v[168:171], v[184:187], 0
	v_mfma_f32_16x16x32_bf16 v[60:63], v[176:179], v[184:187], 0
	v_mfma_f32_16x16x32_bf16 v[52:55], v[168:171], v[192:195], 0
	v_mfma_f32_16x16x32_bf16 v[48:51], v[176:179], v[192:195], 0
	v_mfma_f32_16x16x32_bf16 v[44:47], v[168:171], v[200:203], 0
	v_mfma_f32_16x16x32_bf16 v[40:43], v[176:179], v[200:203], 0
	v_mfma_f32_16x16x32_bf16 v[36:39], v[168:171], v[208:211], 0
	v_mfma_f32_16x16x32_bf16 v[32:35], v[176:179], v[208:211], 0
	v_mfma_f32_16x16x32_bf16 v[68:71], v[172:175], v[188:191], v[68:71]
	v_mfma_f32_16x16x32_bf16 v[60:63], v[180:183], v[188:191], v[60:63]
	v_mfma_f32_16x16x32_bf16 v[52:55], v[172:175], v[196:199], v[52:55]
	v_mfma_f32_16x16x32_bf16 v[48:51], v[180:183], v[196:199], v[48:51]
	v_mfma_f32_16x16x32_bf16 v[44:47], v[172:175], v[204:207], v[44:47]
	v_mfma_f32_16x16x32_bf16 v[40:43], v[180:183], v[204:207], v[40:43]
	v_mfma_f32_16x16x32_bf16 v[36:39], v[172:175], v[212:215], v[36:39]
	v_mfma_f32_16x16x32_bf16 v[32:35], v[180:183], v[212:215], v[32:35]
	s_setprio 0
	s_barrier
	s_add_i32 s33, s81, s70
	s_add_u32 s64, s56, s10
	s_addc_u32 s65, s57, s11
	s_mov_b32 m0, s33
	ds_read_b128 v[184:187], v167 offset:16384
	ds_read_b128 v[188:191], v167 offset:17408
	ds_read_b128 v[192:195], v167 offset:18432
	ds_read_b128 v[196:199], v167 offset:19456
	ds_read_b128 v[200:203], v167 offset:20480
	ds_read_b128 v[204:207], v167 offset:21504
	ds_read_b128 v[208:211], v167 offset:22528
	ds_read_b128 v[212:215], v167 offset:23552
	global_load_lds_dwordx4 v138, s[56:57]
	s_add_i32 m0, s33, 0x2000
	s_add_u32 s94, s56, 0x40000
	s_addc_u32 s95, s57, 0
	s_add_i32 s33, s82, s70
	global_load_lds_dwordx4 v142, s[56:57]
	s_mov_b32 m0, s33
	s_add_u32 s84, s58, s10
	s_addc_u32 s85, s59, s11
	global_load_lds_dwordx4 v138, s[94:95]
	s_add_i32 m0, s33, 0x2000
	s_nop 0
	global_load_lds_dwordx4 v142, s[94:95]
	s_mov_b32 m0, s53
	s_nop 0
	global_load_lds_dwordx4 v136, s[58:59]
	s_mov_b32 m0, s72
	s_nop 0
	global_load_lds_dwordx4 v140, s[58:59]
	s_waitcnt vmcnt(8)
	s_waitcnt lgkmcnt(0)
	s_barrier
; #define PG8_STAGE(bufoff, gbase, voff) do { _Pragma("unroll") for (int _i = 0; _i < 2; ++_i) \
;         __builtin_amdgcn_global_load_lds((const unsigned*)((const char*)(gbase) + (voff)[_i]), (PG8_LAS unsigned*)(lds + (bufoff) + ldsw + _i * 8192), 16, 0, 0); } while (0)
; #define PG8_LDA(dst, b, h) do { _Pragma("unroll") for (int m = 0; m < 4; ++m) _Pragma("unroll") for (int k = 0; k < 2; ++k) dst[m][k] = *(const PG8_LAS bf16x8*)(lds + PG8_SA(b, h) + aoff + m * 2048 + k * 1024); } while (0)
; #define PG8_LDB(dst, b, h) do { _Pragma("unroll") for (int n = 0; n < 2; ++n) _Pragma("unroll") for (int k = 0; k < 2; ++k) dst[n][k] = *(const PG8_LAS bf16x8*)(lds + PG8_SB(b, h) + boff + n * 2048 + k * 1024); } while (0)
; #define PG8_MMA(ai, bj, At, Bt) do { __builtin_amdgcn_s_setprio(1); _Pragma("unroll") for (int m = 0; m < 4; ++m) _Pragma("unroll") for (int n = 0; n < 2; ++n) _Pragma("unroll") for (int k = 0; k < 2; ++k) \
;         acc[ai][bj][m][n] = __builtin_amdgcn_mfma_f32_16x16x32_bf16(Bt[n][k], At[m][k], acc[ai][bj][m][n], 0, 0, 0); __builtin_amdgcn_s_setprio(0); } while (0)
; #define PG8_WAIT_V(n) asm volatile("s_waitcnt vmcnt(" #n ")" ::: "memory")
; #define PG8_WAIT_L(n) asm volatile("s_waitcnt lgkmcnt(" #n ")" ::: "memory")
; #define PG8_BAR __builtin_amdgcn_s_barrier()
; #define PG8_SCHED __builtin_amdgcn_sched_barrier(0)
; template <class Epi, class Sched, bool ALIGN_EPI = false, bool SP2 = false>
; __device__ __forceinline__ void gemm_phase(PG8_LAS unsigned char* lds, const Gemm g, const Sched& S, const Epi& E) {
;     ...
;             PG8_WAIT_V(8); PG8_WAIT_L(0); PG8_BAR; PG8_MMA(1, 0, At, B0); PG8_MMA(1, 1, At, B1); PG8_BAR; PG8_SCHED;
;             PG8_LDB(B0, 1, 0); PG8_LDB(B1, 1, 1); PG8_SCHED; PG8_LDA(At, 1, 0); PG8_STAGE(PG8_SA(0, 1), a2 + hstep, voffA);
;             PG8_WAIT_V(8); PG8_WAIT_L(0); PG8_BAR; PG8_MMA(0, 0, At, B0); PG8_MMA(0, 1, At, B1); PG8_BAR; PG8_SCHED;
	s_setprio 1
	s_waitcnt lgkmcnt(0)
	v_mfma_f32_16x16x32_bf16 v[92:95], v[128:131], v[184:187], 0
	v_mfma_f32_16x16x32_bf16 v[88:91], v[154:157], v[184:187], 0
	v_mfma_f32_16x16x32_bf16 v[84:87], v[128:131], v[192:195], 0
	v_mfma_f32_16x16x32_bf16 v[80:83], v[154:157], v[192:195], 0
	v_mfma_f32_16x16x32_bf16 v[76:79], v[128:131], v[200:203], 0
	v_mfma_f32_16x16x32_bf16 v[72:75], v[154:157], v[200:203], 0
	v_mfma_f32_16x16x32_bf16 v[64:67], v[128:131], v[208:211], 0
	v_mfma_f32_16x16x32_bf16 v[56:59], v[154:157], v[208:211], 0
	v_mfma_f32_16x16x32_bf16 v[92:95], v[132:135], v[188:191], v[92:95]
	v_mfma_f32_16x16x32_bf16 v[88:91], v[158:161], v[188:191], v[88:91]
	v_mfma_f32_16x16x32_bf16 v[84:87], v[132:135], v[196:199], v[84:87]
	v_mfma_f32_16x16x32_bf16 v[80:83], v[158:161], v[196:199], v[80:83]
	v_mfma_f32_16x16x32_bf16 v[76:79], v[132:135], v[204:207], v[76:79]
	v_mfma_f32_16x16x32_bf16 v[72:75], v[158:161], v[204:207], v[72:75]
	v_mfma_f32_16x16x32_bf16 v[64:67], v[132:135], v[212:215], v[64:67]
	v_mfma_f32_16x16x32_bf16 v[56:59], v[158:161], v[212:215], v[56:59]
	s_setprio 0
	s_setprio 1
	v_mfma_f32_16x16x32_bf16 v[28:31], v[168:171], v[184:187], 0
	v_mfma_f32_16x16x32_bf16 v[24:27], v[176:179], v[184:187], 0
	v_mfma_f32_16x16x32_bf16 v[20:23], v[168:171], v[192:195], 0
	v_mfma_f32_16x16x32_bf16 v[16:19], v[176:179], v[192:195], 0
	v_mfma_f32_16x16x32_bf16 v[12:15], v[168:171], v[200:203], 0
	v_mfma_f32_16x16x32_bf16 v[8:11], v[176:179], v[200:203], 0
	v_mfma_f32_16x16x32_bf16 v[4:7], v[168:171], v[208:211], 0
	v_mfma_f32_16x16x32_bf16 v[0:3], v[176:179], v[208:211], 0
	v_mfma_f32_16x16x32_bf16 v[28:31], v[172:175], v[188:191], v[28:31]
	v_mfma_f32_16x16x32_bf16 v[24:27], v[180:183], v[188:191], v[24:27]
	v_mfma_f32_16x16x32_bf16 v[20:23], v[172:175], v[196:199], v[20:23]
	v_mfma_f32_16x16x32_bf16 v[16:19], v[180:183], v[196:199], v[16:19]
	v_mfma_f32_16x16x32_bf16 v[12:15], v[172:175], v[204:207], v[12:15]
	v_mfma_f32_16x16x32_bf16 v[8:11], v[180:183], v[204:207], v[8:11]
	v_mfma_f32_16x16x32_bf16 v[4:7], v[172:175], v[212:215], v[4:7]
	v_mfma_f32_16x16x32_bf16 v[0:3], v[180:183], v[212:215], v[0:3]
	s_setprio 0
	s_barrier
	s_add_i32 s33, 0, 0x18000
	v_add_u32_e32 v153, s33, v163
	s_add_i32 s34, 0, 0x1c000
	ds_read_b128 v[128:131], v153
	ds_read_b128 v[132:135], v153 offset:1024
	ds_read_b128 v[154:157], v153 offset:2048
	ds_read_b128 v[158:161], v153 offset:3072
	v_add_u32_e32 v153, s34, v163
	ds_read_b128 v[168:171], v153
	ds_read_b128 v[172:175], v153 offset:1024
	ds_read_b128 v[176:179], v153 offset:2048
	ds_read_b128 v[180:183], v153 offset:3072
	s_add_u32 s58, s58, 0x40000
	s_addc_u32 s59, s59, 0
	s_mov_b32 m0, s73
	ds_read_b128 v[184:187], v167 offset:32768
	ds_read_b128 v[188:191], v167 offset:33792
	ds_read_b128 v[192:195], v167 offset:34816
	ds_read_b128 v[196:199], v167 offset:35840
	ds_read_b128 v[200:203], v167 offset:36864
	ds_read_b128 v[204:207], v167 offset:37888
	ds_read_b128 v[208:211], v167 offset:38912
	ds_read_b128 v[212:215], v167 offset:39936
	global_load_lds_dwordx4 v136, s[58:59]
	s_mov_b32 m0, s74
	s_nop 0
	global_load_lds_dwordx4 v140, s[58:59]
	s_waitcnt vmcnt(8)
	s_waitcnt lgkmcnt(0)
	s_barrier
	s_setprio 1
	s_waitcnt lgkmcnt(0)
	v_mfma_f32_16x16x32_bf16 v[124:127], v[128:131], v[184:187], v[124:127]
	v_mfma_f32_16x16x32_bf16 v[120:123], v[154:157], v[184:187], v[120:123]
	v_mfma_f32_16x16x32_bf16 v[116:119], v[128:131], v[192:195], v[116:119]
	v_mfma_f32_16x16x32_bf16 v[112:115], v[154:157], v[192:195], v[112:115]
	v_mfma_f32_16x16x32_bf16 v[108:111], v[128:131], v[200:203], v[108:111]
	v_mfma_f32_16x16x32_bf16 v[104:107], v[154:157], v[200:203], v[104:107]
	v_mfma_f32_16x16x32_bf16 v[100:103], v[128:131], v[208:211], v[100:103]
	v_mfma_f32_16x16x32_bf16 v[96:99], v[154:157], v[208:211], v[96:99]
	v_mfma_f32_16x16x32_bf16 v[124:127], v[132:135], v[188:191], v[124:127]
	v_mfma_f32_16x16x32_bf16 v[120:123], v[158:161], v[188:191], v[120:123]
	v_mfma_f32_16x16x32_bf16 v[116:119], v[132:135], v[196:199], v[116:119]
	v_mfma_f32_16x16x32_bf16 v[112:115], v[158:161], v[196:199], v[112:115]
	v_mfma_f32_16x16x32_bf16 v[108:111], v[132:135], v[204:207], v[108:111]
	v_mfma_f32_16x16x32_bf16 v[104:107], v[158:161], v[204:207], v[104:107]
	v_mfma_f32_16x16x32_bf16 v[100:103], v[132:135], v[212:215], v[100:103]
	v_mfma_f32_16x16x32_bf16 v[96:99], v[158:161], v[212:215], v[96:99]
	s_setprio 0
	s_setprio 1
	v_mfma_f32_16x16x32_bf16 v[68:71], v[168:171], v[184:187], v[68:71]
	v_mfma_f32_16x16x32_bf16 v[60:63], v[176:179], v[184:187], v[60:63]
	v_mfma_f32_16x16x32_bf16 v[52:55], v[168:171], v[192:195], v[52:55]
	v_mfma_f32_16x16x32_bf16 v[48:51], v[176:179], v[192:195], v[48:51]
	v_mfma_f32_16x16x32_bf16 v[44:47], v[168:171], v[200:203], v[44:47]
	v_mfma_f32_16x16x32_bf16 v[40:43], v[176:179], v[200:203], v[40:43]
	v_mfma_f32_16x16x32_bf16 v[36:39], v[168:171], v[208:211], v[36:39]
	v_mfma_f32_16x16x32_bf16 v[32:35], v[176:179], v[208:211], v[32:35]
	v_mfma_f32_16x16x32_bf16 v[68:71], v[172:175], v[188:191], v[68:71]
	v_mfma_f32_16x16x32_bf16 v[60:63], v[180:183], v[188:191], v[60:63]
	v_mfma_f32_16x16x32_bf16 v[52:55], v[172:175], v[196:199], v[52:55]
	v_mfma_f32_16x16x32_bf16 v[48:51], v[180:183], v[196:199], v[48:51]
	v_mfma_f32_16x16x32_bf16 v[44:47], v[172:175], v[204:207], v[44:47]
	v_mfma_f32_16x16x32_bf16 v[40:43], v[180:183], v[204:207], v[40:43]
	v_mfma_f32_16x16x32_bf16 v[36:39], v[172:175], v[212:215], v[36:39]
	v_mfma_f32_16x16x32_bf16 v[32:35], v[180:183], v[212:215], v[32:35]
	s_setprio 0
	s_barrier
; #define PG8_STAGE(bufoff, gbase, voff) do { _Pragma("unroll") for (int _i = 0; _i < 2; ++_i) \
;         __builtin_amdgcn_global_load_lds((const unsigned*)((const char*)(gbase) + (voff)[_i]), (PG8_LAS unsigned*)(lds + (bufoff) + ldsw + _i * 8192), 16, 0, 0); } while (0)
; #define PG8_LDA(dst, b, h) do { _Pragma("unroll") for (int m = 0; m < 4; ++m) _Pragma("unroll") for (int k = 0; k < 2; ++k) dst[m][k] = *(const PG8_LAS bf16x8*)(lds + PG8_SA(b, h) + aoff + m * 2048 + k * 1024); } while (0)
; #define PG8_MMA(ai, bj, At, Bt) do { __builtin_amdgcn_s_setprio(1); _Pragma("unroll") for (int m = 0; m < 4; ++m) _Pragma("unroll") for (int n = 0; n < 2; ++n) _Pragma("unroll") for (int k = 0; k < 2; ++k) \
;         acc[ai][bj][m][n] = __builtin_amdgcn_mfma_f32_16x16x32_bf16(Bt[n][k], At[m][k], acc[ai][bj][m][n], 0, 0, 0); __builtin_amdgcn_s_setprio(0); } while (0)
; #define PG8_WAIT_V(n) asm volatile("s_waitcnt vmcnt(" #n ")" ::: "memory")
; #define PG8_WAIT_L(n) asm volatile("s_waitcnt lgkmcnt(" #n ")" ::: "memory")
; #define PG8_BAR __builtin_amdgcn_s_barrier()
; #define PG8_SCHED __builtin_amdgcn_sched_barrier(0)
; template <class Epi, class Sched, bool ALIGN_EPI = false, bool SP2 = false>
; __device__ __forceinline__ void gemm_phase(PG8_LAS unsigned char* lds, const Gemm g, const Sched& S, const Epi& E) {
;     ...
;             PG8_LDA(At, 1, 1); PG8_STAGE(PG8_SB(1, 0), b3, voffB); PG8_STAGE(PG8_SB(1, 1), b3 + hstep, voffB); PG8_STAGE(PG8_SA(1, 0), a3, voffA);
;             PG8_WAIT_V(8); PG8_WAIT_L(0); PG8_BAR; PG8_MMA(1, 0, At, B0); PG8_MMA(1, 1, At, B1); PG8_BAR; PG8_SCHED;
	s_add_i32 s33, s33, s70
	s_mov_b32 m0, s33
	ds_read_b128 v[184:187], v167 offset:49152
	ds_read_b128 v[188:191], v167 offset:50176
	ds_read_b128 v[192:195], v167 offset:51200
	ds_read_b128 v[196:199], v167 offset:52224
	ds_read_b128 v[200:203], v167 offset:53248
	ds_read_b128 v[204:207], v167 offset:54272
	ds_read_b128 v[208:211], v167 offset:55296
	ds_read_b128 v[212:215], v167 offset:56320
	global_load_lds_dwordx4 v138, s[64:65]
	s_add_i32 m0, s33, 0x2000
	s_add_u32 s56, s56, 0x40080
	s_addc_u32 s57, s57, 0
	s_add_i32 s33, s34, s70
	global_load_lds_dwordx4 v142, s[64:65]
	s_mov_b32 m0, s33
	s_nop 0
	global_load_lds_dwordx4 v138, s[56:57]
	s_add_i32 m0, s33, 0x2000
	s_nop 0
	global_load_lds_dwordx4 v142, s[56:57]
	s_mov_b32 m0, s79
	s_nop 0
	global_load_lds_dwordx4 v136, s[84:85]
	s_mov_b32 m0, s80
	s_nop 0
	global_load_lds_dwordx4 v140, s[84:85]
	s_waitcnt vmcnt(8)
	s_waitcnt lgkmcnt(0)
	s_barrier
	s_setprio 1
	s_waitcnt lgkmcnt(0)
	v_mfma_f32_16x16x32_bf16 v[92:95], v[128:131], v[184:187], v[92:95]
	v_mfma_f32_16x16x32_bf16 v[88:91], v[154:157], v[184:187], v[88:91]
	v_mfma_f32_16x16x32_bf16 v[84:87], v[128:131], v[192:195], v[84:87]
	v_mfma_f32_16x16x32_bf16 v[80:83], v[154:157], v[192:195], v[80:83]
	v_mfma_f32_16x16x32_bf16 v[76:79], v[128:131], v[200:203], v[76:79]
	v_mfma_f32_16x16x32_bf16 v[72:75], v[154:157], v[200:203], v[72:75]
	v_mfma_f32_16x16x32_bf16 v[64:67], v[128:131], v[208:211], v[64:67]
	v_mfma_f32_16x16x32_bf16 v[56:59], v[154:157], v[208:211], v[56:59]
	v_mfma_f32_16x16x32_bf16 v[92:95], v[132:135], v[188:191], v[92:95]
	v_mfma_f32_16x16x32_bf16 v[88:91], v[158:161], v[188:191], v[88:91]
	v_mfma_f32_16x16x32_bf16 v[84:87], v[132:135], v[196:199], v[84:87]
	v_mfma_f32_16x16x32_bf16 v[80:83], v[158:161], v[196:199], v[80:83]
	v_mfma_f32_16x16x32_bf16 v[76:79], v[132:135], v[204:207], v[76:79]
	v_mfma_f32_16x16x32_bf16 v[72:75], v[158:161], v[204:207], v[72:75]
	v_mfma_f32_16x16x32_bf16 v[64:67], v[132:135], v[212:215], v[64:67]
	v_mfma_f32_16x16x32_bf16 v[56:59], v[158:161], v[212:215], v[56:59]
	s_setprio 0
	s_setprio 1
	v_mfma_f32_16x16x32_bf16 v[28:31], v[168:171], v[184:187], v[28:31]
	v_mfma_f32_16x16x32_bf16 v[24:27], v[176:179], v[184:187], v[24:27]
	v_mfma_f32_16x16x32_bf16 v[20:23], v[168:171], v[192:195], v[20:23]
	v_mfma_f32_16x16x32_bf16 v[16:19], v[176:179], v[192:195], v[16:19]
	v_mfma_f32_16x16x32_bf16 v[12:15], v[168:171], v[200:203], v[12:15]
	v_mfma_f32_16x16x32_bf16 v[8:11], v[176:179], v[200:203], v[8:11]
	v_mfma_f32_16x16x32_bf16 v[4:7], v[168:171], v[208:211], v[4:7]
	v_mfma_f32_16x16x32_bf16 v[0:3], v[176:179], v[208:211], v[0:3]
	v_mfma_f32_16x16x32_bf16 v[28:31], v[172:175], v[188:191], v[28:31]
	v_mfma_f32_16x16x32_bf16 v[24:27], v[180:183], v[188:191], v[24:27]
	v_mfma_f32_16x16x32_bf16 v[20:23], v[172:175], v[196:199], v[20:23]
	v_mfma_f32_16x16x32_bf16 v[16:19], v[180:183], v[196:199], v[16:19]
	v_mfma_f32_16x16x32_bf16 v[12:15], v[172:175], v[204:207], v[12:15]
	v_mfma_f32_16x16x32_bf16 v[8:11], v[180:183], v[204:207], v[8:11]
	v_mfma_f32_16x16x32_bf16 v[4:7], v[172:175], v[212:215], v[4:7]
	v_mfma_f32_16x16x32_bf16 v[0:3], v[180:183], v[212:215], v[0:3]
	s_setprio 0
	s_barrier
	s_add_i32 s92, s92, 2
	s_add_u32 s54, s54, 0x100
	s_addc_u32 s55, s55, 0
	s_add_u32 s90, s90, 0x100
	s_addc_u32 s91, s91, 0
	s_cmp_gt_u32 s92, 13

; #define PG8_STAGE(bufoff, gbase, voff) do { _Pragma("unroll") for (int _i = 0; _i < 2; ++_i) \
;         __builtin_amdgcn_global_load_lds((const unsigned*)((const char*)(gbase) + (voff)[_i]), (PG8_LAS unsigned*)(lds + (bufoff) + ldsw + _i * 8192), 16, 0, 0); } while (0)
; #define PG8_LDA(dst, b, h) do { _Pragma("unroll") for (int m = 0; m < 4; ++m) _Pragma("unroll") for (int k = 0; k < 2; ++k) dst[m][k] = *(const PG8_LAS bf16x8*)(lds + PG8_SA(b, h) + aoff + m * 2048 + k * 1024); } while (0)
; #define PG8_LDB(dst, b, h) do { _Pragma("unroll") for (int n = 0; n < 2; ++n) _Pragma("unroll") for (int k = 0; k < 2; ++k) dst[n][k] = *(const PG8_LAS bf16x8*)(lds + PG8_SB(b, h) + boff + n * 2048 + k * 1024); } while (0)
; #define PG8_WAIT_V(n) asm volatile("s_waitcnt vmcnt(" #n ")" ::: "memory")
; #define PG8_WAIT_L(n) asm volatile("s_waitcnt lgkmcnt(" #n ")" ::: "memory")
; #define PG8_BAR __builtin_amdgcn_s_barrier()
; #define PG8_SCHED __builtin_amdgcn_sched_barrier(0)
; template <class Epi, class Sched, bool ALIGN_EPI = false, bool SP2 = false>
; __device__ __forceinline__ void gemm_phase(PG8_LAS unsigned char* lds, const Gemm g, const Sched& S, const Epi& E) {
;     ...
;         const bool has_next = S.next(ui + 1, nxt);
;         const char* nA = has_next ? (const char*)g.A + (size_t)nxt.pm * tstep : cA; const char* nB = has_next ? (const char*)g.Bt + (size_t)nxt.pn * tstep : cB;
;         for (int t = 0; t < nt; t += 2) {
;             const bool last = (t == nt - 2);
;             const char* a1 = cA + (size_t)(t + 1) * kstep;
;             const char* a2 = last ? nA : cA + (size_t)(t + 2) * kstep; const char* b2 = last ? nB : cB + (size_t)(t + 2) * kstep;
;             const char* a3 = a2 + kstep; const char* b3 = b2 + kstep;
;             if (last && has_next) S.a_ready(nxt);
;             if constexpr (SP2) {
;             PG8_LDB(B0, 0, 0); PG8_LDB(B1, 0, 1); PG8_SCHED; PG8_LDA(At, 0, 0); PG8_STAGE(PG8_SA(1, 1), a1 + hstep, voffA);
;             PG8_WAIT_V(8); PG8_WAIT_L(0); PG8_BAR; PG8_MMA(0, 0, At, B0); PG8_MMA(0, 1, At, B1); PG8_BAR; PG8_SCHED;
;             PG8_LDA(At, 0, 1); PG8_STAGE(PG8_SB(0, 0), b2, voffB); PG8_STAGE(PG8_SB(0, 1), b2 + hstep, voffB); PG8_STAGE(PG8_SA(0, 0), a2, voffA);
;             PG8_WAIT_V(8); PG8_WAIT_L(0); PG8_BAR; PG8_MMA(1, 0, At, B0); PG8_MMA(1, 1, At, B1); PG8_BAR; PG8_SCHED;
.LBB0_713:
	s_ashr_i32 s23, s22, 31
	s_lshl_b64 s[24:25], s[22:23], 19
	s_add_u32 s24, s16, s24
	s_addc_u32 s25, s17, s25
	s_and_b64 s[36:37], s[0:1], exec
	s_cselect_b32 s23, s25, s41
	s_cselect_b32 s72, s24, s40
	s_ashr_i32 s21, s20, 31
	s_lshl_b64 s[36:37], s[20:21], 19
	s_add_u32 s36, s46, s36
	s_addc_u32 s37, s47, s37
	s_and_b64 s[44:45], s[0:1], exec
	s_cselect_b32 s21, s37, s43
	s_cselect_b32 s73, s36, s42
	s_add_u32 s40, s40, 0x40080
	s_addc_u32 s41, s41, 0
	s_add_u32 s74, s42, 0x100
	s_addc_u32 s75, s43, 0
	s_mov_b32 s76, -2
	s_waitcnt lgkmcnt(0)
	ds_read_b128 v[154:157], v147
	ds_read_b128 v[158:161], v147 offset:1024
	ds_read_b128 v[162:165], v147 offset:2048
	ds_read_b128 v[166:169], v147 offset:3072
	ds_read_b128 v[170:173], v148
	ds_read_b128 v[174:177], v148 offset:1024
	ds_read_b128 v[178:181], v148 offset:2048
	ds_read_b128 v[182:185], v148 offset:3072
	s_add_u32 s33, s40, 0xfffc0080
	s_addc_u32 s34, s41, -1
	s_cmp_eq_u32 s76, 12
	s_cselect_b32 s45, s23, s34
	s_cselect_b32 s44, s72, s33
	s_cselect_b32 s43, s21, s75
	s_cselect_b32 s42, s73, s74
	s_add_i32 m0, s39, 0xc000
	ds_read_b128 v[186:189], v149
	ds_read_b128 v[190:193], v149 offset:1024
	ds_read_b128 v[194:197], v149 offset:2048
	ds_read_b128 v[198:201], v149 offset:3072
	ds_read_b128 v[202:205], v149 offset:4096
	ds_read_b128 v[206:209], v149 offset:5120
	ds_read_b128 v[210:213], v149 offset:6144
	ds_read_b128 v[214:217], v149 offset:7168
	global_load_lds_dwordx4 v136, s[40:41]
	s_add_i32 m0, s39, 0xe000
	s_nop 0
	global_load_lds_dwordx4 v138, s[40:41]
	s_waitcnt vmcnt(8)
	s_waitcnt lgkmcnt(0)
	s_barrier
	s_setprio 1
	s_waitcnt lgkmcnt(0)
	v_mfma_f32_16x16x32_bf16 v[124:127], v[154:157], v[186:189], 0
	v_mfma_f32_16x16x32_bf16 v[116:119], v[162:165], v[186:189], 0
	v_mfma_f32_16x16x32_bf16 v[108:111], v[154:157], v[194:197], 0
	v_mfma_f32_16x16x32_bf16 v[100:103], v[162:165], v[194:197], 0
	v_mfma_f32_16x16x32_bf16 v[92:95], v[154:157], v[202:205], 0
	v_mfma_f32_16x16x32_bf16 v[84:87], v[162:165], v[202:205], 0
	v_mfma_f32_16x16x32_bf16 v[76:79], v[154:157], v[210:213], 0
	v_mfma_f32_16x16x32_bf16 v[68:71], v[162:165], v[210:213], 0
	v_mfma_f32_16x16x32_bf16 v[124:127], v[158:161], v[190:193], v[124:127]
	v_mfma_f32_16x16x32_bf16 v[116:119], v[166:169], v[190:193], v[116:119]
	v_mfma_f32_16x16x32_bf16 v[108:111], v[158:161], v[198:201], v[108:111]
	v_mfma_f32_16x16x32_bf16 v[100:103], v[166:169], v[198:201], v[100:103]
	v_mfma_f32_16x16x32_bf16 v[92:95], v[158:161], v[206:209], v[92:95]
	v_mfma_f32_16x16x32_bf16 v[84:87], v[166:169], v[206:209], v[84:87]
	v_mfma_f32_16x16x32_bf16 v[76:79], v[158:161], v[214:217], v[76:79]
	v_mfma_f32_16x16x32_bf16 v[68:71], v[166:169], v[214:217], v[68:71]
	s_setprio 0
	s_setprio 1
	v_mfma_f32_16x16x32_bf16 v[120:123], v[170:173], v[186:189], 0
	v_mfma_f32_16x16x32_bf16 v[112:115], v[178:181], v[186:189], 0
	v_mfma_f32_16x16x32_bf16 v[104:107], v[170:173], v[194:197], 0
	v_mfma_f32_16x16x32_bf16 v[96:99], v[178:181], v[194:197], 0
	v_mfma_f32_16x16x32_bf16 v[88:91], v[170:173], v[202:205], 0
	v_mfma_f32_16x16x32_bf16 v[80:83], v[178:181], v[202:205], 0
	v_mfma_f32_16x16x32_bf16 v[72:75], v[170:173], v[210:213], 0
	v_mfma_f32_16x16x32_bf16 v[64:67], v[178:181], v[210:213], 0
	v_mfma_f32_16x16x32_bf16 v[120:123], v[174:177], v[190:193], v[120:123]
	v_mfma_f32_16x16x32_bf16 v[112:115], v[182:185], v[190:193], v[112:115]
	v_mfma_f32_16x16x32_bf16 v[104:107], v[174:177], v[198:201], v[104:107]
	v_mfma_f32_16x16x32_bf16 v[96:99], v[182:185], v[198:201], v[96:99]
	v_mfma_f32_16x16x32_bf16 v[88:91], v[174:177], v[206:209], v[88:91]
	v_mfma_f32_16x16x32_bf16 v[80:83], v[182:185], v[206:209], v[80:83]
	v_mfma_f32_16x16x32_bf16 v[72:75], v[174:177], v[214:217], v[72:75]
	v_mfma_f32_16x16x32_bf16 v[64:67], v[182:185], v[214:217], v[64:67]
	s_setprio 0
	s_barrier
	s_add_i32 s33, s62, s52
	s_add_u32 s82, s42, s10
	s_addc_u32 s83, s43, s11
	s_mov_b32 m0, s33
	ds_read_b128 v[186:189], v149 offset:16384
	ds_read_b128 v[190:193], v149 offset:17408
	ds_read_b128 v[194:197], v149 offset:18432
	ds_read_b128 v[198:201], v149 offset:19456
	ds_read_b128 v[202:205], v149 offset:20480
	ds_read_b128 v[206:209], v149 offset:21504
	ds_read_b128 v[210:213], v149 offset:22528
	ds_read_b128 v[214:217], v149 offset:23552
	global_load_lds_dwordx4 v130, s[42:43]
	s_add_i32 m0, s33, 0x2000
	s_add_u32 s78, s42, 0x40000
	s_addc_u32 s79, s43, 0
	s_add_i32 s33, s63, s52
	global_load_lds_dwordx4 v134, s[42:43]
	s_mov_b32 m0, s33
	s_add_u32 s84, s44, s10
	s_addc_u32 s85, s45, s11
	global_load_lds_dwordx4 v130, s[78:79]
	s_add_i32 m0, s33, 0x2000
	s_nop 0
	global_load_lds_dwordx4 v134, s[78:79]
	s_mov_b32 m0, s39
	s_nop 0
	global_load_lds_dwordx4 v128, s[44:45]
	s_mov_b32 m0, s55
	s_nop 0
	global_load_lds_dwordx4 v132, s[44:45]
	s_waitcnt vmcnt(8)
	s_waitcnt lgkmcnt(0)
	s_barrier
; #define PG8_STAGE(bufoff, gbase, voff) do { _Pragma("unroll") for (int _i = 0; _i < 2; ++_i) \
;         __builtin_amdgcn_global_load_lds((const unsigned*)((const char*)(gbase) + (voff)[_i]), (PG8_LAS unsigned*)(lds + (bufoff) + ldsw + _i * 8192), 16, 0, 0); } while (0)
; #define PG8_LDA(dst, b, h) do { _Pragma("unroll") for (int m = 0; m < 4; ++m) _Pragma("unroll") for (int k = 0; k < 2; ++k) dst[m][k] = *(const PG8_LAS bf16x8*)(lds + PG8_SA(b, h) + aoff + m * 2048 + k * 1024); } while (0)
; #define PG8_LDB(dst, b, h) do { _Pragma("unroll") for (int n = 0; n < 2; ++n) _Pragma("unroll") for (int k = 0; k < 2; ++k) dst[n][k] = *(const PG8_LAS bf16x8*)(lds + PG8_SB(b, h) + boff + n * 2048 + k * 1024); } while (0)
; #define PG8_MMA(ai, bj, At, Bt) do { __builtin_amdgcn_s_setprio(1); _Pragma("unroll") for (int m = 0; m < 4; ++m) _Pragma("unroll") for (int n = 0; n < 2; ++n) _Pragma("unroll") for (int k = 0; k < 2; ++k) \
;         acc[ai][bj][m][n] = __builtin_amdgcn_mfma_f32_16x16x32_bf16(Bt[n][k], At[m][k], acc[ai][bj][m][n], 0, 0, 0); __builtin_amdgcn_s_setprio(0); } while (0)
; #define PG8_WAIT_V(n) asm volatile("s_waitcnt vmcnt(" #n ")" ::: "memory")
; #define PG8_WAIT_L(n) asm volatile("s_waitcnt lgkmcnt(" #n ")" ::: "memory")
; #define PG8_BAR __builtin_amdgcn_s_barrier()
; #define PG8_SCHED __builtin_amdgcn_sched_barrier(0)
; template <class Epi, class Sched, bool ALIGN_EPI = false, bool SP2 = false>
; __device__ __forceinline__ void gemm_phase(PG8_LAS unsigned char* lds, const Gemm g, const Sched& S, const Epi& E) {
;     ...
;             PG8_WAIT_V(8); PG8_WAIT_L(0); PG8_BAR; PG8_MMA(1, 0, At, B0); PG8_MMA(1, 1, At, B1); PG8_BAR; PG8_SCHED;
;             PG8_LDB(B0, 1, 0); PG8_LDB(B1, 1, 1); PG8_SCHED; PG8_LDA(At, 1, 0); PG8_STAGE(PG8_SA(0, 1), a2 + hstep, voffA);
;             PG8_WAIT_V(8); PG8_WAIT_L(0); PG8_BAR; PG8_MMA(0, 0, At, B0); PG8_MMA(0, 1, At, B1); PG8_BAR; PG8_SCHED;
	s_setprio 1
	s_waitcnt lgkmcnt(0)
	v_mfma_f32_16x16x32_bf16 v[60:63], v[154:157], v[186:189], 0
	v_mfma_f32_16x16x32_bf16 v[52:55], v[162:165], v[186:189], 0
	v_mfma_f32_16x16x32_bf16 v[44:47], v[154:157], v[194:197], 0
	v_mfma_f32_16x16x32_bf16 v[36:39], v[162:165], v[194:197], 0
	v_mfma_f32_16x16x32_bf16 v[28:31], v[154:157], v[202:205], 0
	v_mfma_f32_16x16x32_bf16 v[20:23], v[162:165], v[202:205], 0
	v_mfma_f32_16x16x32_bf16 v[12:15], v[154:157], v[210:213], 0
	v_mfma_f32_16x16x32_bf16 v[4:7], v[162:165], v[210:213], 0
	v_mfma_f32_16x16x32_bf16 v[60:63], v[158:161], v[190:193], v[60:63]
	v_mfma_f32_16x16x32_bf16 v[52:55], v[166:169], v[190:193], v[52:55]
	v_mfma_f32_16x16x32_bf16 v[44:47], v[158:161], v[198:201], v[44:47]
	v_mfma_f32_16x16x32_bf16 v[36:39], v[166:169], v[198:201], v[36:39]
	v_mfma_f32_16x16x32_bf16 v[28:31], v[158:161], v[206:209], v[28:31]
	v_mfma_f32_16x16x32_bf16 v[20:23], v[166:169], v[206:209], v[20:23]
	v_mfma_f32_16x16x32_bf16 v[12:15], v[158:161], v[214:217], v[12:15]
	v_mfma_f32_16x16x32_bf16 v[4:7], v[166:169], v[214:217], v[4:7]
	s_setprio 0
	s_setprio 1
	v_mfma_f32_16x16x32_bf16 v[56:59], v[170:173], v[186:189], 0
	v_mfma_f32_16x16x32_bf16 v[48:51], v[178:181], v[186:189], 0
	v_mfma_f32_16x16x32_bf16 v[40:43], v[170:173], v[194:197], 0
	v_mfma_f32_16x16x32_bf16 v[32:35], v[178:181], v[194:197], 0
	v_mfma_f32_16x16x32_bf16 v[24:27], v[170:173], v[202:205], 0
	v_mfma_f32_16x16x32_bf16 v[16:19], v[178:181], v[202:205], 0
	v_mfma_f32_16x16x32_bf16 v[8:11], v[170:173], v[210:213], 0
	v_mfma_f32_16x16x32_bf16 v[0:3], v[178:181], v[210:213], 0
	v_mfma_f32_16x16x32_bf16 v[56:59], v[174:177], v[190:193], v[56:59]
	v_mfma_f32_16x16x32_bf16 v[48:51], v[182:185], v[190:193], v[48:51]
	v_mfma_f32_16x16x32_bf16 v[40:43], v[174:177], v[198:201], v[40:43]
	v_mfma_f32_16x16x32_bf16 v[32:35], v[182:185], v[198:201], v[32:35]
	v_mfma_f32_16x16x32_bf16 v[24:27], v[174:177], v[206:209], v[24:27]
	v_mfma_f32_16x16x32_bf16 v[16:19], v[182:185], v[206:209], v[16:19]
	v_mfma_f32_16x16x32_bf16 v[8:11], v[174:177], v[214:217], v[8:11]
	v_mfma_f32_16x16x32_bf16 v[0:3], v[182:185], v[214:217], v[0:3]
	s_setprio 0
	s_barrier
	s_add_i32 s33, 0, 0x18000
	v_add_u32_e32 v153, s33, v145
	s_add_i32 s34, 0, 0x1c000
	ds_read_b128 v[154:157], v153
	ds_read_b128 v[158:161], v153 offset:1024
	ds_read_b128 v[162:165], v153 offset:2048
	ds_read_b128 v[166:169], v153 offset:3072
	v_add_u32_e32 v153, s34, v145
	ds_read_b128 v[170:173], v153
	ds_read_b128 v[174:177], v153 offset:1024
	ds_read_b128 v[178:181], v153 offset:2048
	ds_read_b128 v[182:185], v153 offset:3072
	s_add_u32 s44, s44, 0x40000
	s_addc_u32 s45, s45, 0
	s_mov_b32 m0, s56
	ds_read_b128 v[186:189], v149 offset:32768
	ds_read_b128 v[190:193], v149 offset:33792
	ds_read_b128 v[194:197], v149 offset:34816
	ds_read_b128 v[198:201], v149 offset:35840
	ds_read_b128 v[202:205], v149 offset:36864
	ds_read_b128 v[206:209], v149 offset:37888
	ds_read_b128 v[210:213], v149 offset:38912
	ds_read_b128 v[214:217], v149 offset:39936
	global_load_lds_dwordx4 v128, s[44:45]
	s_mov_b32 m0, s57
	s_nop 0
	global_load_lds_dwordx4 v132, s[44:45]
	s_waitcnt vmcnt(8)
	s_waitcnt lgkmcnt(0)
	s_barrier
	s_setprio 1
	s_waitcnt lgkmcnt(0)
	v_mfma_f32_16x16x32_bf16 v[124:127], v[154:157], v[186:189], v[124:127]
	v_mfma_f32_16x16x32_bf16 v[116:119], v[162:165], v[186:189], v[116:119]
	v_mfma_f32_16x16x32_bf16 v[108:111], v[154:157], v[194:197], v[108:111]
	v_mfma_f32_16x16x32_bf16 v[100:103], v[162:165], v[194:197], v[100:103]
	v_mfma_f32_16x16x32_bf16 v[92:95], v[154:157], v[202:205], v[92:95]
	v_mfma_f32_16x16x32_bf16 v[84:87], v[162:165], v[202:205], v[84:87]
	v_mfma_f32_16x16x32_bf16 v[76:79], v[154:157], v[210:213], v[76:79]
	v_mfma_f32_16x16x32_bf16 v[68:71], v[162:165], v[210:213], v[68:71]
	v_mfma_f32_16x16x32_bf16 v[124:127], v[158:161], v[190:193], v[124:127]
	v_mfma_f32_16x16x32_bf16 v[116:119], v[166:169], v[190:193], v[116:119]
	v_mfma_f32_16x16x32_bf16 v[108:111], v[158:161], v[198:201], v[108:111]
	v_mfma_f32_16x16x32_bf16 v[100:103], v[166:169], v[198:201], v[100:103]
	v_mfma_f32_16x16x32_bf16 v[92:95], v[158:161], v[206:209], v[92:95]
	v_mfma_f32_16x16x32_bf16 v[84:87], v[166:169], v[206:209], v[84:87]
	v_mfma_f32_16x16x32_bf16 v[76:79], v[158:161], v[214:217], v[76:79]
	v_mfma_f32_16x16x32_bf16 v[68:71], v[166:169], v[214:217], v[68:71]
	s_setprio 0
	s_setprio 1
	v_mfma_f32_16x16x32_bf16 v[120:123], v[170:173], v[186:189], v[120:123]
	v_mfma_f32_16x16x32_bf16 v[112:115], v[178:181], v[186:189], v[112:115]
	v_mfma_f32_16x16x32_bf16 v[104:107], v[170:173], v[194:197], v[104:107]
	v_mfma_f32_16x16x32_bf16 v[96:99], v[178:181], v[194:197], v[96:99]
	v_mfma_f32_16x16x32_bf16 v[88:91], v[170:173], v[202:205], v[88:91]
	v_mfma_f32_16x16x32_bf16 v[80:83], v[178:181], v[202:205], v[80:83]
	v_mfma_f32_16x16x32_bf16 v[72:75], v[170:173], v[210:213], v[72:75]
	v_mfma_f32_16x16x32_bf16 v[64:67], v[178:181], v[210:213], v[64:67]
	v_mfma_f32_16x16x32_bf16 v[120:123], v[174:177], v[190:193], v[120:123]
	v_mfma_f32_16x16x32_bf16 v[112:115], v[182:185], v[190:193], v[112:115]
	v_mfma_f32_16x16x32_bf16 v[104:107], v[174:177], v[198:201], v[104:107]
	v_mfma_f32_16x16x32_bf16 v[96:99], v[182:185], v[198:201], v[96:99]
	v_mfma_f32_16x16x32_bf16 v[88:91], v[174:177], v[206:209], v[88:91]
	v_mfma_f32_16x16x32_bf16 v[80:83], v[182:185], v[206:209], v[80:83]
	v_mfma_f32_16x16x32_bf16 v[72:75], v[174:177], v[214:217], v[72:75]
	v_mfma_f32_16x16x32_bf16 v[64:67], v[182:185], v[214:217], v[64:67]
	s_setprio 0
	s_barrier
; #define PG8_STAGE(bufoff, gbase, voff) do { _Pragma("unroll") for (int _i = 0; _i < 2; ++_i) \
;         __builtin_amdgcn_global_load_lds((const unsigned*)((const char*)(gbase) + (voff)[_i]), (PG8_LAS unsigned*)(lds + (bufoff) + ldsw + _i * 8192), 16, 0, 0); } while (0)
; #define PG8_LDA(dst, b, h) do { _Pragma("unroll") for (int m = 0; m < 4; ++m) _Pragma("unroll") for (int k = 0; k < 2; ++k) dst[m][k] = *(const PG8_LAS bf16x8*)(lds + PG8_SA(b, h) + aoff + m * 2048 + k * 1024); } while (0)
; #define PG8_MMA(ai, bj, At, Bt) do { __builtin_amdgcn_s_setprio(1); _Pragma("unroll") for (int m = 0; m < 4; ++m) _Pragma("unroll") for (int n = 0; n < 2; ++n) _Pragma("unroll") for (int k = 0; k < 2; ++k) \
;         acc[ai][bj][m][n] = __builtin_amdgcn_mfma_f32_16x16x32_bf16(Bt[n][k], At[m][k], acc[ai][bj][m][n], 0, 0, 0); __builtin_amdgcn_s_setprio(0); } while (0)
; #define PG8_WAIT_V(n) asm volatile("s_waitcnt vmcnt(" #n ")" ::: "memory")
; #define PG8_WAIT_L(n) asm volatile("s_waitcnt lgkmcnt(" #n ")" ::: "memory")
; #define PG8_BAR __builtin_amdgcn_s_barrier()
; #define PG8_SCHED __builtin_amdgcn_sched_barrier(0)
; template <class Epi, class Sched, bool ALIGN_EPI = false, bool SP2 = false>
; __device__ __forceinline__ void gemm_phase(PG8_LAS unsigned char* lds, const Gemm g, const Sched& S, const Epi& E) {
;     ...
;             PG8_LDA(At, 1, 1); PG8_STAGE(PG8_SB(1, 0), b3, voffB); PG8_STAGE(PG8_SB(1, 1), b3 + hstep, voffB); PG8_STAGE(PG8_SA(1, 0), a3, voffA);
;             PG8_WAIT_V(8); PG8_WAIT_L(0); PG8_BAR; PG8_MMA(1, 0, At, B0); PG8_MMA(1, 1, At, B1); PG8_BAR; PG8_SCHED;
	s_add_i32 s33, s33, s52
	s_mov_b32 m0, s33
	ds_read_b128 v[186:189], v149 offset:49152
	ds_read_b128 v[190:193], v149 offset:50176
	ds_read_b128 v[194:197], v149 offset:51200
	ds_read_b128 v[198:201], v149 offset:52224
	ds_read_b128 v[202:205], v149 offset:53248
	ds_read_b128 v[206:209], v149 offset:54272
	ds_read_b128 v[210:213], v149 offset:55296
	ds_read_b128 v[214:217], v149 offset:56320
	global_load_lds_dwordx4 v130, s[82:83]
	s_add_i32 m0, s33, 0x2000
	s_add_u32 s42, s42, 0x40080
	s_addc_u32 s43, s43, 0
	s_add_i32 s33, s34, s52
	global_load_lds_dwordx4 v134, s[82:83]
	s_mov_b32 m0, s33
	s_nop 0
	global_load_lds_dwordx4 v130, s[42:43]
	s_add_i32 m0, s33, 0x2000
	s_nop 0
	global_load_lds_dwordx4 v134, s[42:43]
	s_mov_b32 m0, s60
	s_nop 0
	global_load_lds_dwordx4 v128, s[84:85]
	s_mov_b32 m0, s61
	s_nop 0
	global_load_lds_dwordx4 v132, s[84:85]
	s_waitcnt vmcnt(8)
	s_waitcnt lgkmcnt(0)
	s_barrier
	s_setprio 1
	s_waitcnt lgkmcnt(0)
	v_mfma_f32_16x16x32_bf16 v[60:63], v[154:157], v[186:189], v[60:63]
	v_mfma_f32_16x16x32_bf16 v[52:55], v[162:165], v[186:189], v[52:55]
	v_mfma_f32_16x16x32_bf16 v[44:47], v[154:157], v[194:197], v[44:47]
	v_mfma_f32_16x16x32_bf16 v[36:39], v[162:165], v[194:197], v[36:39]
	v_mfma_f32_16x16x32_bf16 v[28:31], v[154:157], v[202:205], v[28:31]
	v_mfma_f32_16x16x32_bf16 v[20:23], v[162:165], v[202:205], v[20:23]
	v_mfma_f32_16x16x32_bf16 v[12:15], v[154:157], v[210:213], v[12:15]
	v_mfma_f32_16x16x32_bf16 v[4:7], v[162:165], v[210:213], v[4:7]
	v_mfma_f32_16x16x32_bf16 v[60:63], v[158:161], v[190:193], v[60:63]
	v_mfma_f32_16x16x32_bf16 v[52:55], v[166:169], v[190:193], v[52:55]
	v_mfma_f32_16x16x32_bf16 v[44:47], v[158:161], v[198:201], v[44:47]
	v_mfma_f32_16x16x32_bf16 v[36:39], v[166:169], v[198:201], v[36:39]
	v_mfma_f32_16x16x32_bf16 v[28:31], v[158:161], v[206:209], v[28:31]
	v_mfma_f32_16x16x32_bf16 v[20:23], v[166:169], v[206:209], v[20:23]
	v_mfma_f32_16x16x32_bf16 v[12:15], v[158:161], v[214:217], v[12:15]
	v_mfma_f32_16x16x32_bf16 v[4:7], v[166:169], v[214:217], v[4:7]
	s_setprio 0
	s_setprio 1
	v_mfma_f32_16x16x32_bf16 v[56:59], v[170:173], v[186:189], v[56:59]
	v_mfma_f32_16x16x32_bf16 v[48:51], v[178:181], v[186:189], v[48:51]
	v_mfma_f32_16x16x32_bf16 v[40:43], v[170:173], v[194:197], v[40:43]
	v_mfma_f32_16x16x32_bf16 v[32:35], v[178:181], v[194:197], v[32:35]
	v_mfma_f32_16x16x32_bf16 v[24:27], v[170:173], v[202:205], v[24:27]
	v_mfma_f32_16x16x32_bf16 v[16:19], v[178:181], v[202:205], v[16:19]
	v_mfma_f32_16x16x32_bf16 v[8:11], v[170:173], v[210:213], v[8:11]
	v_mfma_f32_16x16x32_bf16 v[0:3], v[178:181], v[210:213], v[0:3]
	v_mfma_f32_16x16x32_bf16 v[56:59], v[174:177], v[190:193], v[56:59]
	v_mfma_f32_16x16x32_bf16 v[48:51], v[182:185], v[190:193], v[48:51]
	v_mfma_f32_16x16x32_bf16 v[40:43], v[174:177], v[198:201], v[40:43]
	v_mfma_f32_16x16x32_bf16 v[32:35], v[182:185], v[198:201], v[32:35]
	v_mfma_f32_16x16x32_bf16 v[24:27], v[174:177], v[206:209], v[24:27]
	v_mfma_f32_16x16x32_bf16 v[16:19], v[182:185], v[206:209], v[16:19]
	v_mfma_f32_16x16x32_bf16 v[8:11], v[174:177], v[214:217], v[8:11]
	v_mfma_f32_16x16x32_bf16 v[0:3], v[182:185], v[214:217], v[0:3]
	s_setprio 0
	s_barrier
	s_add_i32 s76, s76, 2
	s_add_u32 s40, s40, 0x100
	s_addc_u32 s41, s41, 0
	s_add_u32 s74, s74, 0x100
	s_addc_u32 s75, s75, 0
	s_cmp_gt_u32 s76, 13

; #define PG8_STAGE(bufoff, gbase, voff) do { _Pragma("unroll") for (int _i = 0; _i < 2; ++_i) \
;         __builtin_amdgcn_global_load_lds((const unsigned*)((const char*)(gbase) + (voff)[_i]), (PG8_LAS unsigned*)(lds + (bufoff) + ldsw + _i * 8192), 16, 0, 0); } while (0)
; #define PG8_LDA(dst, b, h) do { _Pragma("unroll") for (int m = 0; m < 4; ++m) _Pragma("unroll") for (int k = 0; k < 2; ++k) dst[m][k] = *(const PG8_LAS bf16x8*)(lds + PG8_SA(b, h) + aoff + m * 2048 + k * 1024); } while (0)
; #define PG8_LDB(dst, b, h) do { _Pragma("unroll") for (int n = 0; n < 2; ++n) _Pragma("unroll") for (int k = 0; k < 2; ++k) dst[n][k] = *(const PG8_LAS bf16x8*)(lds + PG8_SB(b, h) + boff + n * 2048 + k * 1024); } while (0)
; #define PG8_WAIT_V(n) asm volatile("s_waitcnt vmcnt(" #n ")" ::: "memory")
; #define PG8_WAIT_L(n) asm volatile("s_waitcnt lgkmcnt(" #n ")" ::: "memory")
; #define PG8_BAR __builtin_amdgcn_s_barrier()
; #define PG8_SCHED __builtin_amdgcn_sched_barrier(0)
; template <class Epi, class Sched, bool ALIGN_EPI = false, bool SP2 = false>
; __device__ __forceinline__ void gemm_phase(PG8_LAS unsigned char* lds, const Gemm g, const Sched& S, const Epi& E) {
;     ...
;         const bool has_next = S.next(ui + 1, nxt);
;         const char* nA = has_next ? (const char*)g.A + (size_t)nxt.pm * tstep : cA; const char* nB = has_next ? (const char*)g.Bt + (size_t)nxt.pn * tstep : cB;
;         for (int t = 0; t < nt; t += 2) {
;             const bool last = (t == nt - 2);
;             const char* a1 = cA + (size_t)(t + 1) * kstep;
;             const char* a2 = last ? nA : cA + (size_t)(t + 2) * kstep; const char* b2 = last ? nB : cB + (size_t)(t + 2) * kstep;
;             const char* a3 = a2 + kstep; const char* b3 = b2 + kstep;
;             if (last && has_next) S.a_ready(nxt);
;             if constexpr (SP2) {
;             PG8_LDB(B0, 0, 0); PG8_LDB(B1, 0, 1); PG8_SCHED; PG8_LDA(At, 0, 0); PG8_STAGE(PG8_SA(1, 1), a1 + hstep, voffA);
;             PG8_WAIT_V(8); PG8_WAIT_L(0); PG8_BAR; PG8_MMA(0, 0, At, B0); PG8_MMA(0, 1, At, B1); PG8_BAR; PG8_SCHED;
;             PG8_LDA(At, 0, 1); PG8_STAGE(PG8_SB(0, 0), b2, voffB); PG8_STAGE(PG8_SB(0, 1), b2 + hstep, voffB); PG8_STAGE(PG8_SA(0, 0), a2, voffA);
;             PG8_WAIT_V(8); PG8_WAIT_L(0); PG8_BAR; PG8_MMA(1, 0, At, B0); PG8_MMA(1, 1, At, B1); PG8_BAR; PG8_SCHED;
.LBB0_788:
	s_add_u32 s42, s42, 0xb0080
	s_addc_u32 s43, s43, 0
	s_add_u32 s86, s44, 0x100
	s_addc_u32 s87, s45, 0
	s_mov_b32 s90, -2
	s_waitcnt lgkmcnt(0)
	s_waitcnt vmcnt(0)
	ds_read_b128 v[128:131], v203
	ds_read_b128 v[132:135], v203 offset:1024
	ds_read_b128 v[136:139], v203 offset:2048
	ds_read_b128 v[140:143], v203 offset:3072
	ds_read_b128 v[144:147], v204
	ds_read_b128 v[148:151], v204 offset:1024
	ds_read_b128 v[170:173], v204 offset:2048
	ds_read_b128 v[174:177], v204 offset:3072
	s_add_u32 s33, s42, 0xfff50080
	s_addc_u32 s34, s43, -1
	s_cmp_eq_u32 s90, 40
	s_cselect_b32 s47, s5, s34
	s_cselect_b32 s46, s4, s33
	s_cselect_b32 s45, s41, s87
	s_cselect_b32 s44, s40, s86
	s_add_i32 m0, s58, 0xc000
	ds_read_b128 v[178:181], v205
	ds_read_b128 v[182:185], v205 offset:1024
	ds_read_b128 v[186:189], v205 offset:2048
	ds_read_b128 v[190:193], v205 offset:3072
	ds_read_b128 v[194:197], v205 offset:4096
	ds_read_b128 v[206:209], v205 offset:5120
	ds_read_b128 v[210:213], v205 offset:6144
	ds_read_b128 v[214:217], v205 offset:7168
	global_load_lds_dwordx4 v162, s[42:43]
	s_add_i32 m0, s58, 0xe000
	s_nop 0
	global_load_lds_dwordx4 v164, s[42:43]
	s_waitcnt vmcnt(8)
	s_waitcnt lgkmcnt(0)
	s_barrier
	s_setprio 1
	s_waitcnt lgkmcnt(0)
	v_mfma_f32_16x16x32_bf16 v[124:127], v[128:131], v[178:181], 0
	v_mfma_f32_16x16x32_bf16 v[120:123], v[136:139], v[178:181], 0
	v_mfma_f32_16x16x32_bf16 v[116:119], v[128:131], v[186:189], 0
	v_mfma_f32_16x16x32_bf16 v[112:115], v[136:139], v[186:189], 0
	v_mfma_f32_16x16x32_bf16 v[108:111], v[128:131], v[194:197], 0
	v_mfma_f32_16x16x32_bf16 v[104:107], v[136:139], v[194:197], 0
	v_mfma_f32_16x16x32_bf16 v[100:103], v[128:131], v[210:213], 0
	v_mfma_f32_16x16x32_bf16 v[96:99], v[136:139], v[210:213], 0
	v_mfma_f32_16x16x32_bf16 v[124:127], v[132:135], v[182:185], v[124:127]
	v_mfma_f32_16x16x32_bf16 v[120:123], v[140:143], v[182:185], v[120:123]
	v_mfma_f32_16x16x32_bf16 v[116:119], v[132:135], v[190:193], v[116:119]
	v_mfma_f32_16x16x32_bf16 v[112:115], v[140:143], v[190:193], v[112:115]
	v_mfma_f32_16x16x32_bf16 v[108:111], v[132:135], v[206:209], v[108:111]
	v_mfma_f32_16x16x32_bf16 v[104:107], v[140:143], v[206:209], v[104:107]
	v_mfma_f32_16x16x32_bf16 v[100:103], v[132:135], v[214:217], v[100:103]
	v_mfma_f32_16x16x32_bf16 v[96:99], v[140:143], v[214:217], v[96:99]
	s_setprio 0
	s_setprio 1
	v_mfma_f32_16x16x32_bf16 v[68:71], v[144:147], v[178:181], 0
	v_mfma_f32_16x16x32_bf16 v[64:67], v[170:173], v[178:181], 0
	v_mfma_f32_16x16x32_bf16 v[60:63], v[144:147], v[186:189], 0
	v_mfma_f32_16x16x32_bf16 v[52:55], v[170:173], v[186:189], 0
	v_mfma_f32_16x16x32_bf16 v[44:47], v[144:147], v[194:197], 0
	v_mfma_f32_16x16x32_bf16 v[40:43], v[170:173], v[194:197], 0
	v_mfma_f32_16x16x32_bf16 v[36:39], v[144:147], v[210:213], 0
	v_mfma_f32_16x16x32_bf16 v[32:35], v[170:173], v[210:213], 0
	v_mfma_f32_16x16x32_bf16 v[68:71], v[148:151], v[182:185], v[68:71]
	v_mfma_f32_16x16x32_bf16 v[64:67], v[174:177], v[182:185], v[64:67]
	v_mfma_f32_16x16x32_bf16 v[60:63], v[148:151], v[190:193], v[60:63]
	v_mfma_f32_16x16x32_bf16 v[52:55], v[174:177], v[190:193], v[52:55]
	v_mfma_f32_16x16x32_bf16 v[44:47], v[148:151], v[206:209], v[44:47]
	v_mfma_f32_16x16x32_bf16 v[40:43], v[174:177], v[206:209], v[40:43]
	v_mfma_f32_16x16x32_bf16 v[36:39], v[148:151], v[214:217], v[36:39]
	v_mfma_f32_16x16x32_bf16 v[32:35], v[174:177], v[214:217], v[32:35]
	s_setprio 0
	s_barrier
	s_add_i32 s33, s74, s56
	s_add_u32 s64, s44, s12
	s_addc_u32 s65, s45, s13
	s_mov_b32 m0, s33
	ds_read_b128 v[178:181], v205 offset:16384
	ds_read_b128 v[182:185], v205 offset:17408
	ds_read_b128 v[186:189], v205 offset:18432
	ds_read_b128 v[190:193], v205 offset:19456
	ds_read_b128 v[194:197], v205 offset:20480
	ds_read_b128 v[206:209], v205 offset:21504
	ds_read_b128 v[210:213], v205 offset:22528
	ds_read_b128 v[214:217], v205 offset:23552
	global_load_lds_dwordx4 v156, s[44:45]
	s_add_i32 m0, s33, 0x2000
	s_add_u32 s92, s44, 0xb0000
	s_addc_u32 s93, s45, 0
	s_add_i32 s33, s75, s56
	global_load_lds_dwordx4 v160, s[44:45]
	s_mov_b32 m0, s33
	s_add_u32 s84, s46, s12
	s_addc_u32 s85, s47, s13
	global_load_lds_dwordx4 v156, s[92:93]
	s_add_i32 m0, s33, 0x2000
	s_nop 0
	global_load_lds_dwordx4 v160, s[92:93]
	s_mov_b32 m0, s58
	s_nop 0
	global_load_lds_dwordx4 v154, s[46:47]
	s_mov_b32 m0, s59
	s_nop 0
	global_load_lds_dwordx4 v158, s[46:47]
	s_waitcnt vmcnt(8)
	s_waitcnt lgkmcnt(0)
	s_barrier
	s_setprio 1
	s_waitcnt lgkmcnt(0)
	v_mfma_f32_16x16x32_bf16 v[92:95], v[128:131], v[178:181], 0
	v_mfma_f32_16x16x32_bf16 v[88:91], v[136:139], v[178:181], 0
	v_mfma_f32_16x16x32_bf16 v[84:87], v[128:131], v[186:189], 0
	v_mfma_f32_16x16x32_bf16 v[80:83], v[136:139], v[186:189], 0
	v_mfma_f32_16x16x32_bf16 v[76:79], v[128:131], v[194:197], 0
	v_mfma_f32_16x16x32_bf16 v[72:75], v[136:139], v[194:197], 0
	v_mfma_f32_16x16x32_bf16 v[56:59], v[128:131], v[210:213], 0
	v_mfma_f32_16x16x32_bf16 v[48:51], v[136:139], v[210:213], 0
	v_mfma_f32_16x16x32_bf16 v[92:95], v[132:135], v[182:185], v[92:95]
	v_mfma_f32_16x16x32_bf16 v[88:91], v[140:143], v[182:185], v[88:91]
	v_mfma_f32_16x16x32_bf16 v[84:87], v[132:135], v[190:193], v[84:87]
	v_mfma_f32_16x16x32_bf16 v[80:83], v[140:143], v[190:193], v[80:83]
	v_mfma_f32_16x16x32_bf16 v[76:79], v[132:135], v[206:209], v[76:79]
	v_mfma_f32_16x16x32_bf16 v[72:75], v[140:143], v[206:209], v[72:75]
	v_mfma_f32_16x16x32_bf16 v[56:59], v[132:135], v[214:217], v[56:59]
	v_mfma_f32_16x16x32_bf16 v[48:51], v[140:143], v[214:217], v[48:51]
	s_setprio 0
	s_setprio 1
	v_mfma_f32_16x16x32_bf16 v[28:31], v[144:147], v[178:181], 0
	v_mfma_f32_16x16x32_bf16 v[24:27], v[170:173], v[178:181], 0
	v_mfma_f32_16x16x32_bf16 v[20:23], v[144:147], v[186:189], 0
	v_mfma_f32_16x16x32_bf16 v[16:19], v[170:173], v[186:189], 0
	v_mfma_f32_16x16x32_bf16 v[12:15], v[144:147], v[194:197], 0
	v_mfma_f32_16x16x32_bf16 v[8:11], v[170:173], v[194:197], 0
	v_mfma_f32_16x16x32_bf16 v[4:7], v[144:147], v[210:213], 0
	v_mfma_f32_16x16x32_bf16 v[0:3], v[170:173], v[210:213], 0
	v_mfma_f32_16x16x32_bf16 v[28:31], v[148:151], v[182:185], v[28:31]
	v_mfma_f32_16x16x32_bf16 v[24:27], v[174:177], v[182:185], v[24:27]
	v_mfma_f32_16x16x32_bf16 v[20:23], v[148:151], v[190:193], v[20:23]
	v_mfma_f32_16x16x32_bf16 v[16:19], v[174:177], v[190:193], v[16:19]
	v_mfma_f32_16x16x32_bf16 v[12:15], v[148:151], v[206:209], v[12:15]
	v_mfma_f32_16x16x32_bf16 v[8:11], v[174:177], v[206:209], v[8:11]
	v_mfma_f32_16x16x32_bf16 v[4:7], v[148:151], v[214:217], v[4:7]
	v_mfma_f32_16x16x32_bf16 v[0:3], v[174:177], v[214:217], v[0:3]
	s_setprio 0
	s_barrier
; #define PG8_STAGE(bufoff, gbase, voff) do { _Pragma("unroll") for (int _i = 0; _i < 2; ++_i) \
;         __builtin_amdgcn_global_load_lds((const unsigned*)((const char*)(gbase) + (voff)[_i]), (PG8_LAS unsigned*)(lds + (bufoff) + ldsw + _i * 8192), 16, 0, 0); } while (0)
; #define PG8_LDA(dst, b, h) do { _Pragma("unroll") for (int m = 0; m < 4; ++m) _Pragma("unroll") for (int k = 0; k < 2; ++k) dst[m][k] = *(const PG8_LAS bf16x8*)(lds + PG8_SA(b, h) + aoff + m * 2048 + k * 1024); } while (0)
; #define PG8_LDB(dst, b, h) do { _Pragma("unroll") for (int n = 0; n < 2; ++n) _Pragma("unroll") for (int k = 0; k < 2; ++k) dst[n][k] = *(const PG8_LAS bf16x8*)(lds + PG8_SB(b, h) + boff + n * 2048 + k * 1024); } while (0)
; #define PG8_MMA(ai, bj, At, Bt) do { __builtin_amdgcn_s_setprio(1); _Pragma("unroll") for (int m = 0; m < 4; ++m) _Pragma("unroll") for (int n = 0; n < 2; ++n) _Pragma("unroll") for (int k = 0; k < 2; ++k) \
;         acc[ai][bj][m][n] = __builtin_amdgcn_mfma_f32_16x16x32_bf16(Bt[n][k], At[m][k], acc[ai][bj][m][n], 0, 0, 0); __builtin_amdgcn_s_setprio(0); } while (0)
; #define PG8_WAIT_V(n) asm volatile("s_waitcnt vmcnt(" #n ")" ::: "memory")
; #define PG8_WAIT_L(n) asm volatile("s_waitcnt lgkmcnt(" #n ")" ::: "memory")
; #define PG8_BAR __builtin_amdgcn_s_barrier()
; #define PG8_SCHED __builtin_amdgcn_sched_barrier(0)
; template <class Epi, class Sched, bool ALIGN_EPI = false, bool SP2 = false>
; __device__ __forceinline__ void gemm_phase(PG8_LAS unsigned char* lds, const Gemm g, const Sched& S, const Epi& E) {
;     ...
;             PG8_LDB(B0, 1, 0); PG8_LDB(B1, 1, 1); PG8_SCHED; PG8_LDA(At, 1, 0); PG8_STAGE(PG8_SA(0, 1), a2 + hstep, voffA);
;             PG8_WAIT_V(8); PG8_WAIT_L(0); PG8_BAR; PG8_MMA(0, 0, At, B0); PG8_MMA(0, 1, At, B1); PG8_BAR; PG8_SCHED;
;             PG8_LDA(At, 1, 1); PG8_STAGE(PG8_SB(1, 0), b3, voffB); PG8_STAGE(PG8_SB(1, 1), b3 + hstep, voffB); PG8_STAGE(PG8_SA(1, 0), a3, voffA);
;             PG8_WAIT_V(8); PG8_WAIT_L(0); PG8_BAR; PG8_MMA(1, 0, At, B0); PG8_MMA(1, 1, At, B1); PG8_BAR; PG8_SCHED;
	s_add_i32 s33, 0, 0x18000
	s_add_i32 s34, 0, 0x1c000
	v_add_u32_e32 v140, s33, v201
	v_add_u32_e32 v153, s34, v201
	ds_read_b128 v[128:131], v140
	ds_read_b128 v[132:135], v140 offset:1024
	ds_read_b128 v[136:139], v140 offset:2048
	ds_read_b128 v[140:143], v140 offset:3072
	ds_read_b128 v[144:147], v153
	ds_read_b128 v[148:151], v153 offset:1024
	ds_read_b128 v[170:173], v153 offset:2048
	ds_read_b128 v[174:177], v153 offset:3072
	s_add_u32 s46, s46, 0xb0000
	s_addc_u32 s47, s47, 0
	s_mov_b32 m0, s60
	ds_read_b128 v[178:181], v205 offset:32768
	ds_read_b128 v[182:185], v205 offset:33792
	ds_read_b128 v[186:189], v205 offset:34816
	ds_read_b128 v[190:193], v205 offset:35840
	ds_read_b128 v[194:197], v205 offset:36864
	ds_read_b128 v[206:209], v205 offset:37888
	ds_read_b128 v[210:213], v205 offset:38912
	ds_read_b128 v[214:217], v205 offset:39936
	global_load_lds_dwordx4 v154, s[46:47]
	s_mov_b32 m0, s61
	s_nop 0
	global_load_lds_dwordx4 v158, s[46:47]
	s_waitcnt vmcnt(8)
	s_waitcnt lgkmcnt(0)
	s_barrier
	s_setprio 1
	s_waitcnt lgkmcnt(0)
	v_mfma_f32_16x16x32_bf16 v[124:127], v[128:131], v[178:181], v[124:127]
	v_mfma_f32_16x16x32_bf16 v[120:123], v[136:139], v[178:181], v[120:123]
	v_mfma_f32_16x16x32_bf16 v[116:119], v[128:131], v[186:189], v[116:119]
	v_mfma_f32_16x16x32_bf16 v[112:115], v[136:139], v[186:189], v[112:115]
	v_mfma_f32_16x16x32_bf16 v[108:111], v[128:131], v[194:197], v[108:111]
	v_mfma_f32_16x16x32_bf16 v[104:107], v[136:139], v[194:197], v[104:107]
	v_mfma_f32_16x16x32_bf16 v[100:103], v[128:131], v[210:213], v[100:103]
	v_mfma_f32_16x16x32_bf16 v[96:99], v[136:139], v[210:213], v[96:99]
	v_mfma_f32_16x16x32_bf16 v[124:127], v[132:135], v[182:185], v[124:127]
	v_mfma_f32_16x16x32_bf16 v[120:123], v[140:143], v[182:185], v[120:123]
	v_mfma_f32_16x16x32_bf16 v[116:119], v[132:135], v[190:193], v[116:119]
	v_mfma_f32_16x16x32_bf16 v[112:115], v[140:143], v[190:193], v[112:115]
	v_mfma_f32_16x16x32_bf16 v[108:111], v[132:135], v[206:209], v[108:111]
	v_mfma_f32_16x16x32_bf16 v[104:107], v[140:143], v[206:209], v[104:107]
	v_mfma_f32_16x16x32_bf16 v[100:103], v[132:135], v[214:217], v[100:103]
	v_mfma_f32_16x16x32_bf16 v[96:99], v[140:143], v[214:217], v[96:99]
	s_setprio 0
	s_setprio 1
	v_mfma_f32_16x16x32_bf16 v[68:71], v[144:147], v[178:181], v[68:71]
	v_mfma_f32_16x16x32_bf16 v[64:67], v[170:173], v[178:181], v[64:67]
	v_mfma_f32_16x16x32_bf16 v[60:63], v[144:147], v[186:189], v[60:63]
	v_mfma_f32_16x16x32_bf16 v[52:55], v[170:173], v[186:189], v[52:55]
	v_mfma_f32_16x16x32_bf16 v[44:47], v[144:147], v[194:197], v[44:47]
	v_mfma_f32_16x16x32_bf16 v[40:43], v[170:173], v[194:197], v[40:43]
	v_mfma_f32_16x16x32_bf16 v[36:39], v[144:147], v[210:213], v[36:39]
	v_mfma_f32_16x16x32_bf16 v[32:35], v[170:173], v[210:213], v[32:35]
	v_mfma_f32_16x16x32_bf16 v[68:71], v[148:151], v[182:185], v[68:71]
	v_mfma_f32_16x16x32_bf16 v[64:67], v[174:177], v[182:185], v[64:67]
	v_mfma_f32_16x16x32_bf16 v[60:63], v[148:151], v[190:193], v[60:63]
	v_mfma_f32_16x16x32_bf16 v[52:55], v[174:177], v[190:193], v[52:55]
	v_mfma_f32_16x16x32_bf16 v[44:47], v[148:151], v[206:209], v[44:47]
	v_mfma_f32_16x16x32_bf16 v[40:43], v[174:177], v[206:209], v[40:43]
	v_mfma_f32_16x16x32_bf16 v[36:39], v[148:151], v[214:217], v[36:39]
	v_mfma_f32_16x16x32_bf16 v[32:35], v[174:177], v[214:217], v[32:35]
	s_setprio 0
	s_barrier
	s_add_i32 s33, s33, s56
	s_mov_b32 m0, s33
	ds_read_b128 v[178:181], v205 offset:49152
	ds_read_b128 v[182:185], v205 offset:50176
	ds_read_b128 v[186:189], v205 offset:51200
	ds_read_b128 v[190:193], v205 offset:52224
	ds_read_b128 v[194:197], v205 offset:53248
	ds_read_b128 v[206:209], v205 offset:54272
	ds_read_b128 v[210:213], v205 offset:55296
	ds_read_b128 v[214:217], v205 offset:56320
	global_load_lds_dwordx4 v156, s[64:65]
	s_add_i32 m0, s33, 0x2000
	s_add_u32 s44, s44, 0xb0080
	s_addc_u32 s45, s45, 0
	s_add_i32 s33, s34, s56
	global_load_lds_dwordx4 v160, s[64:65]
	s_mov_b32 m0, s33
	s_nop 0
	global_load_lds_dwordx4 v156, s[44:45]
	s_add_i32 m0, s33, 0x2000
	s_nop 0
	global_load_lds_dwordx4 v160, s[44:45]
	s_mov_b32 m0, s72
	s_nop 0
	global_load_lds_dwordx4 v154, s[84:85]
	s_mov_b32 m0, s73
	s_nop 0
	global_load_lds_dwordx4 v158, s[84:85]
	s_waitcnt vmcnt(8)
	s_waitcnt lgkmcnt(0)
	s_barrier
	s_setprio 1
	s_waitcnt lgkmcnt(0)
	v_mfma_f32_16x16x32_bf16 v[92:95], v[128:131], v[178:181], v[92:95]
	v_mfma_f32_16x16x32_bf16 v[88:91], v[136:139], v[178:181], v[88:91]
	v_mfma_f32_16x16x32_bf16 v[84:87], v[128:131], v[186:189], v[84:87]
	v_mfma_f32_16x16x32_bf16 v[80:83], v[136:139], v[186:189], v[80:83]
	v_mfma_f32_16x16x32_bf16 v[76:79], v[128:131], v[194:197], v[76:79]
	v_mfma_f32_16x16x32_bf16 v[72:75], v[136:139], v[194:197], v[72:75]
	v_mfma_f32_16x16x32_bf16 v[56:59], v[128:131], v[210:213], v[56:59]
	v_mfma_f32_16x16x32_bf16 v[48:51], v[136:139], v[210:213], v[48:51]
	v_mfma_f32_16x16x32_bf16 v[92:95], v[132:135], v[182:185], v[92:95]
	v_mfma_f32_16x16x32_bf16 v[88:91], v[140:143], v[182:185], v[88:91]
	v_mfma_f32_16x16x32_bf16 v[84:87], v[132:135], v[190:193], v[84:87]
	v_mfma_f32_16x16x32_bf16 v[80:83], v[140:143], v[190:193], v[80:83]
	v_mfma_f32_16x16x32_bf16 v[76:79], v[132:135], v[206:209], v[76:79]
	v_mfma_f32_16x16x32_bf16 v[72:75], v[140:143], v[206:209], v[72:75]
	v_mfma_f32_16x16x32_bf16 v[56:59], v[132:135], v[214:217], v[56:59]
	v_mfma_f32_16x16x32_bf16 v[48:51], v[140:143], v[214:217], v[48:51]
	s_setprio 0
	s_setprio 1
	v_mfma_f32_16x16x32_bf16 v[28:31], v[144:147], v[178:181], v[28:31]
	v_mfma_f32_16x16x32_bf16 v[24:27], v[170:173], v[178:181], v[24:27]
	v_mfma_f32_16x16x32_bf16 v[20:23], v[144:147], v[186:189], v[20:23]
	v_mfma_f32_16x16x32_bf16 v[16:19], v[170:173], v[186:189], v[16:19]
	v_mfma_f32_16x16x32_bf16 v[12:15], v[144:147], v[194:197], v[12:15]
	v_mfma_f32_16x16x32_bf16 v[8:11], v[170:173], v[194:197], v[8:11]
	v_mfma_f32_16x16x32_bf16 v[4:7], v[144:147], v[210:213], v[4:7]
	v_mfma_f32_16x16x32_bf16 v[0:3], v[170:173], v[210:213], v[0:3]
	v_mfma_f32_16x16x32_bf16 v[28:31], v[148:151], v[182:185], v[28:31]
	v_mfma_f32_16x16x32_bf16 v[24:27], v[174:177], v[182:185], v[24:27]
	v_mfma_f32_16x16x32_bf16 v[20:23], v[148:151], v[190:193], v[20:23]
	v_mfma_f32_16x16x32_bf16 v[16:19], v[174:177], v[190:193], v[16:19]
	v_mfma_f32_16x16x32_bf16 v[12:15], v[148:151], v[206:209], v[12:15]
	v_mfma_f32_16x16x32_bf16 v[8:11], v[174:177], v[206:209], v[8:11]
	v_mfma_f32_16x16x32_bf16 v[4:7], v[148:151], v[214:217], v[4:7]
	v_mfma_f32_16x16x32_bf16 v[0:3], v[174:177], v[214:217], v[0:3]
	s_setprio 0
	s_barrier
	s_add_i32 s90, s90, 2
	s_add_u32 s42, s42, 0x100
	s_addc_u32 s43, s43, 0
	s_add_u32 s86, s86, 0x100
	s_addc_u32 s87, s87, 0
	s_cmp_gt_u32 s90, 41

; #define PG8_STAGE(bufoff, gbase, voff) do { _Pragma("unroll") for (int _i = 0; _i < 2; ++_i) \
;         __builtin_amdgcn_global_load_lds((const unsigned*)((const char*)(gbase) + (voff)[_i]), (PG8_LAS unsigned*)(lds + (bufoff) + ldsw + _i * 8192), 16, 0, 0); } while (0)
; #define PG8_LDA(dst, b, h) do { _Pragma("unroll") for (int m = 0; m < 4; ++m) _Pragma("unroll") for (int k = 0; k < 2; ++k) dst[m][k] = *(const PG8_LAS bf16x8*)(lds + PG8_SA(b, h) + aoff + m * 2048 + k * 1024); } while (0)
; #define PG8_LDB(dst, b, h) do { _Pragma("unroll") for (int n = 0; n < 2; ++n) _Pragma("unroll") for (int k = 0; k < 2; ++k) dst[n][k] = *(const PG8_LAS bf16x8*)(lds + PG8_SB(b, h) + boff + n * 2048 + k * 1024); } while (0)
; #define PG8_MMA(ai, bj, At, Bt) do { __builtin_amdgcn_s_setprio(1); _Pragma("unroll") for (int m = 0; m < 4; ++m) _Pragma("unroll") for (int n = 0; n < 2; ++n) _Pragma("unroll") for (int k = 0; k < 2; ++k) \
;         acc[ai][bj][m][n] = __builtin_amdgcn_mfma_f32_16x16x32_bf16(Bt[n][k], At[m][k], acc[ai][bj][m][n], 0, 0, 0); __builtin_amdgcn_s_setprio(0); } while (0)
; #define PG8_WAIT_V(n) asm volatile("s_waitcnt vmcnt(" #n ")" ::: "memory")
; #define PG8_BAR __builtin_amdgcn_s_barrier()
; template <class Epi, class Sched, bool ALIGN_EPI = false, bool SP2 = false>
; __device__ __forceinline__ void gemm_phase(PG8_LAS unsigned char* lds, const Gemm g, const Sched& S, const Epi& E) {
;     ...
;         const char* nA = has_next ? (const char*)g.A + (size_t)nxt.pm * tstep : cA; const char* nB = has_next ? (const char*)g.Bt + (size_t)nxt.pn * tstep : cB;
;         for (int t = 0; t < nt; t += 2) {
;             const bool last = (t == nt - 2);
;             const char* a1 = cA + (size_t)(t + 1) * kstep;
;             const char* a2 = last ? nA : cA + (size_t)(t + 2) * kstep; const char* b2 = last ? nB : cB + (size_t)(t + 2) * kstep;
;     ...
;             PG8_LDB(B0, 0, 0); PG8_LDB(B1, 0, 1); PG8_SCHED; PG8_LDA(At, 0, 0); PG8_STAGE(PG8_SA(1, 1), a1 + hstep, voffA);
;             PG8_WAIT_V(8); PG8_WAIT_L(0); PG8_BAR; PG8_MMA(0, 0, At, B0); PG8_MMA(0, 1, At, B1); PG8_BAR; PG8_SCHED;
;             PG8_LDA(At, 0, 1); PG8_STAGE(PG8_SB(0, 0), b2, voffB); PG8_STAGE(PG8_SB(0, 1), b2 + hstep, voffB); PG8_STAGE(PG8_SA(0, 0), a2, voffA);
;             PG8_WAIT_V(8); PG8_WAIT_L(0); PG8_BAR; PG8_MMA(1, 0, At, B0); PG8_MMA(1, 1, At, B1); PG8_BAR; PG8_SCHED;
.LBB0_914:
	s_ashr_i32 s45, s44, 31
	s_lshl_b64 s[46:47], s[44:45], 19
	s_add_u32 s46, s60, s46
	s_addc_u32 s47, s61, s47
	s_and_b64 s[48:49], s[0:1], exec
	s_cselect_b32 s5, s47, s55
	s_cselect_b32 s45, s46, s54
	s_ashr_i32 s43, s42, 31
	s_lshl_b64 s[48:49], s[42:43], 19
	s_add_u32 s48, s16, s48
	s_addc_u32 s49, s17, s49
	s_and_b64 s[58:59], s[0:1], exec
	s_cselect_b32 s43, s49, s57
	s_cselect_b32 s86, s48, s56
	s_add_u32 s54, s54, 0x40080
	s_addc_u32 s55, s55, 0
	s_add_u32 s87, s56, 0x100
	s_addc_u32 s90, s57, 0
	s_mov_b32 s91, -2
	s_waitcnt lgkmcnt(0)
	ds_read_b128 v[144:147], v159
	ds_read_b128 v[148:151], v159 offset:1024
	ds_read_b128 v[162:165], v159 offset:2048
	ds_read_b128 v[166:169], v159 offset:3072
	ds_read_b128 v[170:173], v160
	ds_read_b128 v[174:177], v160 offset:1024
	ds_read_b128 v[178:181], v160 offset:2048
	ds_read_b128 v[182:185], v160 offset:3072
	s_add_u32 s33, s54, 0xfffc0080
	s_addc_u32 s34, s55, -1
	s_cmp_eq_u32 s91, 12
	s_cselect_b32 s59, s5, s34
	s_cselect_b32 s58, s45, s33
	s_cselect_b32 s57, s43, s90
	s_cselect_b32 s56, s86, s87
	s_add_i32 m0, s53, 0xc000
	ds_read_b128 v[186:189], v161
	ds_read_b128 v[190:193], v161 offset:1024
	ds_read_b128 v[194:197], v161 offset:2048
	ds_read_b128 v[198:201], v161 offset:3072
	ds_read_b128 v[202:205], v161 offset:4096
	ds_read_b128 v[206:209], v161 offset:5120
	ds_read_b128 v[210:213], v161 offset:6144
	ds_read_b128 v[214:217], v161 offset:7168
	global_load_lds_dwordx4 v136, s[54:55]
	s_add_i32 m0, s53, 0xe000
	s_nop 0
	global_load_lds_dwordx4 v138, s[54:55]
	s_waitcnt vmcnt(8)
	s_waitcnt lgkmcnt(0)
	s_barrier
	s_setprio 1
	s_waitcnt lgkmcnt(0)
	v_mfma_f32_16x16x32_bf16 v[124:127], v[144:147], v[186:189], 0
	v_mfma_f32_16x16x32_bf16 v[120:123], v[162:165], v[186:189], 0
	v_mfma_f32_16x16x32_bf16 v[108:111], v[144:147], v[194:197], 0
	v_mfma_f32_16x16x32_bf16 v[104:107], v[162:165], v[194:197], 0
	v_mfma_f32_16x16x32_bf16 v[92:95], v[144:147], v[202:205], 0
	v_mfma_f32_16x16x32_bf16 v[88:91], v[162:165], v[202:205], 0
	v_mfma_f32_16x16x32_bf16 v[76:79], v[144:147], v[210:213], 0
	v_mfma_f32_16x16x32_bf16 v[72:75], v[162:165], v[210:213], 0
	v_mfma_f32_16x16x32_bf16 v[124:127], v[148:151], v[190:193], v[124:127]
	v_mfma_f32_16x16x32_bf16 v[120:123], v[166:169], v[190:193], v[120:123]
	v_mfma_f32_16x16x32_bf16 v[108:111], v[148:151], v[198:201], v[108:111]
	v_mfma_f32_16x16x32_bf16 v[104:107], v[166:169], v[198:201], v[104:107]
	v_mfma_f32_16x16x32_bf16 v[92:95], v[148:151], v[206:209], v[92:95]
	v_mfma_f32_16x16x32_bf16 v[88:91], v[166:169], v[206:209], v[88:91]
	v_mfma_f32_16x16x32_bf16 v[76:79], v[148:151], v[214:217], v[76:79]
	v_mfma_f32_16x16x32_bf16 v[72:75], v[166:169], v[214:217], v[72:75]
	s_setprio 0
	s_setprio 1
	v_mfma_f32_16x16x32_bf16 v[116:119], v[170:173], v[186:189], 0
	v_mfma_f32_16x16x32_bf16 v[112:115], v[178:181], v[186:189], 0
	v_mfma_f32_16x16x32_bf16 v[100:103], v[170:173], v[194:197], 0
	v_mfma_f32_16x16x32_bf16 v[96:99], v[178:181], v[194:197], 0
	v_mfma_f32_16x16x32_bf16 v[84:87], v[170:173], v[202:205], 0
	v_mfma_f32_16x16x32_bf16 v[80:83], v[178:181], v[202:205], 0
	v_mfma_f32_16x16x32_bf16 v[68:71], v[170:173], v[210:213], 0
	v_mfma_f32_16x16x32_bf16 v[64:67], v[178:181], v[210:213], 0
	v_mfma_f32_16x16x32_bf16 v[116:119], v[174:177], v[190:193], v[116:119]
	v_mfma_f32_16x16x32_bf16 v[112:115], v[182:185], v[190:193], v[112:115]
	v_mfma_f32_16x16x32_bf16 v[100:103], v[174:177], v[198:201], v[100:103]
	v_mfma_f32_16x16x32_bf16 v[96:99], v[182:185], v[198:201], v[96:99]
	v_mfma_f32_16x16x32_bf16 v[84:87], v[174:177], v[206:209], v[84:87]
	v_mfma_f32_16x16x32_bf16 v[80:83], v[182:185], v[206:209], v[80:83]
	v_mfma_f32_16x16x32_bf16 v[68:71], v[174:177], v[214:217], v[68:71]
	v_mfma_f32_16x16x32_bf16 v[64:67], v[182:185], v[214:217], v[64:67]
	s_setprio 0
	s_barrier
	s_add_i32 s33, s78, s62
	s_add_u32 s80, s56, s20
	s_addc_u32 s81, s57, s21
	s_mov_b32 m0, s33
	ds_read_b128 v[186:189], v161 offset:16384
	ds_read_b128 v[190:193], v161 offset:17408
	ds_read_b128 v[194:197], v161 offset:18432
	ds_read_b128 v[198:201], v161 offset:19456
	ds_read_b128 v[202:205], v161 offset:20480
	ds_read_b128 v[206:209], v161 offset:21504
	ds_read_b128 v[210:213], v161 offset:22528
	ds_read_b128 v[214:217], v161 offset:23552
	global_load_lds_dwordx4 v130, s[56:57]
	s_add_i32 m0, s33, 0x2000
	s_add_u32 s92, s56, 0x40000
	s_addc_u32 s93, s57, 0
	s_add_i32 s33, s79, s62
	global_load_lds_dwordx4 v134, s[56:57]
	s_mov_b32 m0, s33
	s_add_u32 s82, s58, s20
	s_addc_u32 s83, s59, s21
	global_load_lds_dwordx4 v130, s[92:93]
	s_add_i32 m0, s33, 0x2000
	s_nop 0
	global_load_lds_dwordx4 v134, s[92:93]
	s_mov_b32 m0, s53
	s_nop 0
	global_load_lds_dwordx4 v128, s[58:59]
	s_mov_b32 m0, s63
	s_nop 0
	global_load_lds_dwordx4 v132, s[58:59]
	s_waitcnt vmcnt(8)
	s_waitcnt lgkmcnt(0)
	s_barrier
; #define PG8_STAGE(bufoff, gbase, voff) do { _Pragma("unroll") for (int _i = 0; _i < 2; ++_i) \
;         __builtin_amdgcn_global_load_lds((const unsigned*)((const char*)(gbase) + (voff)[_i]), (PG8_LAS unsigned*)(lds + (bufoff) + ldsw + _i * 8192), 16, 0, 0); } while (0)
; #define PG8_LDA(dst, b, h) do { _Pragma("unroll") for (int m = 0; m < 4; ++m) _Pragma("unroll") for (int k = 0; k < 2; ++k) dst[m][k] = *(const PG8_LAS bf16x8*)(lds + PG8_SA(b, h) + aoff + m * 2048 + k * 1024); } while (0)
; #define PG8_LDB(dst, b, h) do { _Pragma("unroll") for (int n = 0; n < 2; ++n) _Pragma("unroll") for (int k = 0; k < 2; ++k) dst[n][k] = *(const PG8_LAS bf16x8*)(lds + PG8_SB(b, h) + boff + n * 2048 + k * 1024); } while (0)
; #define PG8_MMA(ai, bj, At, Bt) do { __builtin_amdgcn_s_setprio(1); _Pragma("unroll") for (int m = 0; m < 4; ++m) _Pragma("unroll") for (int n = 0; n < 2; ++n) _Pragma("unroll") for (int k = 0; k < 2; ++k) \
;         acc[ai][bj][m][n] = __builtin_amdgcn_mfma_f32_16x16x32_bf16(Bt[n][k], At[m][k], acc[ai][bj][m][n], 0, 0, 0); __builtin_amdgcn_s_setprio(0); } while (0)
; #define PG8_WAIT_V(n) asm volatile("s_waitcnt vmcnt(" #n ")" ::: "memory")
; #define PG8_WAIT_L(n) asm volatile("s_waitcnt lgkmcnt(" #n ")" ::: "memory")
; #define PG8_BAR __builtin_amdgcn_s_barrier()
; #define PG8_SCHED __builtin_amdgcn_sched_barrier(0)
; template <class Epi, class Sched, bool ALIGN_EPI = false, bool SP2 = false>
; __device__ __forceinline__ void gemm_phase(PG8_LAS unsigned char* lds, const Gemm g, const Sched& S, const Epi& E) {
;     ...
;             PG8_WAIT_V(8); PG8_WAIT_L(0); PG8_BAR; PG8_MMA(1, 0, At, B0); PG8_MMA(1, 1, At, B1); PG8_BAR; PG8_SCHED;
;             PG8_LDB(B0, 1, 0); PG8_LDB(B1, 1, 1); PG8_SCHED; PG8_LDA(At, 1, 0); PG8_STAGE(PG8_SA(0, 1), a2 + hstep, voffA);
;             PG8_WAIT_V(8); PG8_WAIT_L(0); PG8_BAR; PG8_MMA(0, 0, At, B0); PG8_MMA(0, 1, At, B1); PG8_BAR; PG8_SCHED;
	s_setprio 1
	s_waitcnt lgkmcnt(0)
	v_mfma_f32_16x16x32_bf16 v[60:63], v[144:147], v[186:189], 0
	v_mfma_f32_16x16x32_bf16 v[56:59], v[162:165], v[186:189], 0
	v_mfma_f32_16x16x32_bf16 v[48:51], v[144:147], v[194:197], 0
	v_mfma_f32_16x16x32_bf16 v[40:43], v[162:165], v[194:197], 0
	v_mfma_f32_16x16x32_bf16 v[32:35], v[144:147], v[202:205], 0
	v_mfma_f32_16x16x32_bf16 v[24:27], v[162:165], v[202:205], 0
	v_mfma_f32_16x16x32_bf16 v[16:19], v[144:147], v[210:213], 0
	v_mfma_f32_16x16x32_bf16 v[8:11], v[162:165], v[210:213], 0
	v_mfma_f32_16x16x32_bf16 v[60:63], v[148:151], v[190:193], v[60:63]
	v_mfma_f32_16x16x32_bf16 v[56:59], v[166:169], v[190:193], v[56:59]
	v_mfma_f32_16x16x32_bf16 v[48:51], v[148:151], v[198:201], v[48:51]
	v_mfma_f32_16x16x32_bf16 v[40:43], v[166:169], v[198:201], v[40:43]
	v_mfma_f32_16x16x32_bf16 v[32:35], v[148:151], v[206:209], v[32:35]
	v_mfma_f32_16x16x32_bf16 v[24:27], v[166:169], v[206:209], v[24:27]
	v_mfma_f32_16x16x32_bf16 v[16:19], v[148:151], v[214:217], v[16:19]
	v_mfma_f32_16x16x32_bf16 v[8:11], v[166:169], v[214:217], v[8:11]
	s_setprio 0
	s_setprio 1
	v_mfma_f32_16x16x32_bf16 v[52:55], v[170:173], v[186:189], 0
	v_mfma_f32_16x16x32_bf16 v[44:47], v[178:181], v[186:189], 0
	v_mfma_f32_16x16x32_bf16 v[36:39], v[170:173], v[194:197], 0
	v_mfma_f32_16x16x32_bf16 v[28:31], v[178:181], v[194:197], 0
	v_mfma_f32_16x16x32_bf16 v[20:23], v[170:173], v[202:205], 0
	v_mfma_f32_16x16x32_bf16 v[12:15], v[178:181], v[202:205], 0
	v_mfma_f32_16x16x32_bf16 v[4:7], v[170:173], v[210:213], 0
	v_mfma_f32_16x16x32_bf16 v[0:3], v[178:181], v[210:213], 0
	v_mfma_f32_16x16x32_bf16 v[52:55], v[174:177], v[190:193], v[52:55]
	v_mfma_f32_16x16x32_bf16 v[44:47], v[182:185], v[190:193], v[44:47]
	v_mfma_f32_16x16x32_bf16 v[36:39], v[174:177], v[198:201], v[36:39]
	v_mfma_f32_16x16x32_bf16 v[28:31], v[182:185], v[198:201], v[28:31]
	v_mfma_f32_16x16x32_bf16 v[20:23], v[174:177], v[206:209], v[20:23]
	v_mfma_f32_16x16x32_bf16 v[12:15], v[182:185], v[206:209], v[12:15]
	v_mfma_f32_16x16x32_bf16 v[4:7], v[174:177], v[214:217], v[4:7]
	v_mfma_f32_16x16x32_bf16 v[0:3], v[182:185], v[214:217], v[0:3]
	s_setprio 0
	s_barrier
	s_add_i32 s33, 0, 0x18000
	v_add_u32_e32 v153, s33, v157
	s_add_i32 s34, 0, 0x1c000
	ds_read_b128 v[144:147], v153
	ds_read_b128 v[148:151], v153 offset:1024
	ds_read_b128 v[162:165], v153 offset:2048
	ds_read_b128 v[166:169], v153 offset:3072
	v_add_u32_e32 v153, s34, v157
	ds_read_b128 v[170:173], v153
	ds_read_b128 v[174:177], v153 offset:1024
	ds_read_b128 v[178:181], v153 offset:2048
	ds_read_b128 v[182:185], v153 offset:3072
	s_add_u32 s58, s58, 0x40000
	s_addc_u32 s59, s59, 0
	s_mov_b32 m0, s70
	ds_read_b128 v[186:189], v161 offset:32768
	ds_read_b128 v[190:193], v161 offset:33792
	ds_read_b128 v[194:197], v161 offset:34816
	ds_read_b128 v[198:201], v161 offset:35840
	ds_read_b128 v[202:205], v161 offset:36864
	ds_read_b128 v[206:209], v161 offset:37888
	ds_read_b128 v[210:213], v161 offset:38912
	ds_read_b128 v[214:217], v161 offset:39936
	global_load_lds_dwordx4 v128, s[58:59]
	s_mov_b32 m0, s71
	s_nop 0
	global_load_lds_dwordx4 v132, s[58:59]
	s_waitcnt vmcnt(8)
	s_waitcnt lgkmcnt(0)
	s_barrier
	s_setprio 1
	s_waitcnt lgkmcnt(0)
	v_mfma_f32_16x16x32_bf16 v[124:127], v[144:147], v[186:189], v[124:127]
	v_mfma_f32_16x16x32_bf16 v[120:123], v[162:165], v[186:189], v[120:123]
	v_mfma_f32_16x16x32_bf16 v[108:111], v[144:147], v[194:197], v[108:111]
	v_mfma_f32_16x16x32_bf16 v[104:107], v[162:165], v[194:197], v[104:107]
	v_mfma_f32_16x16x32_bf16 v[92:95], v[144:147], v[202:205], v[92:95]
	v_mfma_f32_16x16x32_bf16 v[88:91], v[162:165], v[202:205], v[88:91]
	v_mfma_f32_16x16x32_bf16 v[76:79], v[144:147], v[210:213], v[76:79]
	v_mfma_f32_16x16x32_bf16 v[72:75], v[162:165], v[210:213], v[72:75]
	v_mfma_f32_16x16x32_bf16 v[124:127], v[148:151], v[190:193], v[124:127]
	v_mfma_f32_16x16x32_bf16 v[120:123], v[166:169], v[190:193], v[120:123]
	v_mfma_f32_16x16x32_bf16 v[108:111], v[148:151], v[198:201], v[108:111]
	v_mfma_f32_16x16x32_bf16 v[104:107], v[166:169], v[198:201], v[104:107]
	v_mfma_f32_16x16x32_bf16 v[92:95], v[148:151], v[206:209], v[92:95]
	v_mfma_f32_16x16x32_bf16 v[88:91], v[166:169], v[206:209], v[88:91]
	v_mfma_f32_16x16x32_bf16 v[76:79], v[148:151], v[214:217], v[76:79]
	v_mfma_f32_16x16x32_bf16 v[72:75], v[166:169], v[214:217], v[72:75]
	s_setprio 0
	s_setprio 1
	v_mfma_f32_16x16x32_bf16 v[116:119], v[170:173], v[186:189], v[116:119]
	v_mfma_f32_16x16x32_bf16 v[112:115], v[178:181], v[186:189], v[112:115]
	v_mfma_f32_16x16x32_bf16 v[100:103], v[170:173], v[194:197], v[100:103]
	v_mfma_f32_16x16x32_bf16 v[96:99], v[178:181], v[194:197], v[96:99]
	v_mfma_f32_16x16x32_bf16 v[84:87], v[170:173], v[202:205], v[84:87]
	v_mfma_f32_16x16x32_bf16 v[80:83], v[178:181], v[202:205], v[80:83]
	v_mfma_f32_16x16x32_bf16 v[68:71], v[170:173], v[210:213], v[68:71]
	v_mfma_f32_16x16x32_bf16 v[64:67], v[178:181], v[210:213], v[64:67]
	v_mfma_f32_16x16x32_bf16 v[116:119], v[174:177], v[190:193], v[116:119]
	v_mfma_f32_16x16x32_bf16 v[112:115], v[182:185], v[190:193], v[112:115]
	v_mfma_f32_16x16x32_bf16 v[100:103], v[174:177], v[198:201], v[100:103]
	v_mfma_f32_16x16x32_bf16 v[96:99], v[182:185], v[198:201], v[96:99]
	v_mfma_f32_16x16x32_bf16 v[84:87], v[174:177], v[206:209], v[84:87]
	v_mfma_f32_16x16x32_bf16 v[80:83], v[182:185], v[206:209], v[80:83]
	v_mfma_f32_16x16x32_bf16 v[68:71], v[174:177], v[214:217], v[68:71]
	v_mfma_f32_16x16x32_bf16 v[64:67], v[182:185], v[214:217], v[64:67]
	s_setprio 0
	s_barrier
; #define PG8_STAGE(bufoff, gbase, voff) do { _Pragma("unroll") for (int _i = 0; _i < 2; ++_i) \
;         __builtin_amdgcn_global_load_lds((const unsigned*)((const char*)(gbase) + (voff)[_i]), (PG8_LAS unsigned*)(lds + (bufoff) + ldsw + _i * 8192), 16, 0, 0); } while (0)
; #define PG8_LDA(dst, b, h) do { _Pragma("unroll") for (int m = 0; m < 4; ++m) _Pragma("unroll") for (int k = 0; k < 2; ++k) dst[m][k] = *(const PG8_LAS bf16x8*)(lds + PG8_SA(b, h) + aoff + m * 2048 + k * 1024); } while (0)
; #define PG8_MMA(ai, bj, At, Bt) do { __builtin_amdgcn_s_setprio(1); _Pragma("unroll") for (int m = 0; m < 4; ++m) _Pragma("unroll") for (int n = 0; n < 2; ++n) _Pragma("unroll") for (int k = 0; k < 2; ++k) \
;         acc[ai][bj][m][n] = __builtin_amdgcn_mfma_f32_16x16x32_bf16(Bt[n][k], At[m][k], acc[ai][bj][m][n], 0, 0, 0); __builtin_amdgcn_s_setprio(0); } while (0)
; #define PG8_WAIT_V(n) asm volatile("s_waitcnt vmcnt(" #n ")" ::: "memory")
; #define PG8_WAIT_L(n) asm volatile("s_waitcnt lgkmcnt(" #n ")" ::: "memory")
; #define PG8_BAR __builtin_amdgcn_s_barrier()
; #define PG8_SCHED __builtin_amdgcn_sched_barrier(0)
; template <class Epi, class Sched, bool ALIGN_EPI = false, bool SP2 = false>
; __device__ __forceinline__ void gemm_phase(PG8_LAS unsigned char* lds, const Gemm g, const Sched& S, const Epi& E) {
;     ...
;             PG8_LDA(At, 1, 1); PG8_STAGE(PG8_SB(1, 0), b3, voffB); PG8_STAGE(PG8_SB(1, 1), b3 + hstep, voffB); PG8_STAGE(PG8_SA(1, 0), a3, voffA);
;             PG8_WAIT_V(8); PG8_WAIT_L(0); PG8_BAR; PG8_MMA(1, 0, At, B0); PG8_MMA(1, 1, At, B1); PG8_BAR; PG8_SCHED;
	s_add_i32 s33, s33, s62
	s_mov_b32 m0, s33
	ds_read_b128 v[186:189], v161 offset:49152
	ds_read_b128 v[190:193], v161 offset:50176
	ds_read_b128 v[194:197], v161 offset:51200
	ds_read_b128 v[198:201], v161 offset:52224
	ds_read_b128 v[202:205], v161 offset:53248
	ds_read_b128 v[206:209], v161 offset:54272
	ds_read_b128 v[210:213], v161 offset:55296
	ds_read_b128 v[214:217], v161 offset:56320
	global_load_lds_dwordx4 v130, s[80:81]
	s_add_i32 m0, s33, 0x2000
	s_add_u32 s56, s56, 0x40080
	s_addc_u32 s57, s57, 0
	s_add_i32 s33, s34, s62
	global_load_lds_dwordx4 v134, s[80:81]
	s_mov_b32 m0, s33
	s_nop 0
	global_load_lds_dwordx4 v130, s[56:57]
	s_add_i32 m0, s33, 0x2000
	s_nop 0
	global_load_lds_dwordx4 v134, s[56:57]
	s_mov_b32 m0, s75
	s_nop 0
	global_load_lds_dwordx4 v128, s[82:83]
	s_mov_b32 m0, s76
	s_nop 0
	global_load_lds_dwordx4 v132, s[82:83]
	s_waitcnt vmcnt(8)
	s_waitcnt lgkmcnt(0)
	s_barrier
	s_setprio 1
	s_waitcnt lgkmcnt(0)
	v_mfma_f32_16x16x32_bf16 v[60:63], v[144:147], v[186:189], v[60:63]
	v_mfma_f32_16x16x32_bf16 v[56:59], v[162:165], v[186:189], v[56:59]
	v_mfma_f32_16x16x32_bf16 v[48:51], v[144:147], v[194:197], v[48:51]
	v_mfma_f32_16x16x32_bf16 v[40:43], v[162:165], v[194:197], v[40:43]
	v_mfma_f32_16x16x32_bf16 v[32:35], v[144:147], v[202:205], v[32:35]
	v_mfma_f32_16x16x32_bf16 v[24:27], v[162:165], v[202:205], v[24:27]
	v_mfma_f32_16x16x32_bf16 v[16:19], v[144:147], v[210:213], v[16:19]
	v_mfma_f32_16x16x32_bf16 v[8:11], v[162:165], v[210:213], v[8:11]
	v_mfma_f32_16x16x32_bf16 v[60:63], v[148:151], v[190:193], v[60:63]
	v_mfma_f32_16x16x32_bf16 v[56:59], v[166:169], v[190:193], v[56:59]
	v_mfma_f32_16x16x32_bf16 v[48:51], v[148:151], v[198:201], v[48:51]
	v_mfma_f32_16x16x32_bf16 v[40:43], v[166:169], v[198:201], v[40:43]
	v_mfma_f32_16x16x32_bf16 v[32:35], v[148:151], v[206:209], v[32:35]
	v_mfma_f32_16x16x32_bf16 v[24:27], v[166:169], v[206:209], v[24:27]
	v_mfma_f32_16x16x32_bf16 v[16:19], v[148:151], v[214:217], v[16:19]
	v_mfma_f32_16x16x32_bf16 v[8:11], v[166:169], v[214:217], v[8:11]
	s_setprio 0
	s_setprio 1
	v_mfma_f32_16x16x32_bf16 v[52:55], v[170:173], v[186:189], v[52:55]
	v_mfma_f32_16x16x32_bf16 v[44:47], v[178:181], v[186:189], v[44:47]
	v_mfma_f32_16x16x32_bf16 v[36:39], v[170:173], v[194:197], v[36:39]
	v_mfma_f32_16x16x32_bf16 v[28:31], v[178:181], v[194:197], v[28:31]
	v_mfma_f32_16x16x32_bf16 v[20:23], v[170:173], v[202:205], v[20:23]
	v_mfma_f32_16x16x32_bf16 v[12:15], v[178:181], v[202:205], v[12:15]
	v_mfma_f32_16x16x32_bf16 v[4:7], v[170:173], v[210:213], v[4:7]
	v_mfma_f32_16x16x32_bf16 v[0:3], v[178:181], v[210:213], v[0:3]
	v_mfma_f32_16x16x32_bf16 v[52:55], v[174:177], v[190:193], v[52:55]
	v_mfma_f32_16x16x32_bf16 v[44:47], v[182:185], v[190:193], v[44:47]
	v_mfma_f32_16x16x32_bf16 v[36:39], v[174:177], v[198:201], v[36:39]
	v_mfma_f32_16x16x32_bf16 v[28:31], v[182:185], v[198:201], v[28:31]
	v_mfma_f32_16x16x32_bf16 v[20:23], v[174:177], v[206:209], v[20:23]
	v_mfma_f32_16x16x32_bf16 v[12:15], v[182:185], v[206:209], v[12:15]
	v_mfma_f32_16x16x32_bf16 v[4:7], v[174:177], v[214:217], v[4:7]
	v_mfma_f32_16x16x32_bf16 v[0:3], v[182:185], v[214:217], v[0:3]
	s_setprio 0
	s_barrier
	s_add_i32 s91, s91, 2
	s_add_u32 s54, s54, 0x100
	s_addc_u32 s55, s55, 0
	s_add_u32 s87, s87, 0x100
	s_addc_u32 s90, s90, 0
	s_cmp_gt_u32 s91, 13

; #define PG8_STAGE(bufoff, gbase, voff) do { _Pragma("unroll") for (int _i = 0; _i < 2; ++_i) \
;         __builtin_amdgcn_global_load_lds((const unsigned*)((const char*)(gbase) + (voff)[_i]), (PG8_LAS unsigned*)(lds + (bufoff) + ldsw + _i * 8192), 16, 0, 0); } while (0)
; #define PG8_LDA(dst, b, h) do { _Pragma("unroll") for (int m = 0; m < 4; ++m) _Pragma("unroll") for (int k = 0; k < 2; ++k) dst[m][k] = *(const PG8_LAS bf16x8*)(lds + PG8_SA(b, h) + aoff + m * 2048 + k * 1024); } while (0)
; #define PG8_LDB(dst, b, h) do { _Pragma("unroll") for (int n = 0; n < 2; ++n) _Pragma("unroll") for (int k = 0; k < 2; ++k) dst[n][k] = *(const PG8_LAS bf16x8*)(lds + PG8_SB(b, h) + boff + n * 2048 + k * 1024); } while (0)
; #define PG8_MMA(ai, bj, At, Bt) do { __builtin_amdgcn_s_setprio(1); _Pragma("unroll") for (int m = 0; m < 4; ++m) _Pragma("unroll") for (int n = 0; n < 2; ++n) _Pragma("unroll") for (int k = 0; k < 2; ++k) \
;         acc[ai][bj][m][n] = __builtin_amdgcn_mfma_f32_16x16x32_bf16(Bt[n][k], At[m][k], acc[ai][bj][m][n], 0, 0, 0); __builtin_amdgcn_s_setprio(0); } while (0)
; #define PG8_WAIT_V(n) asm volatile("s_waitcnt vmcnt(" #n ")" ::: "memory")
; #define PG8_BAR __builtin_amdgcn_s_barrier()
; template <class Epi, class Sched, bool ALIGN_EPI = false, bool SP2 = false>
; __device__ __forceinline__ void gemm_phase(PG8_LAS unsigned char* lds, const Gemm g, const Sched& S, const Epi& E) {
;     ...
;         const char* nA = has_next ? (const char*)g.A + (size_t)nxt.pm * tstep : cA; const char* nB = has_next ? (const char*)g.Bt + (size_t)nxt.pn * tstep : cB;
;         for (int t = 0; t < nt; t += 2) {
;             const bool last = (t == nt - 2);
;             const char* a1 = cA + (size_t)(t + 1) * kstep;
;             const char* a2 = last ? nA : cA + (size_t)(t + 2) * kstep; const char* b2 = last ? nB : cB + (size_t)(t + 2) * kstep;
;     ...
;             PG8_LDB(B0, 0, 0); PG8_LDB(B1, 0, 1); PG8_SCHED; PG8_LDA(At, 0, 0); PG8_STAGE(PG8_SA(1, 1), a1 + hstep, voffA);
;             PG8_WAIT_V(8); PG8_WAIT_L(0); PG8_BAR; PG8_MMA(0, 0, At, B0); PG8_MMA(0, 1, At, B1); PG8_BAR; PG8_SCHED;
;             PG8_LDA(At, 0, 1); PG8_STAGE(PG8_SB(0, 0), b2, voffB); PG8_STAGE(PG8_SB(0, 1), b2 + hstep, voffB); PG8_STAGE(PG8_SA(0, 0), a2, voffA);
;             PG8_WAIT_V(8); PG8_WAIT_L(0); PG8_BAR; PG8_MMA(1, 0, At, B0); PG8_MMA(1, 1, At, B1); PG8_BAR; PG8_SCHED;
.LBB0_1209:
	s_ashr_i32 s43, s42, 31
	s_lshl_b64 s[44:45], s[42:43], 19
	s_add_u32 s44, s16, s44
	s_addc_u32 s45, s17, s45
	s_and_b64 s[46:47], s[0:1], exec
	s_cselect_b32 s43, s45, s5
	s_cselect_b32 s76, s44, s4
	s_ashr_i32 s41, s40, 31
	s_lshl_b64 s[46:47], s[40:41], 19
	s_add_u32 s46, s56, s46
	s_addc_u32 s47, s57, s47
	s_and_b64 s[54:55], s[0:1], exec
	s_cselect_b32 s41, s47, s53
	s_cselect_b32 s77, s46, s52
	s_add_u32 s4, s4, 0x40080
	s_addc_u32 s5, s5, 0
	s_add_u32 s78, s52, 0x100
	s_addc_u32 s79, s53, 0
	s_mov_b32 s80, -2
	s_waitcnt lgkmcnt(0)
	ds_read_b128 v[128:131], v181
	ds_read_b128 v[132:135], v181 offset:1024
	ds_read_b128 v[136:139], v181 offset:2048
	ds_read_b128 v[140:143], v181 offset:3072
	ds_read_b128 v[144:147], v182
	ds_read_b128 v[166:169], v182 offset:1024
	ds_read_b128 v[170:173], v182 offset:2048
	ds_read_b128 v[174:177], v182 offset:3072
	s_add_u32 s33, s4, 0xfffc0080
	s_addc_u32 s34, s5, -1
	s_cmp_eq_u32 s80, 12
	s_cselect_b32 s55, s43, s34
	s_cselect_b32 s54, s76, s33
	s_cselect_b32 s53, s41, s79
	s_cselect_b32 s52, s77, s78
	s_add_i32 m0, s49, 0xc000
	ds_read_b128 v[184:187], v183
	ds_read_b128 v[188:191], v183 offset:1024
	ds_read_b128 v[192:195], v183 offset:2048
	ds_read_b128 v[196:199], v183 offset:3072
	ds_read_b128 v[200:203], v183 offset:4096
	ds_read_b128 v[204:207], v183 offset:5120
	ds_read_b128 v[208:211], v183 offset:6144
	ds_read_b128 v[212:215], v183 offset:7168
	global_load_lds_dwordx4 v158, s[4:5]
	s_add_i32 m0, s49, 0xe000
	s_nop 0
	global_load_lds_dwordx4 v160, s[4:5]
	s_waitcnt vmcnt(8)
	s_waitcnt lgkmcnt(0)
	s_barrier
	s_setprio 1
	s_waitcnt lgkmcnt(0)
	v_mfma_f32_16x16x32_bf16 v[124:127], v[128:131], v[184:187], 0
	v_mfma_f32_16x16x32_bf16 v[120:123], v[136:139], v[184:187], 0
	v_mfma_f32_16x16x32_bf16 v[116:119], v[128:131], v[192:195], 0
	v_mfma_f32_16x16x32_bf16 v[112:115], v[136:139], v[192:195], 0
	v_mfma_f32_16x16x32_bf16 v[108:111], v[128:131], v[200:203], 0
	v_mfma_f32_16x16x32_bf16 v[104:107], v[136:139], v[200:203], 0
	v_mfma_f32_16x16x32_bf16 v[100:103], v[128:131], v[208:211], 0
	v_mfma_f32_16x16x32_bf16 v[96:99], v[136:139], v[208:211], 0
	v_mfma_f32_16x16x32_bf16 v[124:127], v[132:135], v[188:191], v[124:127]
	v_mfma_f32_16x16x32_bf16 v[120:123], v[140:143], v[188:191], v[120:123]
	v_mfma_f32_16x16x32_bf16 v[116:119], v[132:135], v[196:199], v[116:119]
	v_mfma_f32_16x16x32_bf16 v[112:115], v[140:143], v[196:199], v[112:115]
	v_mfma_f32_16x16x32_bf16 v[108:111], v[132:135], v[204:207], v[108:111]
	v_mfma_f32_16x16x32_bf16 v[104:107], v[140:143], v[204:207], v[104:107]
	v_mfma_f32_16x16x32_bf16 v[100:103], v[132:135], v[212:215], v[100:103]
	v_mfma_f32_16x16x32_bf16 v[96:99], v[140:143], v[212:215], v[96:99]
	s_setprio 0
	s_setprio 1
	v_mfma_f32_16x16x32_bf16 v[60:63], v[144:147], v[184:187], 0
	v_mfma_f32_16x16x32_bf16 v[56:59], v[170:173], v[184:187], 0
	v_mfma_f32_16x16x32_bf16 v[52:55], v[144:147], v[192:195], 0
	v_mfma_f32_16x16x32_bf16 v[48:51], v[170:173], v[192:195], 0
	v_mfma_f32_16x16x32_bf16 v[44:47], v[144:147], v[200:203], 0
	v_mfma_f32_16x16x32_bf16 v[40:43], v[170:173], v[200:203], 0
	v_mfma_f32_16x16x32_bf16 v[36:39], v[144:147], v[208:211], 0
	v_mfma_f32_16x16x32_bf16 v[32:35], v[170:173], v[208:211], 0
	v_mfma_f32_16x16x32_bf16 v[60:63], v[166:169], v[188:191], v[60:63]
	v_mfma_f32_16x16x32_bf16 v[56:59], v[174:177], v[188:191], v[56:59]
	v_mfma_f32_16x16x32_bf16 v[52:55], v[166:169], v[196:199], v[52:55]
	v_mfma_f32_16x16x32_bf16 v[48:51], v[174:177], v[196:199], v[48:51]
	v_mfma_f32_16x16x32_bf16 v[44:47], v[166:169], v[204:207], v[44:47]
	v_mfma_f32_16x16x32_bf16 v[40:43], v[174:177], v[204:207], v[40:43]
	v_mfma_f32_16x16x32_bf16 v[36:39], v[166:169], v[212:215], v[36:39]
	v_mfma_f32_16x16x32_bf16 v[32:35], v[174:177], v[212:215], v[32:35]
	s_setprio 0
	s_barrier
	s_add_i32 s33, s69, s58
	s_add_u32 s86, s52, s20
	s_addc_u32 s87, s53, s21
	s_mov_b32 m0, s33
	ds_read_b128 v[184:187], v183 offset:16384
	ds_read_b128 v[188:191], v183 offset:17408
	ds_read_b128 v[192:195], v183 offset:18432
	ds_read_b128 v[196:199], v183 offset:19456
	ds_read_b128 v[200:203], v183 offset:20480
	ds_read_b128 v[204:207], v183 offset:21504
	ds_read_b128 v[208:211], v183 offset:22528
	ds_read_b128 v[212:215], v183 offset:23552
	global_load_lds_dwordx4 v150, s[52:53]
	s_add_i32 m0, s33, 0x2000
	s_add_u32 s82, s52, 0x40000
	s_addc_u32 s83, s53, 0
	s_add_i32 s33, s70, s58
	global_load_lds_dwordx4 v156, s[52:53]
	s_mov_b32 m0, s33
	s_add_u32 s88, s54, s20
	s_addc_u32 s89, s55, s21
	global_load_lds_dwordx4 v150, s[82:83]
	s_add_i32 m0, s33, 0x2000
	s_nop 0
	global_load_lds_dwordx4 v156, s[82:83]
	s_mov_b32 m0, s49
	s_nop 0
	global_load_lds_dwordx4 v148, s[54:55]
	s_mov_b32 m0, s60
	s_nop 0
	global_load_lds_dwordx4 v154, s[54:55]
	s_waitcnt vmcnt(8)
	s_waitcnt lgkmcnt(0)
	s_barrier
; #define PG8_STAGE(bufoff, gbase, voff) do { _Pragma("unroll") for (int _i = 0; _i < 2; ++_i) \
;         __builtin_amdgcn_global_load_lds((const unsigned*)((const char*)(gbase) + (voff)[_i]), (PG8_LAS unsigned*)(lds + (bufoff) + ldsw + _i * 8192), 16, 0, 0); } while (0)
; #define PG8_LDA(dst, b, h) do { _Pragma("unroll") for (int m = 0; m < 4; ++m) _Pragma("unroll") for (int k = 0; k < 2; ++k) dst[m][k] = *(const PG8_LAS bf16x8*)(lds + PG8_SA(b, h) + aoff + m * 2048 + k * 1024); } while (0)
; #define PG8_LDB(dst, b, h) do { _Pragma("unroll") for (int n = 0; n < 2; ++n) _Pragma("unroll") for (int k = 0; k < 2; ++k) dst[n][k] = *(const PG8_LAS bf16x8*)(lds + PG8_SB(b, h) + boff + n * 2048 + k * 1024); } while (0)
; #define PG8_MMA(ai, bj, At, Bt) do { __builtin_amdgcn_s_setprio(1); _Pragma("unroll") for (int m = 0; m < 4; ++m) _Pragma("unroll") for (int n = 0; n < 2; ++n) _Pragma("unroll") for (int k = 0; k < 2; ++k) \
;         acc[ai][bj][m][n] = __builtin_amdgcn_mfma_f32_16x16x32_bf16(Bt[n][k], At[m][k], acc[ai][bj][m][n], 0, 0, 0); __builtin_amdgcn_s_setprio(0); } while (0)
; #define PG8_WAIT_V(n) asm volatile("s_waitcnt vmcnt(" #n ")" ::: "memory")
; #define PG8_WAIT_L(n) asm volatile("s_waitcnt lgkmcnt(" #n ")" ::: "memory")
; #define PG8_BAR __builtin_amdgcn_s_barrier()
; #define PG8_SCHED __builtin_amdgcn_sched_barrier(0)
; template <class Epi, class Sched, bool ALIGN_EPI = false, bool SP2 = false>
; __device__ __forceinline__ void gemm_phase(PG8_LAS unsigned char* lds, const Gemm g, const Sched& S, const Epi& E) {
;     ...
;             PG8_WAIT_V(8); PG8_WAIT_L(0); PG8_BAR; PG8_MMA(1, 0, At, B0); PG8_MMA(1, 1, At, B1); PG8_BAR; PG8_SCHED;
;             PG8_LDB(B0, 1, 0); PG8_LDB(B1, 1, 1); PG8_SCHED; PG8_LDA(At, 1, 0); PG8_STAGE(PG8_SA(0, 1), a2 + hstep, voffA);
;             PG8_WAIT_V(8); PG8_WAIT_L(0); PG8_BAR; PG8_MMA(0, 0, At, B0); PG8_MMA(0, 1, At, B1); PG8_BAR; PG8_SCHED;
	s_setprio 1
	s_waitcnt lgkmcnt(0)
	v_mfma_f32_16x16x32_bf16 v[92:95], v[128:131], v[184:187], 0
	v_mfma_f32_16x16x32_bf16 v[88:91], v[136:139], v[184:187], 0
	v_mfma_f32_16x16x32_bf16 v[84:87], v[128:131], v[192:195], 0
	v_mfma_f32_16x16x32_bf16 v[80:83], v[136:139], v[192:195], 0
	v_mfma_f32_16x16x32_bf16 v[76:79], v[128:131], v[200:203], 0
	v_mfma_f32_16x16x32_bf16 v[72:75], v[136:139], v[200:203], 0
	v_mfma_f32_16x16x32_bf16 v[68:71], v[128:131], v[208:211], 0
	v_mfma_f32_16x16x32_bf16 v[64:67], v[136:139], v[208:211], 0
	v_mfma_f32_16x16x32_bf16 v[92:95], v[132:135], v[188:191], v[92:95]
	v_mfma_f32_16x16x32_bf16 v[88:91], v[140:143], v[188:191], v[88:91]
	v_mfma_f32_16x16x32_bf16 v[84:87], v[132:135], v[196:199], v[84:87]
	v_mfma_f32_16x16x32_bf16 v[80:83], v[140:143], v[196:199], v[80:83]
	v_mfma_f32_16x16x32_bf16 v[76:79], v[132:135], v[204:207], v[76:79]
	v_mfma_f32_16x16x32_bf16 v[72:75], v[140:143], v[204:207], v[72:75]
	v_mfma_f32_16x16x32_bf16 v[68:71], v[132:135], v[212:215], v[68:71]
	v_mfma_f32_16x16x32_bf16 v[64:67], v[140:143], v[212:215], v[64:67]
	s_setprio 0
	s_setprio 1
	v_mfma_f32_16x16x32_bf16 v[28:31], v[144:147], v[184:187], 0
	v_mfma_f32_16x16x32_bf16 v[24:27], v[170:173], v[184:187], 0
	v_mfma_f32_16x16x32_bf16 v[20:23], v[144:147], v[192:195], 0
	v_mfma_f32_16x16x32_bf16 v[16:19], v[170:173], v[192:195], 0
	v_mfma_f32_16x16x32_bf16 v[12:15], v[144:147], v[200:203], 0
	v_mfma_f32_16x16x32_bf16 v[8:11], v[170:173], v[200:203], 0
	v_mfma_f32_16x16x32_bf16 v[4:7], v[144:147], v[208:211], 0
	v_mfma_f32_16x16x32_bf16 v[0:3], v[170:173], v[208:211], 0
	v_mfma_f32_16x16x32_bf16 v[28:31], v[166:169], v[188:191], v[28:31]
	v_mfma_f32_16x16x32_bf16 v[24:27], v[174:177], v[188:191], v[24:27]
	v_mfma_f32_16x16x32_bf16 v[20:23], v[166:169], v[196:199], v[20:23]
	v_mfma_f32_16x16x32_bf16 v[16:19], v[174:177], v[196:199], v[16:19]
	v_mfma_f32_16x16x32_bf16 v[12:15], v[166:169], v[204:207], v[12:15]
	v_mfma_f32_16x16x32_bf16 v[8:11], v[174:177], v[204:207], v[8:11]
	v_mfma_f32_16x16x32_bf16 v[4:7], v[166:169], v[212:215], v[4:7]
	v_mfma_f32_16x16x32_bf16 v[0:3], v[174:177], v[212:215], v[0:3]
	s_setprio 0
	s_barrier
	s_add_i32 s33, 0, 0x18000
	s_add_i32 s34, 0, 0x1c000
	v_add_u32_e32 v140, s33, v179
	v_add_u32_e32 v153, s34, v179
	ds_read_b128 v[128:131], v140
	ds_read_b128 v[132:135], v140 offset:1024
	ds_read_b128 v[136:139], v140 offset:2048
	ds_read_b128 v[140:143], v140 offset:3072
	ds_read_b128 v[144:147], v153
	ds_read_b128 v[166:169], v153 offset:1024
	ds_read_b128 v[170:173], v153 offset:2048
	ds_read_b128 v[174:177], v153 offset:3072
	s_add_u32 s54, s54, 0x40000
	s_addc_u32 s55, s55, 0
	s_mov_b32 m0, s61
	ds_read_b128 v[184:187], v183 offset:32768
	ds_read_b128 v[188:191], v183 offset:33792
	ds_read_b128 v[192:195], v183 offset:34816
	ds_read_b128 v[196:199], v183 offset:35840
	ds_read_b128 v[200:203], v183 offset:36864
	ds_read_b128 v[204:207], v183 offset:37888
	ds_read_b128 v[208:211], v183 offset:38912
	ds_read_b128 v[212:215], v183 offset:39936
	global_load_lds_dwordx4 v148, s[54:55]
	s_mov_b32 m0, s62
	s_nop 0
	global_load_lds_dwordx4 v154, s[54:55]
	s_waitcnt vmcnt(8)
	s_waitcnt lgkmcnt(0)
	s_barrier
	s_setprio 1
	s_waitcnt lgkmcnt(0)
	v_mfma_f32_16x16x32_bf16 v[124:127], v[128:131], v[184:187], v[124:127]
	v_mfma_f32_16x16x32_bf16 v[120:123], v[136:139], v[184:187], v[120:123]
	v_mfma_f32_16x16x32_bf16 v[116:119], v[128:131], v[192:195], v[116:119]
	v_mfma_f32_16x16x32_bf16 v[112:115], v[136:139], v[192:195], v[112:115]
	v_mfma_f32_16x16x32_bf16 v[108:111], v[128:131], v[200:203], v[108:111]
	v_mfma_f32_16x16x32_bf16 v[104:107], v[136:139], v[200:203], v[104:107]
	v_mfma_f32_16x16x32_bf16 v[100:103], v[128:131], v[208:211], v[100:103]
	v_mfma_f32_16x16x32_bf16 v[96:99], v[136:139], v[208:211], v[96:99]
	v_mfma_f32_16x16x32_bf16 v[124:127], v[132:135], v[188:191], v[124:127]
	v_mfma_f32_16x16x32_bf16 v[120:123], v[140:143], v[188:191], v[120:123]
	v_mfma_f32_16x16x32_bf16 v[116:119], v[132:135], v[196:199], v[116:119]
	v_mfma_f32_16x16x32_bf16 v[112:115], v[140:143], v[196:199], v[112:115]
	v_mfma_f32_16x16x32_bf16 v[108:111], v[132:135], v[204:207], v[108:111]
	v_mfma_f32_16x16x32_bf16 v[104:107], v[140:143], v[204:207], v[104:107]
	v_mfma_f32_16x16x32_bf16 v[100:103], v[132:135], v[212:215], v[100:103]
	v_mfma_f32_16x16x32_bf16 v[96:99], v[140:143], v[212:215], v[96:99]
	s_setprio 0
	s_setprio 1
	v_mfma_f32_16x16x32_bf16 v[60:63], v[144:147], v[184:187], v[60:63]
	v_mfma_f32_16x16x32_bf16 v[56:59], v[170:173], v[184:187], v[56:59]
	v_mfma_f32_16x16x32_bf16 v[52:55], v[144:147], v[192:195], v[52:55]
	v_mfma_f32_16x16x32_bf16 v[48:51], v[170:173], v[192:195], v[48:51]
	v_mfma_f32_16x16x32_bf16 v[44:47], v[144:147], v[200:203], v[44:47]
	v_mfma_f32_16x16x32_bf16 v[40:43], v[170:173], v[200:203], v[40:43]
	v_mfma_f32_16x16x32_bf16 v[36:39], v[144:147], v[208:211], v[36:39]
	v_mfma_f32_16x16x32_bf16 v[32:35], v[170:173], v[208:211], v[32:35]
	v_mfma_f32_16x16x32_bf16 v[60:63], v[166:169], v[188:191], v[60:63]
	v_mfma_f32_16x16x32_bf16 v[56:59], v[174:177], v[188:191], v[56:59]
	v_mfma_f32_16x16x32_bf16 v[52:55], v[166:169], v[196:199], v[52:55]
	v_mfma_f32_16x16x32_bf16 v[48:51], v[174:177], v[196:199], v[48:51]
	v_mfma_f32_16x16x32_bf16 v[44:47], v[166:169], v[204:207], v[44:47]
	v_mfma_f32_16x16x32_bf16 v[40:43], v[174:177], v[204:207], v[40:43]
	v_mfma_f32_16x16x32_bf16 v[36:39], v[166:169], v[212:215], v[36:39]
	v_mfma_f32_16x16x32_bf16 v[32:35], v[174:177], v[212:215], v[32:35]
	s_setprio 0
	s_barrier
; #define PG8_STAGE(bufoff, gbase, voff) do { _Pragma("unroll") for (int _i = 0; _i < 2; ++_i) \
;         __builtin_amdgcn_global_load_lds((const unsigned*)((const char*)(gbase) + (voff)[_i]), (PG8_LAS unsigned*)(lds + (bufoff) + ldsw + _i * 8192), 16, 0, 0); } while (0)
; #define PG8_LDA(dst, b, h) do { _Pragma("unroll") for (int m = 0; m < 4; ++m) _Pragma("unroll") for (int k = 0; k < 2; ++k) dst[m][k] = *(const PG8_LAS bf16x8*)(lds + PG8_SA(b, h) + aoff + m * 2048 + k * 1024); } while (0)
; #define PG8_MMA(ai, bj, At, Bt) do { __builtin_amdgcn_s_setprio(1); _Pragma("unroll") for (int m = 0; m < 4; ++m) _Pragma("unroll") for (int n = 0; n < 2; ++n) _Pragma("unroll") for (int k = 0; k < 2; ++k) \
;         acc[ai][bj][m][n] = __builtin_amdgcn_mfma_f32_16x16x32_bf16(Bt[n][k], At[m][k], acc[ai][bj][m][n], 0, 0, 0); __builtin_amdgcn_s_setprio(0); } while (0)
; #define PG8_WAIT_V(n) asm volatile("s_waitcnt vmcnt(" #n ")" ::: "memory")
; #define PG8_WAIT_L(n) asm volatile("s_waitcnt lgkmcnt(" #n ")" ::: "memory")
; #define PG8_BAR __builtin_amdgcn_s_barrier()
; #define PG8_SCHED __builtin_amdgcn_sched_barrier(0)
; template <class Epi, class Sched, bool ALIGN_EPI = false, bool SP2 = false>
; __device__ __forceinline__ void gemm_phase(PG8_LAS unsigned char* lds, const Gemm g, const Sched& S, const Epi& E) {
;     ...
;             PG8_LDA(At, 1, 1); PG8_STAGE(PG8_SB(1, 0), b3, voffB); PG8_STAGE(PG8_SB(1, 1), b3 + hstep, voffB); PG8_STAGE(PG8_SA(1, 0), a3, voffA);
;             PG8_WAIT_V(8); PG8_WAIT_L(0); PG8_BAR; PG8_MMA(1, 0, At, B0); PG8_MMA(1, 1, At, B1); PG8_BAR; PG8_SCHED;
	s_add_i32 s33, s33, s58
	s_mov_b32 m0, s33
	ds_read_b128 v[184:187], v183 offset:49152
	ds_read_b128 v[188:191], v183 offset:50176
	ds_read_b128 v[192:195], v183 offset:51200
	ds_read_b128 v[196:199], v183 offset:52224
	ds_read_b128 v[200:203], v183 offset:53248
	ds_read_b128 v[204:207], v183 offset:54272
	ds_read_b128 v[208:211], v183 offset:55296
	ds_read_b128 v[212:215], v183 offset:56320
	global_load_lds_dwordx4 v150, s[86:87]
	s_add_i32 m0, s33, 0x2000
	s_add_u32 s52, s52, 0x40080
	s_addc_u32 s53, s53, 0
	s_add_i32 s33, s34, s58
	global_load_lds_dwordx4 v156, s[86:87]
	s_mov_b32 m0, s33
	s_nop 0
	global_load_lds_dwordx4 v150, s[52:53]
	s_add_i32 m0, s33, 0x2000
	s_nop 0
	global_load_lds_dwordx4 v156, s[52:53]
	s_mov_b32 m0, s67
	s_nop 0
	global_load_lds_dwordx4 v148, s[88:89]
	s_mov_b32 m0, s68
	s_nop 0
	global_load_lds_dwordx4 v154, s[88:89]
	s_waitcnt vmcnt(8)
	s_waitcnt lgkmcnt(0)
	s_barrier
	s_setprio 1
	s_waitcnt lgkmcnt(0)
	v_mfma_f32_16x16x32_bf16 v[92:95], v[128:131], v[184:187], v[92:95]
	v_mfma_f32_16x16x32_bf16 v[88:91], v[136:139], v[184:187], v[88:91]
	v_mfma_f32_16x16x32_bf16 v[84:87], v[128:131], v[192:195], v[84:87]
	v_mfma_f32_16x16x32_bf16 v[80:83], v[136:139], v[192:195], v[80:83]
	v_mfma_f32_16x16x32_bf16 v[76:79], v[128:131], v[200:203], v[76:79]
	v_mfma_f32_16x16x32_bf16 v[72:75], v[136:139], v[200:203], v[72:75]
	v_mfma_f32_16x16x32_bf16 v[68:71], v[128:131], v[208:211], v[68:71]
	v_mfma_f32_16x16x32_bf16 v[64:67], v[136:139], v[208:211], v[64:67]
	v_mfma_f32_16x16x32_bf16 v[92:95], v[132:135], v[188:191], v[92:95]
	v_mfma_f32_16x16x32_bf16 v[88:91], v[140:143], v[188:191], v[88:91]
	v_mfma_f32_16x16x32_bf16 v[84:87], v[132:135], v[196:199], v[84:87]
	v_mfma_f32_16x16x32_bf16 v[80:83], v[140:143], v[196:199], v[80:83]
	v_mfma_f32_16x16x32_bf16 v[76:79], v[132:135], v[204:207], v[76:79]
	v_mfma_f32_16x16x32_bf16 v[72:75], v[140:143], v[204:207], v[72:75]
	v_mfma_f32_16x16x32_bf16 v[68:71], v[132:135], v[212:215], v[68:71]
	v_mfma_f32_16x16x32_bf16 v[64:67], v[140:143], v[212:215], v[64:67]
	s_setprio 0
	s_setprio 1
	v_mfma_f32_16x16x32_bf16 v[28:31], v[144:147], v[184:187], v[28:31]
	v_mfma_f32_16x16x32_bf16 v[24:27], v[170:173], v[184:187], v[24:27]
	v_mfma_f32_16x16x32_bf16 v[20:23], v[144:147], v[192:195], v[20:23]
	v_mfma_f32_16x16x32_bf16 v[16:19], v[170:173], v[192:195], v[16:19]
	v_mfma_f32_16x16x32_bf16 v[12:15], v[144:147], v[200:203], v[12:15]
	v_mfma_f32_16x16x32_bf16 v[8:11], v[170:173], v[200:203], v[8:11]
	v_mfma_f32_16x16x32_bf16 v[4:7], v[144:147], v[208:211], v[4:7]
	v_mfma_f32_16x16x32_bf16 v[0:3], v[170:173], v[208:211], v[0:3]
	v_mfma_f32_16x16x32_bf16 v[28:31], v[166:169], v[188:191], v[28:31]
	v_mfma_f32_16x16x32_bf16 v[24:27], v[174:177], v[188:191], v[24:27]
	v_mfma_f32_16x16x32_bf16 v[20:23], v[166:169], v[196:199], v[20:23]
	v_mfma_f32_16x16x32_bf16 v[16:19], v[174:177], v[196:199], v[16:19]
	v_mfma_f32_16x16x32_bf16 v[12:15], v[166:169], v[204:207], v[12:15]
	v_mfma_f32_16x16x32_bf16 v[8:11], v[174:177], v[204:207], v[8:11]
	v_mfma_f32_16x16x32_bf16 v[4:7], v[166:169], v[212:215], v[4:7]
	v_mfma_f32_16x16x32_bf16 v[0:3], v[174:177], v[212:215], v[0:3]
	s_setprio 0
	s_barrier
	s_add_i32 s80, s80, 2
	s_add_u32 s4, s4, 0x100
	s_addc_u32 s5, s5, 0
	s_add_u32 s78, s78, 0x100
	s_addc_u32 s79, s79, 0
	s_cmp_gt_u32 s80, 13

; #define PG8_STAGE(bufoff, gbase, voff) do { _Pragma("unroll") for (int _i = 0; _i < 2; ++_i) \
;         __builtin_amdgcn_global_load_lds((const unsigned*)((const char*)(gbase) + (voff)[_i]), (PG8_LAS unsigned*)(lds + (bufoff) + ldsw + _i * 8192), 16, 0, 0); } while (0)
; #define PG8_LDA(dst, b, h) do { _Pragma("unroll") for (int m = 0; m < 4; ++m) _Pragma("unroll") for (int k = 0; k < 2; ++k) dst[m][k] = *(const PG8_LAS bf16x8*)(lds + PG8_SA(b, h) + aoff + m * 2048 + k * 1024); } while (0)
; #define PG8_LDB(dst, b, h) do { _Pragma("unroll") for (int n = 0; n < 2; ++n) _Pragma("unroll") for (int k = 0; k < 2; ++k) dst[n][k] = *(const PG8_LAS bf16x8*)(lds + PG8_SB(b, h) + boff + n * 2048 + k * 1024); } while (0)
; #define PG8_MMA(ai, bj, At, Bt) do { __builtin_amdgcn_s_setprio(1); _Pragma("unroll") for (int m = 0; m < 4; ++m) _Pragma("unroll") for (int n = 0; n < 2; ++n) _Pragma("unroll") for (int k = 0; k < 2; ++k) \
;         acc[ai][bj][m][n] = __builtin_amdgcn_mfma_f32_16x16x32_bf16(Bt[n][k], At[m][k], acc[ai][bj][m][n], 0, 0, 0); __builtin_amdgcn_s_setprio(0); } while (0)
; #define PG8_WAIT_V(n) asm volatile("s_waitcnt vmcnt(" #n ")" ::: "memory")
; #define PG8_BAR __builtin_amdgcn_s_barrier()
; template <class Epi, class Sched, bool ALIGN_EPI = false, bool SP2 = false>
; __device__ __forceinline__ void gemm_phase(PG8_LAS unsigned char* lds, const Gemm g, const Sched& S, const Epi& E) {
;     ...
;         const char* nA = has_next ? (const char*)g.A + (size_t)nxt.pm * tstep : cA; const char* nB = has_next ? (const char*)g.Bt + (size_t)nxt.pn * tstep : cB;
;         for (int t = 0; t < nt; t += 2) {
;             const bool last = (t == nt - 2);
;             const char* a1 = cA + (size_t)(t + 1) * kstep;
;             const char* a2 = last ? nA : cA + (size_t)(t + 2) * kstep; const char* b2 = last ? nB : cB + (size_t)(t + 2) * kstep;
;     ...
;             PG8_LDB(B0, 0, 0); PG8_LDB(B1, 0, 1); PG8_SCHED; PG8_LDA(At, 0, 0); PG8_STAGE(PG8_SA(1, 1), a1 + hstep, voffA);
;             PG8_WAIT_V(8); PG8_WAIT_L(0); PG8_BAR; PG8_MMA(0, 0, At, B0); PG8_MMA(0, 1, At, B1); PG8_BAR; PG8_SCHED;
;             PG8_LDA(At, 0, 1); PG8_STAGE(PG8_SB(0, 0), b2, voffB); PG8_STAGE(PG8_SB(0, 1), b2 + hstep, voffB); PG8_STAGE(PG8_SA(0, 0), a2, voffA);
;             PG8_WAIT_V(8); PG8_WAIT_L(0); PG8_BAR; PG8_MMA(1, 0, At, B0); PG8_MMA(1, 1, At, B1); PG8_BAR; PG8_SCHED;
.LBB0_1341:
	s_ashr_i32 s19, s18, 31
	s_lshl_b64 s[20:21], s[18:19], 19
	s_add_u32 s20, s16, s20
	s_addc_u32 s21, s17, s21
	s_and_b64 s[22:23], s[0:1], exec
	s_cselect_b32 s19, s21, s37
	s_cselect_b32 s58, s20, s36
	s_ashr_i32 s15, s14, 31
	s_lshl_b64 s[22:23], s[14:15], 19
	s_add_u32 s22, s42, s22
	s_addc_u32 s23, s43, s23
	s_and_b64 s[40:41], s[0:1], exec
	s_cselect_b32 s15, s23, s39
	s_cselect_b32 s59, s22, s38
	s_add_u32 s36, s36, 0x40080
	s_addc_u32 s37, s37, 0
	s_add_u32 s60, s38, 0x100
	s_addc_u32 s61, s39, 0
	s_mov_b32 s62, -2
	s_waitcnt lgkmcnt(0)
	ds_read_b128 v[154:157], v147
	ds_read_b128 v[158:161], v147 offset:1024
	ds_read_b128 v[162:165], v147 offset:2048
	ds_read_b128 v[166:169], v147 offset:3072
	ds_read_b128 v[170:173], v148
	ds_read_b128 v[174:177], v148 offset:1024
	ds_read_b128 v[178:181], v148 offset:2048
	ds_read_b128 v[182:185], v148 offset:3072
	s_add_u32 s33, s36, 0xfffc0080
	s_addc_u32 s34, s37, -1
	s_cmp_eq_u32 s62, 12
	s_cselect_b32 s41, s19, s34
	s_cselect_b32 s40, s58, s33
	s_cselect_b32 s39, s15, s61
	s_cselect_b32 s38, s59, s60
	s_add_i32 m0, s25, 0xc000
	ds_read_b128 v[186:189], v149
	ds_read_b128 v[190:193], v149 offset:1024
	ds_read_b128 v[194:197], v149 offset:2048
	ds_read_b128 v[198:201], v149 offset:3072
	ds_read_b128 v[202:205], v149 offset:4096
	ds_read_b128 v[206:209], v149 offset:5120
	ds_read_b128 v[210:213], v149 offset:6144
	ds_read_b128 v[214:217], v149 offset:7168
	global_load_lds_dwordx4 v136, s[36:37]
	s_add_i32 m0, s25, 0xe000
	s_nop 0
	global_load_lds_dwordx4 v138, s[36:37]
	s_waitcnt vmcnt(8)
	s_waitcnt lgkmcnt(0)
	s_barrier
	s_setprio 1
	s_waitcnt lgkmcnt(0)
	v_mfma_f32_16x16x32_bf16 v[124:127], v[154:157], v[186:189], 0
	v_mfma_f32_16x16x32_bf16 v[116:119], v[162:165], v[186:189], 0
	v_mfma_f32_16x16x32_bf16 v[108:111], v[154:157], v[194:197], 0
	v_mfma_f32_16x16x32_bf16 v[100:103], v[162:165], v[194:197], 0
	v_mfma_f32_16x16x32_bf16 v[92:95], v[154:157], v[202:205], 0
	v_mfma_f32_16x16x32_bf16 v[84:87], v[162:165], v[202:205], 0
	v_mfma_f32_16x16x32_bf16 v[76:79], v[154:157], v[210:213], 0
	v_mfma_f32_16x16x32_bf16 v[68:71], v[162:165], v[210:213], 0
	v_mfma_f32_16x16x32_bf16 v[124:127], v[158:161], v[190:193], v[124:127]
	v_mfma_f32_16x16x32_bf16 v[116:119], v[166:169], v[190:193], v[116:119]
	v_mfma_f32_16x16x32_bf16 v[108:111], v[158:161], v[198:201], v[108:111]
	v_mfma_f32_16x16x32_bf16 v[100:103], v[166:169], v[198:201], v[100:103]
	v_mfma_f32_16x16x32_bf16 v[92:95], v[158:161], v[206:209], v[92:95]
	v_mfma_f32_16x16x32_bf16 v[84:87], v[166:169], v[206:209], v[84:87]
	v_mfma_f32_16x16x32_bf16 v[76:79], v[158:161], v[214:217], v[76:79]
	v_mfma_f32_16x16x32_bf16 v[68:71], v[166:169], v[214:217], v[68:71]
	s_setprio 0
	s_setprio 1
	v_mfma_f32_16x16x32_bf16 v[120:123], v[170:173], v[186:189], 0
	v_mfma_f32_16x16x32_bf16 v[112:115], v[178:181], v[186:189], 0
	v_mfma_f32_16x16x32_bf16 v[104:107], v[170:173], v[194:197], 0
	v_mfma_f32_16x16x32_bf16 v[96:99], v[178:181], v[194:197], 0
	v_mfma_f32_16x16x32_bf16 v[88:91], v[170:173], v[202:205], 0
	v_mfma_f32_16x16x32_bf16 v[80:83], v[178:181], v[202:205], 0
	v_mfma_f32_16x16x32_bf16 v[72:75], v[170:173], v[210:213], 0
	v_mfma_f32_16x16x32_bf16 v[64:67], v[178:181], v[210:213], 0
	v_mfma_f32_16x16x32_bf16 v[120:123], v[174:177], v[190:193], v[120:123]
	v_mfma_f32_16x16x32_bf16 v[112:115], v[182:185], v[190:193], v[112:115]
	v_mfma_f32_16x16x32_bf16 v[104:107], v[174:177], v[198:201], v[104:107]
	v_mfma_f32_16x16x32_bf16 v[96:99], v[182:185], v[198:201], v[96:99]
	v_mfma_f32_16x16x32_bf16 v[88:91], v[174:177], v[206:209], v[88:91]
	v_mfma_f32_16x16x32_bf16 v[80:83], v[182:185], v[206:209], v[80:83]
	v_mfma_f32_16x16x32_bf16 v[72:75], v[174:177], v[214:217], v[72:75]
	v_mfma_f32_16x16x32_bf16 v[64:67], v[182:185], v[214:217], v[64:67]
	s_setprio 0
	s_barrier
	s_add_i32 s33, s54, s44
	s_add_u32 s82, s38, s10
	s_addc_u32 s83, s39, s11
	s_mov_b32 m0, s33
	ds_read_b128 v[186:189], v149 offset:16384
	ds_read_b128 v[190:193], v149 offset:17408
	ds_read_b128 v[194:197], v149 offset:18432
	ds_read_b128 v[198:201], v149 offset:19456
	ds_read_b128 v[202:205], v149 offset:20480
	ds_read_b128 v[206:209], v149 offset:21504
	ds_read_b128 v[210:213], v149 offset:22528
	ds_read_b128 v[214:217], v149 offset:23552
	global_load_lds_dwordx4 v130, s[38:39]
	s_add_i32 m0, s33, 0x2000
	s_add_u32 s64, s38, 0x40000
	s_addc_u32 s65, s39, 0
	s_add_i32 s33, s55, s44
	global_load_lds_dwordx4 v134, s[38:39]
	s_mov_b32 m0, s33
	s_add_u32 s84, s40, s10
	s_addc_u32 s85, s41, s11
	global_load_lds_dwordx4 v130, s[64:65]
	s_add_i32 m0, s33, 0x2000
	s_nop 0
	global_load_lds_dwordx4 v134, s[64:65]
	s_mov_b32 m0, s25
	s_nop 0
	global_load_lds_dwordx4 v128, s[40:41]
	s_mov_b32 m0, s47
	s_nop 0
	global_load_lds_dwordx4 v132, s[40:41]
	s_waitcnt vmcnt(8)
	s_waitcnt lgkmcnt(0)
	s_barrier
; #define PG8_STAGE(bufoff, gbase, voff) do { _Pragma("unroll") for (int _i = 0; _i < 2; ++_i) \
;         __builtin_amdgcn_global_load_lds((const unsigned*)((const char*)(gbase) + (voff)[_i]), (PG8_LAS unsigned*)(lds + (bufoff) + ldsw + _i * 8192), 16, 0, 0); } while (0)
; #define PG8_LDA(dst, b, h) do { _Pragma("unroll") for (int m = 0; m < 4; ++m) _Pragma("unroll") for (int k = 0; k < 2; ++k) dst[m][k] = *(const PG8_LAS bf16x8*)(lds + PG8_SA(b, h) + aoff + m * 2048 + k * 1024); } while (0)
; #define PG8_LDB(dst, b, h) do { _Pragma("unroll") for (int n = 0; n < 2; ++n) _Pragma("unroll") for (int k = 0; k < 2; ++k) dst[n][k] = *(const PG8_LAS bf16x8*)(lds + PG8_SB(b, h) + boff + n * 2048 + k * 1024); } while (0)
; #define PG8_MMA(ai, bj, At, Bt) do { __builtin_amdgcn_s_setprio(1); _Pragma("unroll") for (int m = 0; m < 4; ++m) _Pragma("unroll") for (int n = 0; n < 2; ++n) _Pragma("unroll") for (int k = 0; k < 2; ++k) \
;         acc[ai][bj][m][n] = __builtin_amdgcn_mfma_f32_16x16x32_bf16(Bt[n][k], At[m][k], acc[ai][bj][m][n], 0, 0, 0); __builtin_amdgcn_s_setprio(0); } while (0)
; #define PG8_WAIT_V(n) asm volatile("s_waitcnt vmcnt(" #n ")" ::: "memory")
; #define PG8_WAIT_L(n) asm volatile("s_waitcnt lgkmcnt(" #n ")" ::: "memory")
; #define PG8_BAR __builtin_amdgcn_s_barrier()
; #define PG8_SCHED __builtin_amdgcn_sched_barrier(0)
; template <class Epi, class Sched, bool ALIGN_EPI = false, bool SP2 = false>
; __device__ __forceinline__ void gemm_phase(PG8_LAS unsigned char* lds, const Gemm g, const Sched& S, const Epi& E) {
;     ...
;             PG8_WAIT_V(8); PG8_WAIT_L(0); PG8_BAR; PG8_MMA(1, 0, At, B0); PG8_MMA(1, 1, At, B1); PG8_BAR; PG8_SCHED;
;             PG8_LDB(B0, 1, 0); PG8_LDB(B1, 1, 1); PG8_SCHED; PG8_LDA(At, 1, 0); PG8_STAGE(PG8_SA(0, 1), a2 + hstep, voffA);
;             PG8_WAIT_V(8); PG8_WAIT_L(0); PG8_BAR; PG8_MMA(0, 0, At, B0); PG8_MMA(0, 1, At, B1); PG8_BAR; PG8_SCHED;
	s_setprio 1
	s_waitcnt lgkmcnt(0)
	v_mfma_f32_16x16x32_bf16 v[60:63], v[154:157], v[186:189], 0
	v_mfma_f32_16x16x32_bf16 v[52:55], v[162:165], v[186:189], 0
	v_mfma_f32_16x16x32_bf16 v[44:47], v[154:157], v[194:197], 0
	v_mfma_f32_16x16x32_bf16 v[36:39], v[162:165], v[194:197], 0
	v_mfma_f32_16x16x32_bf16 v[28:31], v[154:157], v[202:205], 0
	v_mfma_f32_16x16x32_bf16 v[20:23], v[162:165], v[202:205], 0
	v_mfma_f32_16x16x32_bf16 v[12:15], v[154:157], v[210:213], 0
	v_mfma_f32_16x16x32_bf16 v[4:7], v[162:165], v[210:213], 0
	v_mfma_f32_16x16x32_bf16 v[60:63], v[158:161], v[190:193], v[60:63]
	v_mfma_f32_16x16x32_bf16 v[52:55], v[166:169], v[190:193], v[52:55]
	v_mfma_f32_16x16x32_bf16 v[44:47], v[158:161], v[198:201], v[44:47]
	v_mfma_f32_16x16x32_bf16 v[36:39], v[166:169], v[198:201], v[36:39]
	v_mfma_f32_16x16x32_bf16 v[28:31], v[158:161], v[206:209], v[28:31]
	v_mfma_f32_16x16x32_bf16 v[20:23], v[166:169], v[206:209], v[20:23]
	v_mfma_f32_16x16x32_bf16 v[12:15], v[158:161], v[214:217], v[12:15]
	v_mfma_f32_16x16x32_bf16 v[4:7], v[166:169], v[214:217], v[4:7]
	s_setprio 0
	s_setprio 1
	v_mfma_f32_16x16x32_bf16 v[56:59], v[170:173], v[186:189], 0
	v_mfma_f32_16x16x32_bf16 v[48:51], v[178:181], v[186:189], 0
	v_mfma_f32_16x16x32_bf16 v[40:43], v[170:173], v[194:197], 0
	v_mfma_f32_16x16x32_bf16 v[32:35], v[178:181], v[194:197], 0
	v_mfma_f32_16x16x32_bf16 v[24:27], v[170:173], v[202:205], 0
	v_mfma_f32_16x16x32_bf16 v[16:19], v[178:181], v[202:205], 0
	v_mfma_f32_16x16x32_bf16 v[8:11], v[170:173], v[210:213], 0
	v_mfma_f32_16x16x32_bf16 v[0:3], v[178:181], v[210:213], 0
	v_mfma_f32_16x16x32_bf16 v[56:59], v[174:177], v[190:193], v[56:59]
	v_mfma_f32_16x16x32_bf16 v[48:51], v[182:185], v[190:193], v[48:51]
	v_mfma_f32_16x16x32_bf16 v[40:43], v[174:177], v[198:201], v[40:43]
	v_mfma_f32_16x16x32_bf16 v[32:35], v[182:185], v[198:201], v[32:35]
	v_mfma_f32_16x16x32_bf16 v[24:27], v[174:177], v[206:209], v[24:27]
	v_mfma_f32_16x16x32_bf16 v[16:19], v[182:185], v[206:209], v[16:19]
	v_mfma_f32_16x16x32_bf16 v[8:11], v[174:177], v[214:217], v[8:11]
	v_mfma_f32_16x16x32_bf16 v[0:3], v[182:185], v[214:217], v[0:3]
	s_setprio 0
	s_barrier
	s_add_i32 s33, 0, 0x18000
	v_add_u32_e32 v153, s33, v145
	s_add_i32 s34, 0, 0x1c000
	ds_read_b128 v[154:157], v153
	ds_read_b128 v[158:161], v153 offset:1024
	ds_read_b128 v[162:165], v153 offset:2048
	ds_read_b128 v[166:169], v153 offset:3072
	v_add_u32_e32 v153, s34, v145
	ds_read_b128 v[170:173], v153
	ds_read_b128 v[174:177], v153 offset:1024
	ds_read_b128 v[178:181], v153 offset:2048
	ds_read_b128 v[182:185], v153 offset:3072
	s_add_u32 s40, s40, 0x40000
	s_addc_u32 s41, s41, 0
	s_mov_b32 m0, s48
	ds_read_b128 v[186:189], v149 offset:32768
	ds_read_b128 v[190:193], v149 offset:33792
	ds_read_b128 v[194:197], v149 offset:34816
	ds_read_b128 v[198:201], v149 offset:35840
	ds_read_b128 v[202:205], v149 offset:36864
	ds_read_b128 v[206:209], v149 offset:37888
	ds_read_b128 v[210:213], v149 offset:38912
	ds_read_b128 v[214:217], v149 offset:39936
	global_load_lds_dwordx4 v128, s[40:41]
	s_mov_b32 m0, s49
	s_nop 0
	global_load_lds_dwordx4 v132, s[40:41]
	s_waitcnt vmcnt(8)
	s_waitcnt lgkmcnt(0)
	s_barrier
	s_setprio 1
	s_waitcnt lgkmcnt(0)
	v_mfma_f32_16x16x32_bf16 v[124:127], v[154:157], v[186:189], v[124:127]
	v_mfma_f32_16x16x32_bf16 v[116:119], v[162:165], v[186:189], v[116:119]
	v_mfma_f32_16x16x32_bf16 v[108:111], v[154:157], v[194:197], v[108:111]
	v_mfma_f32_16x16x32_bf16 v[100:103], v[162:165], v[194:197], v[100:103]
	v_mfma_f32_16x16x32_bf16 v[92:95], v[154:157], v[202:205], v[92:95]
	v_mfma_f32_16x16x32_bf16 v[84:87], v[162:165], v[202:205], v[84:87]
	v_mfma_f32_16x16x32_bf16 v[76:79], v[154:157], v[210:213], v[76:79]
	v_mfma_f32_16x16x32_bf16 v[68:71], v[162:165], v[210:213], v[68:71]
	v_mfma_f32_16x16x32_bf16 v[124:127], v[158:161], v[190:193], v[124:127]
	v_mfma_f32_16x16x32_bf16 v[116:119], v[166:169], v[190:193], v[116:119]
	v_mfma_f32_16x16x32_bf16 v[108:111], v[158:161], v[198:201], v[108:111]
	v_mfma_f32_16x16x32_bf16 v[100:103], v[166:169], v[198:201], v[100:103]
	v_mfma_f32_16x16x32_bf16 v[92:95], v[158:161], v[206:209], v[92:95]
	v_mfma_f32_16x16x32_bf16 v[84:87], v[166:169], v[206:209], v[84:87]
	v_mfma_f32_16x16x32_bf16 v[76:79], v[158:161], v[214:217], v[76:79]
	v_mfma_f32_16x16x32_bf16 v[68:71], v[166:169], v[214:217], v[68:71]
	s_setprio 0
	s_setprio 1
	v_mfma_f32_16x16x32_bf16 v[120:123], v[170:173], v[186:189], v[120:123]
	v_mfma_f32_16x16x32_bf16 v[112:115], v[178:181], v[186:189], v[112:115]
	v_mfma_f32_16x16x32_bf16 v[104:107], v[170:173], v[194:197], v[104:107]
	v_mfma_f32_16x16x32_bf16 v[96:99], v[178:181], v[194:197], v[96:99]
	v_mfma_f32_16x16x32_bf16 v[88:91], v[170:173], v[202:205], v[88:91]
	v_mfma_f32_16x16x32_bf16 v[80:83], v[178:181], v[202:205], v[80:83]
	v_mfma_f32_16x16x32_bf16 v[72:75], v[170:173], v[210:213], v[72:75]
	v_mfma_f32_16x16x32_bf16 v[64:67], v[178:181], v[210:213], v[64:67]
	v_mfma_f32_16x16x32_bf16 v[120:123], v[174:177], v[190:193], v[120:123]
	v_mfma_f32_16x16x32_bf16 v[112:115], v[182:185], v[190:193], v[112:115]
	v_mfma_f32_16x16x32_bf16 v[104:107], v[174:177], v[198:201], v[104:107]
	v_mfma_f32_16x16x32_bf16 v[96:99], v[182:185], v[198:201], v[96:99]
	v_mfma_f32_16x16x32_bf16 v[88:91], v[174:177], v[206:209], v[88:91]
	v_mfma_f32_16x16x32_bf16 v[80:83], v[182:185], v[206:209], v[80:83]
	v_mfma_f32_16x16x32_bf16 v[72:75], v[174:177], v[214:217], v[72:75]
	v_mfma_f32_16x16x32_bf16 v[64:67], v[182:185], v[214:217], v[64:67]
	s_setprio 0
	s_barrier
; #define PG8_STAGE(bufoff, gbase, voff) do { _Pragma("unroll") for (int _i = 0; _i < 2; ++_i) \
;         __builtin_amdgcn_global_load_lds((const unsigned*)((const char*)(gbase) + (voff)[_i]), (PG8_LAS unsigned*)(lds + (bufoff) + ldsw + _i * 8192), 16, 0, 0); } while (0)
; #define PG8_LDA(dst, b, h) do { _Pragma("unroll") for (int m = 0; m < 4; ++m) _Pragma("unroll") for (int k = 0; k < 2; ++k) dst[m][k] = *(const PG8_LAS bf16x8*)(lds + PG8_SA(b, h) + aoff + m * 2048 + k * 1024); } while (0)
; #define PG8_MMA(ai, bj, At, Bt) do { __builtin_amdgcn_s_setprio(1); _Pragma("unroll") for (int m = 0; m < 4; ++m) _Pragma("unroll") for (int n = 0; n < 2; ++n) _Pragma("unroll") for (int k = 0; k < 2; ++k) \
;         acc[ai][bj][m][n] = __builtin_amdgcn_mfma_f32_16x16x32_bf16(Bt[n][k], At[m][k], acc[ai][bj][m][n], 0, 0, 0); __builtin_amdgcn_s_setprio(0); } while (0)
; #define PG8_WAIT_V(n) asm volatile("s_waitcnt vmcnt(" #n ")" ::: "memory")
; #define PG8_WAIT_L(n) asm volatile("s_waitcnt lgkmcnt(" #n ")" ::: "memory")
; #define PG8_BAR __builtin_amdgcn_s_barrier()
; #define PG8_SCHED __builtin_amdgcn_sched_barrier(0)
; template <class Epi, class Sched, bool ALIGN_EPI = false, bool SP2 = false>
; __device__ __forceinline__ void gemm_phase(PG8_LAS unsigned char* lds, const Gemm g, const Sched& S, const Epi& E) {
;     ...
;             PG8_LDA(At, 1, 1); PG8_STAGE(PG8_SB(1, 0), b3, voffB); PG8_STAGE(PG8_SB(1, 1), b3 + hstep, voffB); PG8_STAGE(PG8_SA(1, 0), a3, voffA);
;             PG8_WAIT_V(8); PG8_WAIT_L(0); PG8_BAR; PG8_MMA(1, 0, At, B0); PG8_MMA(1, 1, At, B1); PG8_BAR; PG8_SCHED;
	s_add_i32 s33, s33, s44
	s_mov_b32 m0, s33
	ds_read_b128 v[186:189], v149 offset:49152
	ds_read_b128 v[190:193], v149 offset:50176
	ds_read_b128 v[194:197], v149 offset:51200
	ds_read_b128 v[198:201], v149 offset:52224
	ds_read_b128 v[202:205], v149 offset:53248
	ds_read_b128 v[206:209], v149 offset:54272
	ds_read_b128 v[210:213], v149 offset:55296
	ds_read_b128 v[214:217], v149 offset:56320
	global_load_lds_dwordx4 v130, s[82:83]
	s_add_i32 m0, s33, 0x2000
	s_add_u32 s38, s38, 0x40080
	s_addc_u32 s39, s39, 0
	s_add_i32 s33, s34, s44
	global_load_lds_dwordx4 v134, s[82:83]
	s_mov_b32 m0, s33
	s_nop 0
	global_load_lds_dwordx4 v130, s[38:39]
	s_add_i32 m0, s33, 0x2000
	s_nop 0
	global_load_lds_dwordx4 v134, s[38:39]
	s_mov_b32 m0, s52
	s_nop 0
	global_load_lds_dwordx4 v128, s[84:85]
	s_mov_b32 m0, s53
	s_nop 0
	global_load_lds_dwordx4 v132, s[84:85]
	s_waitcnt vmcnt(8)
	s_waitcnt lgkmcnt(0)
	s_barrier
	s_setprio 1
	s_waitcnt lgkmcnt(0)
	v_mfma_f32_16x16x32_bf16 v[60:63], v[154:157], v[186:189], v[60:63]
	v_mfma_f32_16x16x32_bf16 v[52:55], v[162:165], v[186:189], v[52:55]
	v_mfma_f32_16x16x32_bf16 v[44:47], v[154:157], v[194:197], v[44:47]
	v_mfma_f32_16x16x32_bf16 v[36:39], v[162:165], v[194:197], v[36:39]
	v_mfma_f32_16x16x32_bf16 v[28:31], v[154:157], v[202:205], v[28:31]
	v_mfma_f32_16x16x32_bf16 v[20:23], v[162:165], v[202:205], v[20:23]
	v_mfma_f32_16x16x32_bf16 v[12:15], v[154:157], v[210:213], v[12:15]
	v_mfma_f32_16x16x32_bf16 v[4:7], v[162:165], v[210:213], v[4:7]
	v_mfma_f32_16x16x32_bf16 v[60:63], v[158:161], v[190:193], v[60:63]
	v_mfma_f32_16x16x32_bf16 v[52:55], v[166:169], v[190:193], v[52:55]
	v_mfma_f32_16x16x32_bf16 v[44:47], v[158:161], v[198:201], v[44:47]
	v_mfma_f32_16x16x32_bf16 v[36:39], v[166:169], v[198:201], v[36:39]
	v_mfma_f32_16x16x32_bf16 v[28:31], v[158:161], v[206:209], v[28:31]
	v_mfma_f32_16x16x32_bf16 v[20:23], v[166:169], v[206:209], v[20:23]
	v_mfma_f32_16x16x32_bf16 v[12:15], v[158:161], v[214:217], v[12:15]
	v_mfma_f32_16x16x32_bf16 v[4:7], v[166:169], v[214:217], v[4:7]
	s_setprio 0
	s_setprio 1
	v_mfma_f32_16x16x32_bf16 v[56:59], v[170:173], v[186:189], v[56:59]
	v_mfma_f32_16x16x32_bf16 v[48:51], v[178:181], v[186:189], v[48:51]
	v_mfma_f32_16x16x32_bf16 v[40:43], v[170:173], v[194:197], v[40:43]
	v_mfma_f32_16x16x32_bf16 v[32:35], v[178:181], v[194:197], v[32:35]
	v_mfma_f32_16x16x32_bf16 v[24:27], v[170:173], v[202:205], v[24:27]
	v_mfma_f32_16x16x32_bf16 v[16:19], v[178:181], v[202:205], v[16:19]
	v_mfma_f32_16x16x32_bf16 v[8:11], v[170:173], v[210:213], v[8:11]
	v_mfma_f32_16x16x32_bf16 v[0:3], v[178:181], v[210:213], v[0:3]
	v_mfma_f32_16x16x32_bf16 v[56:59], v[174:177], v[190:193], v[56:59]
	v_mfma_f32_16x16x32_bf16 v[48:51], v[182:185], v[190:193], v[48:51]
	v_mfma_f32_16x16x32_bf16 v[40:43], v[174:177], v[198:201], v[40:43]
	v_mfma_f32_16x16x32_bf16 v[32:35], v[182:185], v[198:201], v[32:35]
	v_mfma_f32_16x16x32_bf16 v[24:27], v[174:177], v[206:209], v[24:27]
	v_mfma_f32_16x16x32_bf16 v[16:19], v[182:185], v[206:209], v[16:19]
	v_mfma_f32_16x16x32_bf16 v[8:11], v[174:177], v[214:217], v[8:11]
	v_mfma_f32_16x16x32_bf16 v[0:3], v[182:185], v[214:217], v[0:3]
	s_setprio 0
	s_barrier
	s_add_i32 s62, s62, 2
	s_add_u32 s36, s36, 0x100
	s_addc_u32 s37, s37, 0
	s_add_u32 s60, s60, 0x100
	s_addc_u32 s61, s61, 0
	s_cmp_gt_u32 s62, 13

; #define PG8_STAGE(bufoff, gbase, voff) do { _Pragma("unroll") for (int _i = 0; _i < 2; ++_i) \
;         __builtin_amdgcn_global_load_lds((const unsigned*)((const char*)(gbase) + (voff)[_i]), (PG8_LAS unsigned*)(lds + (bufoff) + ldsw + _i * 8192), 16, 0, 0); } while (0)
; #define PG8_LDA(dst, b, h) do { _Pragma("unroll") for (int m = 0; m < 4; ++m) _Pragma("unroll") for (int k = 0; k < 2; ++k) dst[m][k] = *(const PG8_LAS bf16x8*)(lds + PG8_SA(b, h) + aoff + m * 2048 + k * 1024); } while (0)
; #define PG8_LDB(dst, b, h) do { _Pragma("unroll") for (int n = 0; n < 2; ++n) _Pragma("unroll") for (int k = 0; k < 2; ++k) dst[n][k] = *(const PG8_LAS bf16x8*)(lds + PG8_SB(b, h) + boff + n * 2048 + k * 1024); } while (0)
; #define PG8_MMA(ai, bj, At, Bt) do { __builtin_amdgcn_s_setprio(1); _Pragma("unroll") for (int m = 0; m < 4; ++m) _Pragma("unroll") for (int n = 0; n < 2; ++n) _Pragma("unroll") for (int k = 0; k < 2; ++k) \
;         acc[ai][bj][m][n] = __builtin_amdgcn_mfma_f32_16x16x32_bf16(Bt[n][k], At[m][k], acc[ai][bj][m][n], 0, 0, 0); __builtin_amdgcn_s_setprio(0); } while (0)
; #define PG8_WAIT_V(n) asm volatile("s_waitcnt vmcnt(" #n ")" ::: "memory")
; #define PG8_WAIT_L(n) asm volatile("s_waitcnt lgkmcnt(" #n ")" ::: "memory")
; #define PG8_BAR __builtin_amdgcn_s_barrier()
; template <class Epi, class Sched, bool ALIGN_EPI = false, bool SP2 = false>
; __device__ __forceinline__ void gemm_phase(PG8_LAS unsigned char* lds, const Gemm g, const Sched& S, const Epi& E) {
;     ...
;             const char* a1 = cA + (size_t)(t + 1) * kstep;
;             const char* a2 = last ? nA : cA + (size_t)(t + 2) * kstep; const char* b2 = last ? nB : cB + (size_t)(t + 2) * kstep;
;             const char* a3 = a2 + kstep; const char* b3 = b2 + kstep;
;             if (last && has_next) S.a_ready(nxt);
;             if constexpr (SP2) {
;             PG8_LDB(B0, 0, 0); PG8_LDB(B1, 0, 1); PG8_SCHED; PG8_LDA(At, 0, 0); PG8_STAGE(PG8_SA(1, 1), a1 + hstep, voffA);
;             PG8_WAIT_V(8); PG8_WAIT_L(0); PG8_BAR; PG8_MMA(0, 0, At, B0); PG8_MMA(0, 1, At, B1); PG8_BAR; PG8_SCHED;
;             PG8_LDA(At, 0, 1); PG8_STAGE(PG8_SB(0, 0), b2, voffB); PG8_STAGE(PG8_SB(0, 1), b2 + hstep, voffB); PG8_STAGE(PG8_SA(0, 0), a2, voffA);
;             PG8_WAIT_V(8); PG8_WAIT_L(0); PG8_BAR; PG8_MMA(1, 0, At, B0); PG8_MMA(1, 1, At, B1); PG8_BAR; PG8_SCHED;
.LBB0_1416:
	s_add_u32 s24, s24, 0xb0080
	s_addc_u32 s25, s25, 0
	s_add_u32 s55, s30, 0x100
	s_addc_u32 s56, s31, 0
	s_mov_b32 s57, -2
	s_waitcnt lgkmcnt(0)
	ds_read_b128 v[128:131], v161
	ds_read_b128 v[132:135], v161 offset:1024
	ds_read_b128 v[152:155], v161 offset:2048
	ds_read_b128 v[164:167], v161 offset:3072
	ds_read_b128 v[168:171], v162
	ds_read_b128 v[172:175], v162 offset:1024
	ds_read_b128 v[176:179], v162 offset:2048
	ds_read_b128 v[180:183], v162 offset:3072
	s_add_u32 s28, s24, 0xfff50080
	s_addc_u32 s29, s25, -1
	s_cmp_eq_u32 s57, 40
	s_cselect_b32 s31, s5, s29
	s_cselect_b32 s30, s4, s28
	s_cselect_b32 s29, s23, s56
	s_cselect_b32 s28, s22, s55
	s_add_i32 m0, s39, 0xc000
	ds_read_b128 v[184:187], v163
	ds_read_b128 v[188:191], v163 offset:1024
	ds_read_b128 v[192:195], v163 offset:2048
	ds_read_b128 v[196:199], v163 offset:3072
	ds_read_b128 v[200:203], v163 offset:4096
	ds_read_b128 v[204:207], v163 offset:5120
	ds_read_b128 v[208:211], v163 offset:6144
	ds_read_b128 v[212:215], v163 offset:7168
	global_load_lds_dwordx4 v144, s[24:25]
	s_add_i32 m0, s39, 0xe000
	s_nop 0
	global_load_lds_dwordx4 v146, s[24:25]
	s_waitcnt vmcnt(8)
	s_waitcnt lgkmcnt(0)
	s_barrier
	s_setprio 1
	s_waitcnt lgkmcnt(0)
	v_mfma_f32_16x16x32_bf16 v[124:127], v[128:131], v[184:187], 0
	v_mfma_f32_16x16x32_bf16 v[120:123], v[152:155], v[184:187], 0
	v_mfma_f32_16x16x32_bf16 v[116:119], v[128:131], v[192:195], 0
	v_mfma_f32_16x16x32_bf16 v[112:115], v[152:155], v[192:195], 0
	v_mfma_f32_16x16x32_bf16 v[108:111], v[128:131], v[200:203], 0
	v_mfma_f32_16x16x32_bf16 v[104:107], v[152:155], v[200:203], 0
	v_mfma_f32_16x16x32_bf16 v[100:103], v[128:131], v[208:211], 0
	v_mfma_f32_16x16x32_bf16 v[96:99], v[152:155], v[208:211], 0
	v_mfma_f32_16x16x32_bf16 v[124:127], v[132:135], v[188:191], v[124:127]
	v_mfma_f32_16x16x32_bf16 v[120:123], v[164:167], v[188:191], v[120:123]
	v_mfma_f32_16x16x32_bf16 v[116:119], v[132:135], v[196:199], v[116:119]
	v_mfma_f32_16x16x32_bf16 v[112:115], v[164:167], v[196:199], v[112:115]
	v_mfma_f32_16x16x32_bf16 v[108:111], v[132:135], v[204:207], v[108:111]
	v_mfma_f32_16x16x32_bf16 v[104:107], v[164:167], v[204:207], v[104:107]
	v_mfma_f32_16x16x32_bf16 v[100:103], v[132:135], v[212:215], v[100:103]
	v_mfma_f32_16x16x32_bf16 v[96:99], v[164:167], v[212:215], v[96:99]
	s_setprio 0
	s_setprio 1
	v_mfma_f32_16x16x32_bf16 v[64:67], v[168:171], v[184:187], 0
	v_mfma_f32_16x16x32_bf16 v[56:59], v[176:179], v[184:187], 0
	v_mfma_f32_16x16x32_bf16 v[52:55], v[168:171], v[192:195], 0
	v_mfma_f32_16x16x32_bf16 v[48:51], v[176:179], v[192:195], 0
	v_mfma_f32_16x16x32_bf16 v[44:47], v[168:171], v[200:203], 0
	v_mfma_f32_16x16x32_bf16 v[40:43], v[176:179], v[200:203], 0
	v_mfma_f32_16x16x32_bf16 v[36:39], v[168:171], v[208:211], 0
	v_mfma_f32_16x16x32_bf16 v[32:35], v[176:179], v[208:211], 0
	v_mfma_f32_16x16x32_bf16 v[64:67], v[172:175], v[188:191], v[64:67]
	v_mfma_f32_16x16x32_bf16 v[56:59], v[180:183], v[188:191], v[56:59]
	v_mfma_f32_16x16x32_bf16 v[52:55], v[172:175], v[196:199], v[52:55]
	v_mfma_f32_16x16x32_bf16 v[48:51], v[180:183], v[196:199], v[48:51]
	v_mfma_f32_16x16x32_bf16 v[44:47], v[172:175], v[204:207], v[44:47]
	v_mfma_f32_16x16x32_bf16 v[40:43], v[180:183], v[204:207], v[40:43]
	v_mfma_f32_16x16x32_bf16 v[36:39], v[172:175], v[212:215], v[36:39]
	v_mfma_f32_16x16x32_bf16 v[32:35], v[180:183], v[212:215], v[32:35]
	s_setprio 0
	s_barrier
	s_add_i32 s58, s49, s37
	s_add_u32 s62, s28, s10
	s_addc_u32 s63, s29, s11
	s_mov_b32 m0, s58
	ds_read_b128 v[184:187], v163 offset:16384
	ds_read_b128 v[188:191], v163 offset:17408
	ds_read_b128 v[192:195], v163 offset:18432
	ds_read_b128 v[196:199], v163 offset:19456
	ds_read_b128 v[200:203], v163 offset:20480
	ds_read_b128 v[204:207], v163 offset:21504
	ds_read_b128 v[208:211], v163 offset:22528
	ds_read_b128 v[212:215], v163 offset:23552
	global_load_lds_dwordx4 v138, s[28:29]
	s_add_i32 m0, s58, 0x2000
	s_add_u32 s58, s28, 0xb0000
	s_addc_u32 s59, s29, 0
	s_add_i32 s60, s50, s37
	global_load_lds_dwordx4 v142, s[28:29]
	s_mov_b32 m0, s60
	s_add_u32 s64, s30, s10
	s_addc_u32 s65, s31, s11
	global_load_lds_dwordx4 v138, s[58:59]
	s_add_i32 m0, s60, 0x2000
	s_nop 0
	global_load_lds_dwordx4 v142, s[58:59]
	s_mov_b32 m0, s39
	s_nop 0
	global_load_lds_dwordx4 v136, s[30:31]
	s_mov_b32 m0, s40
	s_nop 0
	global_load_lds_dwordx4 v140, s[30:31]
	s_waitcnt vmcnt(8)
	s_waitcnt lgkmcnt(0)
	s_barrier
	s_setprio 1
	s_waitcnt lgkmcnt(0)
	v_mfma_f32_16x16x32_bf16 v[92:95], v[128:131], v[184:187], 0
	v_mfma_f32_16x16x32_bf16 v[88:91], v[152:155], v[184:187], 0
	v_mfma_f32_16x16x32_bf16 v[84:87], v[128:131], v[192:195], 0
	v_mfma_f32_16x16x32_bf16 v[80:83], v[152:155], v[192:195], 0
	v_mfma_f32_16x16x32_bf16 v[76:79], v[128:131], v[200:203], 0
	v_mfma_f32_16x16x32_bf16 v[72:75], v[152:155], v[200:203], 0
	v_mfma_f32_16x16x32_bf16 v[68:71], v[128:131], v[208:211], 0
	v_mfma_f32_16x16x32_bf16 v[60:63], v[152:155], v[208:211], 0
	v_mfma_f32_16x16x32_bf16 v[92:95], v[132:135], v[188:191], v[92:95]
	v_mfma_f32_16x16x32_bf16 v[88:91], v[164:167], v[188:191], v[88:91]
	v_mfma_f32_16x16x32_bf16 v[84:87], v[132:135], v[196:199], v[84:87]
	v_mfma_f32_16x16x32_bf16 v[80:83], v[164:167], v[196:199], v[80:83]
	v_mfma_f32_16x16x32_bf16 v[76:79], v[132:135], v[204:207], v[76:79]
	v_mfma_f32_16x16x32_bf16 v[72:75], v[164:167], v[204:207], v[72:75]
	v_mfma_f32_16x16x32_bf16 v[68:71], v[132:135], v[212:215], v[68:71]
	v_mfma_f32_16x16x32_bf16 v[60:63], v[164:167], v[212:215], v[60:63]
	s_setprio 0
	s_setprio 1
	v_mfma_f32_16x16x32_bf16 v[28:31], v[168:171], v[184:187], 0
	v_mfma_f32_16x16x32_bf16 v[24:27], v[176:179], v[184:187], 0
	v_mfma_f32_16x16x32_bf16 v[20:23], v[168:171], v[192:195], 0
	v_mfma_f32_16x16x32_bf16 v[16:19], v[176:179], v[192:195], 0
	v_mfma_f32_16x16x32_bf16 v[12:15], v[168:171], v[200:203], 0
	v_mfma_f32_16x16x32_bf16 v[8:11], v[176:179], v[200:203], 0
	v_mfma_f32_16x16x32_bf16 v[4:7], v[168:171], v[208:211], 0
	v_mfma_f32_16x16x32_bf16 v[0:3], v[176:179], v[208:211], 0
	v_mfma_f32_16x16x32_bf16 v[28:31], v[172:175], v[188:191], v[28:31]
	v_mfma_f32_16x16x32_bf16 v[24:27], v[180:183], v[188:191], v[24:27]
	v_mfma_f32_16x16x32_bf16 v[20:23], v[172:175], v[196:199], v[20:23]
	v_mfma_f32_16x16x32_bf16 v[16:19], v[180:183], v[196:199], v[16:19]
	v_mfma_f32_16x16x32_bf16 v[12:15], v[172:175], v[204:207], v[12:15]
	v_mfma_f32_16x16x32_bf16 v[8:11], v[180:183], v[204:207], v[8:11]
	v_mfma_f32_16x16x32_bf16 v[4:7], v[172:175], v[212:215], v[4:7]
	v_mfma_f32_16x16x32_bf16 v[0:3], v[180:183], v[212:215], v[0:3]
	s_setprio 0
	s_barrier
; #define PG8_STAGE(bufoff, gbase, voff) do { _Pragma("unroll") for (int _i = 0; _i < 2; ++_i) \
;         __builtin_amdgcn_global_load_lds((const unsigned*)((const char*)(gbase) + (voff)[_i]), (PG8_LAS unsigned*)(lds + (bufoff) + ldsw + _i * 8192), 16, 0, 0); } while (0)
; #define PG8_LDA(dst, b, h) do { _Pragma("unroll") for (int m = 0; m < 4; ++m) _Pragma("unroll") for (int k = 0; k < 2; ++k) dst[m][k] = *(const PG8_LAS bf16x8*)(lds + PG8_SA(b, h) + aoff + m * 2048 + k * 1024); } while (0)
; #define PG8_LDB(dst, b, h) do { _Pragma("unroll") for (int n = 0; n < 2; ++n) _Pragma("unroll") for (int k = 0; k < 2; ++k) dst[n][k] = *(const PG8_LAS bf16x8*)(lds + PG8_SB(b, h) + boff + n * 2048 + k * 1024); } while (0)
; #define PG8_MMA(ai, bj, At, Bt) do { __builtin_amdgcn_s_setprio(1); _Pragma("unroll") for (int m = 0; m < 4; ++m) _Pragma("unroll") for (int n = 0; n < 2; ++n) _Pragma("unroll") for (int k = 0; k < 2; ++k) \
;         acc[ai][bj][m][n] = __builtin_amdgcn_mfma_f32_16x16x32_bf16(Bt[n][k], At[m][k], acc[ai][bj][m][n], 0, 0, 0); __builtin_amdgcn_s_setprio(0); } while (0)
; #define PG8_WAIT_V(n) asm volatile("s_waitcnt vmcnt(" #n ")" ::: "memory")
; #define PG8_WAIT_L(n) asm volatile("s_waitcnt lgkmcnt(" #n ")" ::: "memory")
; #define PG8_BAR __builtin_amdgcn_s_barrier()
; #define PG8_SCHED __builtin_amdgcn_sched_barrier(0)
; template <class Epi, class Sched, bool ALIGN_EPI = false, bool SP2 = false>
; __device__ __forceinline__ void gemm_phase(PG8_LAS unsigned char* lds, const Gemm g, const Sched& S, const Epi& E) {
;     ...
;             PG8_LDB(B0, 1, 0); PG8_LDB(B1, 1, 1); PG8_SCHED; PG8_LDA(At, 1, 0); PG8_STAGE(PG8_SA(0, 1), a2 + hstep, voffA);
;             PG8_WAIT_V(8); PG8_WAIT_L(0); PG8_BAR; PG8_MMA(0, 0, At, B0); PG8_MMA(0, 1, At, B1); PG8_BAR; PG8_SCHED;
;             PG8_LDA(At, 1, 1); PG8_STAGE(PG8_SB(1, 0), b3, voffB); PG8_STAGE(PG8_SB(1, 1), b3 + hstep, voffB); PG8_STAGE(PG8_SA(1, 0), a3, voffA);
;             PG8_WAIT_V(8); PG8_WAIT_L(0); PG8_BAR; PG8_MMA(1, 0, At, B0); PG8_MMA(1, 1, At, B1); PG8_BAR; PG8_SCHED;
	s_add_i32 s58, 0, 0x18000
	s_add_i32 s59, 0, 0x1c000
	v_add_u32_e32 v164, s58, v159
	v_add_u32_e32 v180, s59, v159
	ds_read_b128 v[128:131], v164
	ds_read_b128 v[132:135], v164 offset:1024
	ds_read_b128 v[152:155], v164 offset:2048
	ds_read_b128 v[164:167], v164 offset:3072
	ds_read_b128 v[168:171], v180
	ds_read_b128 v[172:175], v180 offset:1024
	ds_read_b128 v[176:179], v180 offset:2048
	ds_read_b128 v[180:183], v180 offset:3072
	s_add_u32 s30, s30, 0xb0000
	s_addc_u32 s31, s31, 0
	s_mov_b32 m0, s41
	ds_read_b128 v[184:187], v163 offset:32768
	ds_read_b128 v[188:191], v163 offset:33792
	ds_read_b128 v[192:195], v163 offset:34816
	ds_read_b128 v[196:199], v163 offset:35840
	ds_read_b128 v[200:203], v163 offset:36864
	ds_read_b128 v[204:207], v163 offset:37888
	ds_read_b128 v[208:211], v163 offset:38912
	ds_read_b128 v[212:215], v163 offset:39936
	global_load_lds_dwordx4 v136, s[30:31]
	s_mov_b32 m0, s42
	s_nop 0
	global_load_lds_dwordx4 v140, s[30:31]
	s_waitcnt vmcnt(8)
	s_waitcnt lgkmcnt(0)
	s_barrier
	s_setprio 1
	s_waitcnt lgkmcnt(0)
	v_mfma_f32_16x16x32_bf16 v[124:127], v[128:131], v[184:187], v[124:127]
	v_mfma_f32_16x16x32_bf16 v[120:123], v[152:155], v[184:187], v[120:123]
	v_mfma_f32_16x16x32_bf16 v[116:119], v[128:131], v[192:195], v[116:119]
	v_mfma_f32_16x16x32_bf16 v[112:115], v[152:155], v[192:195], v[112:115]
	v_mfma_f32_16x16x32_bf16 v[108:111], v[128:131], v[200:203], v[108:111]
	v_mfma_f32_16x16x32_bf16 v[104:107], v[152:155], v[200:203], v[104:107]
	v_mfma_f32_16x16x32_bf16 v[100:103], v[128:131], v[208:211], v[100:103]
	v_mfma_f32_16x16x32_bf16 v[96:99], v[152:155], v[208:211], v[96:99]
	v_mfma_f32_16x16x32_bf16 v[124:127], v[132:135], v[188:191], v[124:127]
	v_mfma_f32_16x16x32_bf16 v[120:123], v[164:167], v[188:191], v[120:123]
	v_mfma_f32_16x16x32_bf16 v[116:119], v[132:135], v[196:199], v[116:119]
	v_mfma_f32_16x16x32_bf16 v[112:115], v[164:167], v[196:199], v[112:115]
	v_mfma_f32_16x16x32_bf16 v[108:111], v[132:135], v[204:207], v[108:111]
	v_mfma_f32_16x16x32_bf16 v[104:107], v[164:167], v[204:207], v[104:107]
	v_mfma_f32_16x16x32_bf16 v[100:103], v[132:135], v[212:215], v[100:103]
	v_mfma_f32_16x16x32_bf16 v[96:99], v[164:167], v[212:215], v[96:99]
	s_setprio 0
	s_setprio 1
	v_mfma_f32_16x16x32_bf16 v[64:67], v[168:171], v[184:187], v[64:67]
	v_mfma_f32_16x16x32_bf16 v[56:59], v[176:179], v[184:187], v[56:59]
	v_mfma_f32_16x16x32_bf16 v[52:55], v[168:171], v[192:195], v[52:55]
	v_mfma_f32_16x16x32_bf16 v[48:51], v[176:179], v[192:195], v[48:51]
	v_mfma_f32_16x16x32_bf16 v[44:47], v[168:171], v[200:203], v[44:47]
	v_mfma_f32_16x16x32_bf16 v[40:43], v[176:179], v[200:203], v[40:43]
	v_mfma_f32_16x16x32_bf16 v[36:39], v[168:171], v[208:211], v[36:39]
	v_mfma_f32_16x16x32_bf16 v[32:35], v[176:179], v[208:211], v[32:35]
	v_mfma_f32_16x16x32_bf16 v[64:67], v[172:175], v[188:191], v[64:67]
	v_mfma_f32_16x16x32_bf16 v[56:59], v[180:183], v[188:191], v[56:59]
	v_mfma_f32_16x16x32_bf16 v[52:55], v[172:175], v[196:199], v[52:55]
	v_mfma_f32_16x16x32_bf16 v[48:51], v[180:183], v[196:199], v[48:51]
	v_mfma_f32_16x16x32_bf16 v[44:47], v[172:175], v[204:207], v[44:47]
	v_mfma_f32_16x16x32_bf16 v[40:43], v[180:183], v[204:207], v[40:43]
	v_mfma_f32_16x16x32_bf16 v[36:39], v[172:175], v[212:215], v[36:39]
	v_mfma_f32_16x16x32_bf16 v[32:35], v[180:183], v[212:215], v[32:35]
	s_setprio 0
	s_barrier
	s_add_i32 s30, s58, s37
	s_mov_b32 m0, s30
	ds_read_b128 v[184:187], v163 offset:49152
	ds_read_b128 v[188:191], v163 offset:50176
	ds_read_b128 v[192:195], v163 offset:51200
	ds_read_b128 v[196:199], v163 offset:52224
	ds_read_b128 v[200:203], v163 offset:53248
	ds_read_b128 v[204:207], v163 offset:54272
	ds_read_b128 v[208:211], v163 offset:55296
	ds_read_b128 v[212:215], v163 offset:56320
	global_load_lds_dwordx4 v138, s[62:63]
	s_add_i32 m0, s30, 0x2000
	s_add_u32 s28, s28, 0xb0080
	s_addc_u32 s29, s29, 0
	s_add_i32 s30, s59, s37
	global_load_lds_dwordx4 v142, s[62:63]
	s_mov_b32 m0, s30
	s_nop 0
	global_load_lds_dwordx4 v138, s[28:29]
	s_add_i32 m0, s30, 0x2000
	s_nop 0
	global_load_lds_dwordx4 v142, s[28:29]
	s_mov_b32 m0, s47
	s_nop 0
	global_load_lds_dwordx4 v136, s[64:65]
	s_mov_b32 m0, s48
	s_nop 0
	global_load_lds_dwordx4 v140, s[64:65]
	s_waitcnt vmcnt(8)
	s_waitcnt lgkmcnt(0)
	s_barrier
	s_setprio 1
	s_waitcnt lgkmcnt(0)
	v_mfma_f32_16x16x32_bf16 v[92:95], v[128:131], v[184:187], v[92:95]
	v_mfma_f32_16x16x32_bf16 v[88:91], v[152:155], v[184:187], v[88:91]
	v_mfma_f32_16x16x32_bf16 v[84:87], v[128:131], v[192:195], v[84:87]
	v_mfma_f32_16x16x32_bf16 v[80:83], v[152:155], v[192:195], v[80:83]
	v_mfma_f32_16x16x32_bf16 v[76:79], v[128:131], v[200:203], v[76:79]
	v_mfma_f32_16x16x32_bf16 v[72:75], v[152:155], v[200:203], v[72:75]
	v_mfma_f32_16x16x32_bf16 v[68:71], v[128:131], v[208:211], v[68:71]
	v_mfma_f32_16x16x32_bf16 v[60:63], v[152:155], v[208:211], v[60:63]
	v_mfma_f32_16x16x32_bf16 v[92:95], v[132:135], v[188:191], v[92:95]
	v_mfma_f32_16x16x32_bf16 v[88:91], v[164:167], v[188:191], v[88:91]
	v_mfma_f32_16x16x32_bf16 v[84:87], v[132:135], v[196:199], v[84:87]
	v_mfma_f32_16x16x32_bf16 v[80:83], v[164:167], v[196:199], v[80:83]
	v_mfma_f32_16x16x32_bf16 v[76:79], v[132:135], v[204:207], v[76:79]
	v_mfma_f32_16x16x32_bf16 v[72:75], v[164:167], v[204:207], v[72:75]
	v_mfma_f32_16x16x32_bf16 v[68:71], v[132:135], v[212:215], v[68:71]
	v_mfma_f32_16x16x32_bf16 v[60:63], v[164:167], v[212:215], v[60:63]
	s_setprio 0
	s_setprio 1
	v_mfma_f32_16x16x32_bf16 v[28:31], v[168:171], v[184:187], v[28:31]
	v_mfma_f32_16x16x32_bf16 v[24:27], v[176:179], v[184:187], v[24:27]
	v_mfma_f32_16x16x32_bf16 v[20:23], v[168:171], v[192:195], v[20:23]
	v_mfma_f32_16x16x32_bf16 v[16:19], v[176:179], v[192:195], v[16:19]
	v_mfma_f32_16x16x32_bf16 v[12:15], v[168:171], v[200:203], v[12:15]
	v_mfma_f32_16x16x32_bf16 v[8:11], v[176:179], v[200:203], v[8:11]
	v_mfma_f32_16x16x32_bf16 v[4:7], v[168:171], v[208:211], v[4:7]
	v_mfma_f32_16x16x32_bf16 v[0:3], v[176:179], v[208:211], v[0:3]
	v_mfma_f32_16x16x32_bf16 v[28:31], v[172:175], v[188:191], v[28:31]
	v_mfma_f32_16x16x32_bf16 v[24:27], v[180:183], v[188:191], v[24:27]
	v_mfma_f32_16x16x32_bf16 v[20:23], v[172:175], v[196:199], v[20:23]
	v_mfma_f32_16x16x32_bf16 v[16:19], v[180:183], v[196:199], v[16:19]
	v_mfma_f32_16x16x32_bf16 v[12:15], v[172:175], v[204:207], v[12:15]
	v_mfma_f32_16x16x32_bf16 v[8:11], v[180:183], v[204:207], v[8:11]
	v_mfma_f32_16x16x32_bf16 v[4:7], v[172:175], v[212:215], v[4:7]
	v_mfma_f32_16x16x32_bf16 v[0:3], v[180:183], v[212:215], v[0:3]
	s_setprio 0
	s_barrier
	s_add_i32 s57, s57, 2
	s_add_u32 s24, s24, 0x100
	s_addc_u32 s25, s25, 0
	s_add_u32 s55, s55, 0x100
	s_addc_u32 s56, s56, 0
	s_cmp_gt_u32 s57, 41
